# MLA: rescale factor applied to the running row sum inside the rescale path (one VALU op fewer per tile in the main path)
# baseline (speedup 1.0000x reference)
; __device__ __forceinline__ void finishSM9(f32x16& p0, f32x16& p1, float alpha, float& l_reg, v8i32& p8) {
; #pragma unroll
;   for (int r = 0; r < 16; ++r) { p0[r] = __builtin_amdgcn_exp2f(p0[r]); p1[r] = __builtin_amdgcn_exp2f(p1[r]); }
;   float ps = 0;
; #pragma unroll
;   for (int r = 0; r < 16; ++r) ps += p0[r];
; #pragma unroll
;   for (int r = 0; r < 16; ++r) ps += p1[r];
;   { auto rr = __builtin_amdgcn_permlane32_swap(__float_as_uint(ps), __float_as_uint(ps), false, false);
;     ps = __uint_as_float(rr[0]) + __uint_as_float(rr[1]); }
;   l_reg = l_reg * alpha + ps;
; #pragma unroll
;   for (int g = 0; g < 4; ++g) {
;     int w = __builtin_amdgcn_cvt_pk_fp8_f32(p0[4 * g], p0[4 * g + 1], 0, false); p8[g] = __builtin_amdgcn_cvt_pk_fp8_f32(p0[4 * g + 2], p0[4 * g + 3], w, true);
;     int u = __builtin_amdgcn_cvt_pk_fp8_f32(p1[4 * g], p1[4 * g + 1], 0, false); p8[4 + g] = __builtin_amdgcn_cvt_pk_fp8_f32(p1[4 * g + 2], p1[4 * g + 3], u, true); }
; }
; __device__ __forceinline__ void pv8(f32x16* o, const char* Vt, const v8i32 p8, int r32, int hi) {
;   const int sw = (r32 >> 2) & 3, a0 = r32 * 64 + (((hi * 2) ^ sw) << 4), a1 = r32 * 64 + (((hi * 2 + 1) ^ sw) << 4);
; #pragma unroll
;   for (int d0 = 0; d0 < 4; ++d0) {
;     const v8i32 vf = cat8(*reinterpret_cast<const v4i32*>(Vt + d0 * 2048 + a0), *reinterpret_cast<const v4i32*>(Vt + d0 * 2048 + a1));
;     o[d0] = __builtin_amdgcn_mfma_scale_f32_32x32x64_f8f6f4(p8, vf, o[d0], 0, 0, 0, 127, 0, 127); }
; }
; __device__ __forceinline__ void qkt9(f32x16& p0, f32x16& p1, const char* Kn, const char* Kr, const v8i32* qf, const float init, int r32, int hi) {
; #pragma unroll
;   for (int r = 0; r < 16; ++r) { p0[r] = init; p1[r] = init; }
; #pragma unroll
;   for (int s = 0; s < 2; ++s) { const int c0 = s * 4 + hi * 2;
;     const v8i32 a0 = cat8(*reinterpret_cast<const v4i32*>(Kn + KN8SW(r32, c0)), *reinterpret_cast<const v4i32*>(Kn + KN8SW(r32, c0 + 1)));
;     const v8i32 a1 = cat8(*reinterpret_cast<const v4i32*>(Kn + 4096 + KN8SW(r32, c0)), *reinterpret_cast<const v4i32*>(Kn + 4096 + KN8SW(r32, c0 + 1)));
;     p0 = __builtin_amdgcn_mfma_scale_f32_32x32x64_f8f6f4(a0, qf[s], p0, 0, 0, 0, 127, 0, 124);
;     p1 = __builtin_amdgcn_mfma_scale_f32_32x32x64_f8f6f4(a1, qf[s], p1, 0, 0, 0, 127, 0, 124); }
;   { const int c0 = hi * 2;
.LBB0_1321:
	global_load_dwordx4 v[158:161], v176, s[18:19]
	global_load_dwordx4 v[162:165], v178, s[16:17]
	global_load_dwordx4 v[154:157], v[180:181], off
	ds_read_b128 v[114:117], v215 offset:24576
	ds_read_b128 v[118:121], v216 offset:24576
	ds_read_b128 v[222:225], v215 offset:28672
	ds_read_b128 v[226:229], v216 offset:28672
	v_add_u32_e32 v176, 0x2000, v176
	v_add_u32_e32 v178, 0x20000, v178
	s_mov_b64 s[20:21], 0x1000
	v_lshl_add_u64 v[180:181], v[180:181], 0, s[20:21]
	v_exp_f32_e32 v0, v82
	v_exp_f32_e32 v177, v83
	v_exp_f32_e32 v179, v84
	v_exp_f32_e32 v254, v85
	v_add_f32_e32 v219, v0, v177
	v_cvt_pk_fp8_f32 v246, v0, v177
	v_add_f32_e32 v219, v179, v219
	v_add_f32_e32 v219, v254, v219
	v_cvt_pk_fp8_f32 v246, v179, v254 op_sel:[0,0,1]
	s_waitcnt lgkmcnt(2)
	v_mfma_scale_f32_32x32x64_f8f6f4 v[114:129], v[114:121], v[146:153], v[230:245], v194, v193 op_sel_hi:[0,0,0]
	v_exp_f32_e32 v0, v86
	v_exp_f32_e32 v177, v87
	v_exp_f32_e32 v179, v88
	v_exp_f32_e32 v254, v89
	v_add_f32_e32 v219, v0, v219
	v_add_f32_e32 v219, v177, v219
	v_cvt_pk_fp8_f32 v247, v0, v177
	v_add_f32_e32 v219, v179, v219
	v_add_f32_e32 v219, v254, v219
	v_cvt_pk_fp8_f32 v247, v179, v254 op_sel:[0,0,1]
	ds_read_b128 v[82:85], v213 offset:24576
	ds_read_b128 v[86:89], v214 offset:24576
	s_waitcnt lgkmcnt(2)
	v_mfma_scale_f32_32x32x64_f8f6f4 v[98:113], v[222:229], v[146:153], v[230:245], v194, v193 op_sel_hi:[0,0,0]
	ds_read_b128 v[222:225], v213 offset:28672
	ds_read_b128 v[226:229], v214 offset:28672
	v_exp_f32_e32 v0, v90
	v_exp_f32_e32 v177, v91
	v_exp_f32_e32 v179, v92
	v_exp_f32_e32 v254, v93
	v_add_f32_e32 v219, v0, v219
	v_add_f32_e32 v219, v177, v219
	v_cvt_pk_fp8_f32 v248, v0, v177
	v_add_f32_e32 v219, v179, v219
	v_add_f32_e32 v219, v254, v219
	v_cvt_pk_fp8_f32 v248, v179, v254 op_sel:[0,0,1]
	v_exp_f32_e32 v0, v94
	v_exp_f32_e32 v177, v95
	v_exp_f32_e32 v179, v96
	v_exp_f32_e32 v254, v97
	v_add_f32_e32 v219, v0, v219
	v_add_f32_e32 v219, v177, v219
	v_cvt_pk_fp8_f32 v249, v0, v177
	v_add_f32_e32 v219, v179, v219
	v_add_f32_e32 v219, v254, v219
	v_cvt_pk_fp8_f32 v249, v179, v254 op_sel:[0,0,1]
	ds_read_b128 v[90:93], v185 offset:36864
	ds_read_b128 v[94:97], v186 offset:36864
	s_waitcnt lgkmcnt(4)
	v_mfma_scale_f32_32x32x64_f8f6f4 v[114:129], v[82:89], v[138:145], v[114:129], v194, v193 op_sel_hi:[0,0,0]
	v_exp_f32_e32 v0, v66
	v_exp_f32_e32 v177, v67
	v_exp_f32_e32 v179, v68
	v_exp_f32_e32 v254, v69
	v_add_f32_e32 v219, v0, v219
	v_add_f32_e32 v219, v177, v219
	v_cvt_pk_fp8_f32 v250, v0, v177
	v_add_f32_e32 v219, v179, v219
	v_add_f32_e32 v219, v254, v219
	v_cvt_pk_fp8_f32 v250, v179, v254 op_sel:[0,0,1]
	s_waitcnt lgkmcnt(2)
	v_mfma_scale_f32_32x32x64_f8f6f4 v[98:113], v[222:229], v[138:145], v[98:113], v194, v193 op_sel_hi:[0,0,0]
	ds_read_b128 v[222:225], v185 offset:38912
	ds_read_b128 v[226:229], v186 offset:38912
	v_exp_f32_e32 v0, v70
	v_exp_f32_e32 v177, v71
	v_exp_f32_e32 v179, v72
	v_exp_f32_e32 v254, v73
	v_add_f32_e32 v219, v0, v219
	v_add_f32_e32 v219, v177, v219
	v_cvt_pk_fp8_f32 v251, v0, v177
	v_add_f32_e32 v219, v179, v219
	v_add_f32_e32 v219, v254, v219
	v_cvt_pk_fp8_f32 v251, v179, v254 op_sel:[0,0,1]
	v_exp_f32_e32 v0, v74
	v_exp_f32_e32 v177, v75
	v_exp_f32_e32 v179, v76
	v_exp_f32_e32 v254, v77
	v_add_f32_e32 v219, v0, v219
	v_add_f32_e32 v219, v177, v219
	v_cvt_pk_fp8_f32 v252, v0, v177
	v_add_f32_e32 v219, v179, v219
	v_add_f32_e32 v219, v254, v219
	v_cvt_pk_fp8_f32 v252, v179, v254 op_sel:[0,0,1]
	s_waitcnt lgkmcnt(2)
	v_mfma_scale_f32_32x32x64_f8f6f4 v[114:129], v[90:97], v[130:137], v[114:129], v194, v193 op_sel_hi:[0,0,0]
	v_exp_f32_e32 v0, v78
	v_exp_f32_e32 v177, v79
	v_exp_f32_e32 v179, v80
	v_exp_f32_e32 v254, v81
	v_add_f32_e32 v219, v0, v219
	v_add_f32_e32 v219, v177, v219
	v_cvt_pk_fp8_f32 v253, v0, v177
	v_add_f32_e32 v219, v179, v219
	v_add_f32_e32 v219, v254, v219
	v_cvt_pk_fp8_f32 v253, v179, v254 op_sel:[0,0,1]
	ds_read_b128 v[90:93], v185 offset:0
	ds_read_b128 v[94:97], v186 offset:0
	ds_read_b128 v[82:85], v185 offset:2048
	ds_read_b128 v[86:89], v186 offset:2048
	ds_read_b128 v[74:77], v185 offset:4096
	ds_read_b128 v[78:81], v186 offset:4096
	ds_read_b128 v[66:69], v185 offset:6144
	ds_read_b128 v[70:73], v186 offset:6144
	s_waitcnt lgkmcnt(8)
	v_mfma_scale_f32_32x32x64_f8f6f4 v[98:113], v[222:229], v[130:137], v[98:113], v194, v193 op_sel_hi:[0,0,0]
	v_mov_b32_e32 v0, v219
	s_nop 1
	v_permlane32_swap_b32_e32 v219, v0
	v_add_f32_e32 v219, v219, v0
	v_add_f32_e32 v209, v209, v219
	v_max_f32_e32 v177, v114, v115
	v_max3_f32 v177, v177, v116, v117
	v_max3_f32 v177, v177, v118, v119
	v_max3_f32 v177, v177, v120, v121
	v_max3_f32 v177, v177, v122, v123
	v_max3_f32 v177, v177, v124, v125
	v_max3_f32 v177, v177, v126, v127
	v_max3_f32 v177, v177, v128, v129
	s_waitcnt lgkmcnt(6)
	v_mfma_scale_f32_32x32x64_f8f6f4 v[50:65], v[246:253], v[90:97], v[50:65], v194, v194 op_sel_hi:[0,0,0]
	s_waitcnt lgkmcnt(4)
	v_mfma_scale_f32_32x32x64_f8f6f4 v[34:49], v[246:253], v[82:89], v[34:49], v194, v194 op_sel_hi:[0,0,0]
	s_waitcnt lgkmcnt(2)
	v_mfma_scale_f32_32x32x64_f8f6f4 v[18:33], v[246:253], v[74:81], v[18:33], v194, v194 op_sel_hi:[0,0,0]
	s_waitcnt lgkmcnt(0)
	v_mfma_scale_f32_32x32x64_f8f6f4 v[2:17], v[246:253], v[66:73], v[2:17], v194, v194 op_sel_hi:[0,0,0]
	s_waitcnt vmcnt(0)
	ds_write_b128 v210, v[158:161] offset:43008
	ds_write_b128 v211, v[162:165] offset:51200
	ds_write_b128 v212, v[154:157] offset:59392
	v_max_f32_e32 v0, v98, v99
	v_max3_f32 v0, v0, v100, v101
	v_max3_f32 v0, v0, v102, v103
	v_max3_f32 v0, v0, v104, v105
	v_max3_f32 v0, v0, v106, v107
	v_max3_f32 v0, v0, v108, v109
	v_max3_f32 v0, v0, v110, v111
	v_max3_f32 v0, v0, v112, v113
	v_max_f32_e32 v177, v177, v0
	v_mov_b32_e32 v0, v177
	s_nop 1
	v_permlane32_swap_b32_e32 v177, v0
	v_max_f32_e32 v177, v177, v0
	v_cmp_ge_f32_e32 vcc, s90, v177
	s_cmp_eq_u64 vcc, exec
	s_cbranch_scc0 .Lmla_h0_newmax
; __device__ __forceinline__ void finishSM9(f32x16& p0, f32x16& p1, float alpha, float& l_reg, v8i32& p8) {
; #pragma unroll
;   for (int r = 0; r < 16; ++r) { p0[r] = __builtin_amdgcn_exp2f(p0[r]); p1[r] = __builtin_amdgcn_exp2f(p1[r]); }
;   float ps = 0;
; #pragma unroll
;   for (int r = 0; r < 16; ++r) ps += p0[r];
; #pragma unroll
;   for (int r = 0; r < 16; ++r) ps += p1[r];
;   { auto rr = __builtin_amdgcn_permlane32_swap(__float_as_uint(ps), __float_as_uint(ps), false, false);
;     ps = __uint_as_float(rr[0]) + __uint_as_float(rr[1]); }
;   l_reg = l_reg * alpha + ps;
; #pragma unroll
;   for (int g = 0; g < 4; ++g) {
;     int w = __builtin_amdgcn_cvt_pk_fp8_f32(p0[4 * g], p0[4 * g + 1], 0, false); p8[g] = __builtin_amdgcn_cvt_pk_fp8_f32(p0[4 * g + 2], p0[4 * g + 3], w, true);
;     int u = __builtin_amdgcn_cvt_pk_fp8_f32(p1[4 * g], p1[4 * g + 1], 0, false); p8[4 + g] = __builtin_amdgcn_cvt_pk_fp8_f32(p1[4 * g + 2], p1[4 * g + 3], u, true); }
; }
; __device__ __forceinline__ void pv8(f32x16* o, const char* Vt, const v8i32 p8, int r32, int hi) {
;   const int sw = (r32 >> 2) & 3, a0 = r32 * 64 + (((hi * 2) ^ sw) << 4), a1 = r32 * 64 + (((hi * 2 + 1) ^ sw) << 4);
; #pragma unroll
;   for (int d0 = 0; d0 < 4; ++d0) {
;     const v8i32 vf = cat8(*reinterpret_cast<const v4i32*>(Vt + d0 * 2048 + a0), *reinterpret_cast<const v4i32*>(Vt + d0 * 2048 + a1));
;     o[d0] = __builtin_amdgcn_mfma_scale_f32_32x32x64_f8f6f4(p8, vf, o[d0], 0, 0, 0, 127, 0, 127); }
; }
; __device__ __forceinline__ void qkt9(f32x16& p0, f32x16& p1, const char* Kn, const char* Kr, const v8i32* qf, const float init, int r32, int hi) {
; #pragma unroll
;   for (int r = 0; r < 16; ++r) { p0[r] = init; p1[r] = init; }
; #pragma unroll
;   for (int s = 0; s < 2; ++s) { const int c0 = s * 4 + hi * 2;
;     const v8i32 a0 = cat8(*reinterpret_cast<const v4i32*>(Kn + KN8SW(r32, c0)), *reinterpret_cast<const v4i32*>(Kn + KN8SW(r32, c0 + 1)));
;     const v8i32 a1 = cat8(*reinterpret_cast<const v4i32*>(Kn + 4096 + KN8SW(r32, c0)), *reinterpret_cast<const v4i32*>(Kn + 4096 + KN8SW(r32, c0 + 1)));
;     p0 = __builtin_amdgcn_mfma_scale_f32_32x32x64_f8f6f4(a0, qf[s], p0, 0, 0, 0, 127, 0, 124);
;     p1 = __builtin_amdgcn_mfma_scale_f32_32x32x64_f8f6f4(a1, qf[s], p1, 0, 0, 0, 127, 0, 124); }
;   { const int c0 = hi * 2;
.Lmla_h0_cont:
	s_waitcnt lgkmcnt(0)
	s_barrier
	global_load_dwordx4 v[158:161], v176, s[18:19]
	global_load_dwordx4 v[162:165], v178, s[16:17]
	global_load_dwordx4 v[154:157], v[180:181], off
	ds_read_b128 v[82:85], v215 offset:51200
	ds_read_b128 v[86:89], v216 offset:51200
	ds_read_b128 v[222:225], v215 offset:55296
	ds_read_b128 v[226:229], v216 offset:55296
	v_add_u32_e32 v176, 0x2000, v176
	v_add_u32_e32 v178, 0x20000, v178
	s_mov_b64 s[20:21], 0x1000
	v_lshl_add_u64 v[180:181], v[180:181], 0, s[20:21]
	v_exp_f32_e32 v0, v114
	v_exp_f32_e32 v177, v115
	v_exp_f32_e32 v179, v116
	v_exp_f32_e32 v254, v117
	v_add_f32_e32 v219, v0, v177
	v_cvt_pk_fp8_f32 v246, v0, v177
	v_add_f32_e32 v219, v179, v219
	v_add_f32_e32 v219, v254, v219
	v_cvt_pk_fp8_f32 v246, v179, v254 op_sel:[0,0,1]
	s_waitcnt lgkmcnt(2)
	v_mfma_scale_f32_32x32x64_f8f6f4 v[82:97], v[82:89], v[146:153], v[230:245], v194, v193 op_sel_hi:[0,0,0]
	v_exp_f32_e32 v0, v118
	v_exp_f32_e32 v177, v119
	v_exp_f32_e32 v179, v120
	v_exp_f32_e32 v254, v121
	v_add_f32_e32 v219, v0, v219
	v_add_f32_e32 v219, v177, v219
	v_cvt_pk_fp8_f32 v247, v0, v177
	v_add_f32_e32 v219, v179, v219
	v_add_f32_e32 v219, v254, v219
	v_cvt_pk_fp8_f32 v247, v179, v254 op_sel:[0,0,1]
	ds_read_b128 v[114:117], v213 offset:51200
	ds_read_b128 v[118:121], v214 offset:51200
	s_waitcnt lgkmcnt(2)
	v_mfma_scale_f32_32x32x64_f8f6f4 v[66:81], v[222:229], v[146:153], v[230:245], v194, v193 op_sel_hi:[0,0,0]
	ds_read_b128 v[222:225], v213 offset:55296
	ds_read_b128 v[226:229], v214 offset:55296
	v_exp_f32_e32 v0, v122
	v_exp_f32_e32 v177, v123
	v_exp_f32_e32 v179, v124
	v_exp_f32_e32 v254, v125
	v_add_f32_e32 v219, v0, v219
	v_add_f32_e32 v219, v177, v219
	v_cvt_pk_fp8_f32 v248, v0, v177
	v_add_f32_e32 v219, v179, v219
	v_add_f32_e32 v219, v254, v219
	v_cvt_pk_fp8_f32 v248, v179, v254 op_sel:[0,0,1]
	v_exp_f32_e32 v0, v126
	v_exp_f32_e32 v177, v127
	v_exp_f32_e32 v179, v128
	v_exp_f32_e32 v254, v129
	v_add_f32_e32 v219, v0, v219
	v_add_f32_e32 v219, v177, v219
	v_cvt_pk_fp8_f32 v249, v0, v177
	v_add_f32_e32 v219, v179, v219
	v_add_f32_e32 v219, v254, v219
	v_cvt_pk_fp8_f32 v249, v179, v254 op_sel:[0,0,1]
	ds_read_b128 v[122:125], v185 offset:59392
	ds_read_b128 v[126:129], v186 offset:59392
	s_waitcnt lgkmcnt(4)
	v_mfma_scale_f32_32x32x64_f8f6f4 v[82:97], v[114:121], v[138:145], v[82:97], v194, v193 op_sel_hi:[0,0,0]
	v_exp_f32_e32 v0, v98
	v_exp_f32_e32 v177, v99
	v_exp_f32_e32 v179, v100
	v_exp_f32_e32 v254, v101
	v_add_f32_e32 v219, v0, v219
	v_add_f32_e32 v219, v177, v219
	v_cvt_pk_fp8_f32 v250, v0, v177
	v_add_f32_e32 v219, v179, v219
	v_add_f32_e32 v219, v254, v219
	v_cvt_pk_fp8_f32 v250, v179, v254 op_sel:[0,0,1]
	s_waitcnt lgkmcnt(2)
	v_mfma_scale_f32_32x32x64_f8f6f4 v[66:81], v[222:229], v[138:145], v[66:81], v194, v193 op_sel_hi:[0,0,0]
	ds_read_b128 v[222:225], v185 offset:61440
	ds_read_b128 v[226:229], v186 offset:61440
	v_exp_f32_e32 v0, v102
	v_exp_f32_e32 v177, v103
	v_exp_f32_e32 v179, v104
	v_exp_f32_e32 v254, v105
	v_add_f32_e32 v219, v0, v219
	v_add_f32_e32 v219, v177, v219
	v_cvt_pk_fp8_f32 v251, v0, v177
	v_add_f32_e32 v219, v179, v219
	v_add_f32_e32 v219, v254, v219
	v_cvt_pk_fp8_f32 v251, v179, v254 op_sel:[0,0,1]
	v_exp_f32_e32 v0, v106
	v_exp_f32_e32 v177, v107
	v_exp_f32_e32 v179, v108
	v_exp_f32_e32 v254, v109
	v_add_f32_e32 v219, v0, v219
	v_add_f32_e32 v219, v177, v219
	v_cvt_pk_fp8_f32 v252, v0, v177
	v_add_f32_e32 v219, v179, v219
	v_add_f32_e32 v219, v254, v219
	v_cvt_pk_fp8_f32 v252, v179, v254 op_sel:[0,0,1]
	s_waitcnt lgkmcnt(2)
	v_mfma_scale_f32_32x32x64_f8f6f4 v[82:97], v[122:129], v[130:137], v[82:97], v194, v193 op_sel_hi:[0,0,0]
	v_exp_f32_e32 v0, v110
	v_exp_f32_e32 v177, v111
	v_exp_f32_e32 v179, v112
	v_exp_f32_e32 v254, v113
	v_add_f32_e32 v219, v0, v219
	v_add_f32_e32 v219, v177, v219
	v_cvt_pk_fp8_f32 v253, v0, v177
	v_add_f32_e32 v219, v179, v219
	v_add_f32_e32 v219, v254, v219
	v_cvt_pk_fp8_f32 v253, v179, v254 op_sel:[0,0,1]
	ds_read_b128 v[122:125], v185 offset:8192
	ds_read_b128 v[126:129], v186 offset:8192
	ds_read_b128 v[114:117], v185 offset:10240
	ds_read_b128 v[118:121], v186 offset:10240
	ds_read_b128 v[106:109], v185 offset:12288
	ds_read_b128 v[110:113], v186 offset:12288
	ds_read_b128 v[98:101], v185 offset:14336
	ds_read_b128 v[102:105], v186 offset:14336
	s_waitcnt lgkmcnt(8)
	v_mfma_scale_f32_32x32x64_f8f6f4 v[66:81], v[222:229], v[130:137], v[66:81], v194, v193 op_sel_hi:[0,0,0]
	v_mov_b32_e32 v0, v219
	s_nop 1
	v_permlane32_swap_b32_e32 v219, v0
	v_add_f32_e32 v219, v219, v0
	v_add_f32_e32 v209, v209, v219
	v_max_f32_e32 v177, v82, v83
	v_max3_f32 v177, v177, v84, v85
	v_max3_f32 v177, v177, v86, v87
	v_max3_f32 v177, v177, v88, v89
	v_max3_f32 v177, v177, v90, v91
	v_max3_f32 v177, v177, v92, v93
	v_max3_f32 v177, v177, v94, v95
	v_max3_f32 v177, v177, v96, v97
	s_waitcnt lgkmcnt(6)
	v_mfma_scale_f32_32x32x64_f8f6f4 v[50:65], v[246:253], v[122:129], v[50:65], v194, v194 op_sel_hi:[0,0,0]
	s_waitcnt lgkmcnt(4)
	v_mfma_scale_f32_32x32x64_f8f6f4 v[34:49], v[246:253], v[114:121], v[34:49], v194, v194 op_sel_hi:[0,0,0]
	s_waitcnt lgkmcnt(2)
	v_mfma_scale_f32_32x32x64_f8f6f4 v[18:33], v[246:253], v[106:113], v[18:33], v194, v194 op_sel_hi:[0,0,0]
	s_waitcnt lgkmcnt(0)
	v_mfma_scale_f32_32x32x64_f8f6f4 v[2:17], v[246:253], v[98:105], v[2:17], v194, v194 op_sel_hi:[0,0,0]
	s_waitcnt vmcnt(0)
	ds_write_b128 v210, v[158:161]
	ds_write_b128 v211, v[162:165] offset:16384
	ds_write_b128 v212, v[154:157] offset:32768
	v_max_f32_e32 v0, v66, v67
	v_max3_f32 v0, v0, v68, v69
	v_max3_f32 v0, v0, v70, v71
	v_max3_f32 v0, v0, v72, v73
	v_max3_f32 v0, v0, v74, v75
	v_max3_f32 v0, v0, v76, v77
	v_max3_f32 v0, v0, v78, v79
	v_max3_f32 v0, v0, v80, v81
	v_max_f32_e32 v177, v177, v0
	v_mov_b32_e32 v0, v177
	s_nop 1
	v_permlane32_swap_b32_e32 v177, v0
	v_max_f32_e32 v177, v177, v0
	v_cmp_ge_f32_e32 vcc, s90, v177
	s_cmp_eq_u64 vcc, exec
	s_cbranch_scc0 .Lmla_h1_newmax
; __device__ __forceinline__ void finishSM9(f32x16& p0, f32x16& p1, float alpha, float& l_reg, v8i32& p8) {
; #pragma unroll
;   for (int r = 0; r < 16; ++r) { p0[r] = __builtin_amdgcn_exp2f(p0[r]); p1[r] = __builtin_amdgcn_exp2f(p1[r]); }
;   float ps = 0;
; #pragma unroll
;   for (int r = 0; r < 16; ++r) ps += p0[r];
; #pragma unroll
;   for (int r = 0; r < 16; ++r) ps += p1[r];
;   { auto rr = __builtin_amdgcn_permlane32_swap(__float_as_uint(ps), __float_as_uint(ps), false, false);
;     ps = __uint_as_float(rr[0]) + __uint_as_float(rr[1]); }
;   l_reg = l_reg * alpha + ps;
; #pragma unroll
;   for (int g = 0; g < 4; ++g) {
;     int w = __builtin_amdgcn_cvt_pk_fp8_f32(p0[4 * g], p0[4 * g + 1], 0, false); p8[g] = __builtin_amdgcn_cvt_pk_fp8_f32(p0[4 * g + 2], p0[4 * g + 3], w, true);
;     int u = __builtin_amdgcn_cvt_pk_fp8_f32(p1[4 * g], p1[4 * g + 1], 0, false); p8[4 + g] = __builtin_amdgcn_cvt_pk_fp8_f32(p1[4 * g + 2], p1[4 * g + 3], u, true); }
; }
; __device__ __forceinline__ void pv8(f32x16* o, const char* Vt, const v8i32 p8, int r32, int hi) {
;   const int sw = (r32 >> 2) & 3, a0 = r32 * 64 + (((hi * 2) ^ sw) << 4), a1 = r32 * 64 + (((hi * 2 + 1) ^ sw) << 4);
; #pragma unroll
;   for (int d0 = 0; d0 < 4; ++d0) {
;     const v8i32 vf = cat8(*reinterpret_cast<const v4i32*>(Vt + d0 * 2048 + a0), *reinterpret_cast<const v4i32*>(Vt + d0 * 2048 + a1));
;     o[d0] = __builtin_amdgcn_mfma_scale_f32_32x32x64_f8f6f4(p8, vf, o[d0], 0, 0, 0, 127, 0, 127); }
; }
; __device__ __forceinline__ void qkt9(f32x16& p0, f32x16& p1, const char* Kn, const char* Kr, const v8i32* qf, const float init, int r32, int hi) {
; #pragma unroll
;   for (int r = 0; r < 16; ++r) { p0[r] = init; p1[r] = init; }
; #pragma unroll
;   for (int s = 0; s < 2; ++s) { const int c0 = s * 4 + hi * 2;
;     const v8i32 a0 = cat8(*reinterpret_cast<const v4i32*>(Kn + KN8SW(r32, c0)), *reinterpret_cast<const v4i32*>(Kn + KN8SW(r32, c0 + 1)));
;     const v8i32 a1 = cat8(*reinterpret_cast<const v4i32*>(Kn + 4096 + KN8SW(r32, c0)), *reinterpret_cast<const v4i32*>(Kn + 4096 + KN8SW(r32, c0 + 1)));
;     p0 = __builtin_amdgcn_mfma_scale_f32_32x32x64_f8f6f4(a0, qf[s], p0, 0, 0, 0, 127, 0, 124);
;     p1 = __builtin_amdgcn_mfma_scale_f32_32x32x64_f8f6f4(a1, qf[s], p1, 0, 0, 0, 127, 0, 124); }
;   { const int c0 = hi * 2;
.Lmla_h1_cont:
	s_waitcnt lgkmcnt(0)
	s_barrier
	global_load_dwordx4 v[158:161], v176, s[18:19]
	global_load_dwordx4 v[162:165], v178, s[16:17]
	global_load_dwordx4 v[154:157], v[180:181], off
	ds_read_b128 v[114:117], v215 offset:16384
	ds_read_b128 v[118:121], v216 offset:16384
	ds_read_b128 v[222:225], v215 offset:20480
	ds_read_b128 v[226:229], v216 offset:20480
	v_add_u32_e32 v176, 0x2000, v176
	v_add_u32_e32 v178, 0x20000, v178
	s_mov_b64 s[20:21], 0x1000
	v_lshl_add_u64 v[180:181], v[180:181], 0, s[20:21]
	v_exp_f32_e32 v0, v82
	v_exp_f32_e32 v177, v83
	v_exp_f32_e32 v179, v84
	v_exp_f32_e32 v254, v85
	v_add_f32_e32 v219, v0, v177
	v_cvt_pk_fp8_f32 v246, v0, v177
	v_add_f32_e32 v219, v179, v219
	v_add_f32_e32 v219, v254, v219
	v_cvt_pk_fp8_f32 v246, v179, v254 op_sel:[0,0,1]
	s_waitcnt lgkmcnt(2)
	v_mfma_scale_f32_32x32x64_f8f6f4 v[114:129], v[114:121], v[146:153], v[230:245], v194, v193 op_sel_hi:[0,0,0]
	v_exp_f32_e32 v0, v86
	v_exp_f32_e32 v177, v87
	v_exp_f32_e32 v179, v88
	v_exp_f32_e32 v254, v89
	v_add_f32_e32 v219, v0, v219
	v_add_f32_e32 v219, v177, v219
	v_cvt_pk_fp8_f32 v247, v0, v177
	v_add_f32_e32 v219, v179, v219
	v_add_f32_e32 v219, v254, v219
	v_cvt_pk_fp8_f32 v247, v179, v254 op_sel:[0,0,1]
	ds_read_b128 v[82:85], v213 offset:16384
	ds_read_b128 v[86:89], v214 offset:16384
	s_waitcnt lgkmcnt(2)
	v_mfma_scale_f32_32x32x64_f8f6f4 v[98:113], v[222:229], v[146:153], v[230:245], v194, v193 op_sel_hi:[0,0,0]
	ds_read_b128 v[222:225], v213 offset:20480
	ds_read_b128 v[226:229], v214 offset:20480
	v_exp_f32_e32 v0, v90
	v_exp_f32_e32 v177, v91
	v_exp_f32_e32 v179, v92
	v_exp_f32_e32 v254, v93
	v_add_f32_e32 v219, v0, v219
	v_add_f32_e32 v219, v177, v219
	v_cvt_pk_fp8_f32 v248, v0, v177
	v_add_f32_e32 v219, v179, v219
	v_add_f32_e32 v219, v254, v219
	v_cvt_pk_fp8_f32 v248, v179, v254 op_sel:[0,0,1]
	v_exp_f32_e32 v0, v94
	v_exp_f32_e32 v177, v95
	v_exp_f32_e32 v179, v96
	v_exp_f32_e32 v254, v97
	v_add_f32_e32 v219, v0, v219
	v_add_f32_e32 v219, v177, v219
	v_cvt_pk_fp8_f32 v249, v0, v177
	v_add_f32_e32 v219, v179, v219
	v_add_f32_e32 v219, v254, v219
	v_cvt_pk_fp8_f32 v249, v179, v254 op_sel:[0,0,1]
	ds_read_b128 v[90:93], v185 offset:32768
	ds_read_b128 v[94:97], v186 offset:32768
	s_waitcnt lgkmcnt(4)
	v_mfma_scale_f32_32x32x64_f8f6f4 v[114:129], v[82:89], v[138:145], v[114:129], v194, v193 op_sel_hi:[0,0,0]
	v_exp_f32_e32 v0, v66
	v_exp_f32_e32 v177, v67
	v_exp_f32_e32 v179, v68
	v_exp_f32_e32 v254, v69
	v_add_f32_e32 v219, v0, v219
	v_add_f32_e32 v219, v177, v219
	v_cvt_pk_fp8_f32 v250, v0, v177
	v_add_f32_e32 v219, v179, v219
	v_add_f32_e32 v219, v254, v219
	v_cvt_pk_fp8_f32 v250, v179, v254 op_sel:[0,0,1]
	s_waitcnt lgkmcnt(2)
	v_mfma_scale_f32_32x32x64_f8f6f4 v[98:113], v[222:229], v[138:145], v[98:113], v194, v193 op_sel_hi:[0,0,0]
	ds_read_b128 v[222:225], v185 offset:34816
	ds_read_b128 v[226:229], v186 offset:34816
	v_exp_f32_e32 v0, v70
	v_exp_f32_e32 v177, v71
	v_exp_f32_e32 v179, v72
	v_exp_f32_e32 v254, v73
	v_add_f32_e32 v219, v0, v219
	v_add_f32_e32 v219, v177, v219
	v_cvt_pk_fp8_f32 v251, v0, v177
	v_add_f32_e32 v219, v179, v219
	v_add_f32_e32 v219, v254, v219
	v_cvt_pk_fp8_f32 v251, v179, v254 op_sel:[0,0,1]
	v_exp_f32_e32 v0, v74
	v_exp_f32_e32 v177, v75
	v_exp_f32_e32 v179, v76
	v_exp_f32_e32 v254, v77
	v_add_f32_e32 v219, v0, v219
	v_add_f32_e32 v219, v177, v219
	v_cvt_pk_fp8_f32 v252, v0, v177
	v_add_f32_e32 v219, v179, v219
	v_add_f32_e32 v219, v254, v219
	v_cvt_pk_fp8_f32 v252, v179, v254 op_sel:[0,0,1]
	s_waitcnt lgkmcnt(2)
	v_mfma_scale_f32_32x32x64_f8f6f4 v[114:129], v[90:97], v[130:137], v[114:129], v194, v193 op_sel_hi:[0,0,0]
	v_exp_f32_e32 v0, v78
	v_exp_f32_e32 v177, v79
	v_exp_f32_e32 v179, v80
	v_exp_f32_e32 v254, v81
	v_add_f32_e32 v219, v0, v219
	v_add_f32_e32 v219, v177, v219
	v_cvt_pk_fp8_f32 v253, v0, v177
	v_add_f32_e32 v219, v179, v219
	v_add_f32_e32 v219, v254, v219
	v_cvt_pk_fp8_f32 v253, v179, v254 op_sel:[0,0,1]
	ds_read_b128 v[90:93], v185 offset:43008
	ds_read_b128 v[94:97], v186 offset:43008
	ds_read_b128 v[82:85], v185 offset:45056
	ds_read_b128 v[86:89], v186 offset:45056
	ds_read_b128 v[74:77], v185 offset:47104
	ds_read_b128 v[78:81], v186 offset:47104
	ds_read_b128 v[66:69], v185 offset:49152
	ds_read_b128 v[70:73], v186 offset:49152
	s_waitcnt lgkmcnt(8)
	v_mfma_scale_f32_32x32x64_f8f6f4 v[98:113], v[222:229], v[130:137], v[98:113], v194, v193 op_sel_hi:[0,0,0]
	v_mov_b32_e32 v0, v219
	s_nop 1
	v_permlane32_swap_b32_e32 v219, v0
	v_add_f32_e32 v219, v219, v0
	v_add_f32_e32 v209, v209, v219
	v_max_f32_e32 v177, v114, v115
	v_max3_f32 v177, v177, v116, v117
	v_max3_f32 v177, v177, v118, v119
	v_max3_f32 v177, v177, v120, v121
	v_max3_f32 v177, v177, v122, v123
	v_max3_f32 v177, v177, v124, v125
	v_max3_f32 v177, v177, v126, v127
	v_max3_f32 v177, v177, v128, v129
	s_waitcnt lgkmcnt(6)
	v_mfma_scale_f32_32x32x64_f8f6f4 v[50:65], v[246:253], v[90:97], v[50:65], v194, v194 op_sel_hi:[0,0,0]
	s_waitcnt lgkmcnt(4)
	v_mfma_scale_f32_32x32x64_f8f6f4 v[34:49], v[246:253], v[82:89], v[34:49], v194, v194 op_sel_hi:[0,0,0]
	s_waitcnt lgkmcnt(2)
	v_mfma_scale_f32_32x32x64_f8f6f4 v[18:33], v[246:253], v[74:81], v[18:33], v194, v194 op_sel_hi:[0,0,0]
	s_waitcnt lgkmcnt(0)
	v_mfma_scale_f32_32x32x64_f8f6f4 v[2:17], v[246:253], v[66:73], v[2:17], v194, v194 op_sel_hi:[0,0,0]
	s_waitcnt vmcnt(0)
	ds_write_b128 v210, v[158:161] offset:8192
	ds_write_b128 v211, v[162:165] offset:24576
	ds_write_b128 v212, v[154:157] offset:36864
	v_max_f32_e32 v0, v98, v99
	v_max3_f32 v0, v0, v100, v101
	v_max3_f32 v0, v0, v102, v103
	v_max3_f32 v0, v0, v104, v105
	v_max3_f32 v0, v0, v106, v107
	v_max3_f32 v0, v0, v108, v109
	v_max3_f32 v0, v0, v110, v111
	v_max3_f32 v0, v0, v112, v113
	v_max_f32_e32 v177, v177, v0
	v_mov_b32_e32 v0, v177
	s_nop 1
	v_permlane32_swap_b32_e32 v177, v0
	v_max_f32_e32 v177, v177, v0
	v_cmp_ge_f32_e32 vcc, s90, v177
	s_cmp_eq_u64 vcc, exec
	s_cbranch_scc0 .Lmla_h2_newmax
; __device__ __forceinline__ void finishSM9(f32x16& p0, f32x16& p1, float alpha, float& l_reg, v8i32& p8) {
; #pragma unroll
;   for (int r = 0; r < 16; ++r) { p0[r] = __builtin_amdgcn_exp2f(p0[r]); p1[r] = __builtin_amdgcn_exp2f(p1[r]); }
;   float ps = 0;
; #pragma unroll
;   for (int r = 0; r < 16; ++r) ps += p0[r];
; #pragma unroll
;   for (int r = 0; r < 16; ++r) ps += p1[r];
;   { auto rr = __builtin_amdgcn_permlane32_swap(__float_as_uint(ps), __float_as_uint(ps), false, false);
;     ps = __uint_as_float(rr[0]) + __uint_as_float(rr[1]); }
;   l_reg = l_reg * alpha + ps;
; #pragma unroll
;   for (int g = 0; g < 4; ++g) {
;     int w = __builtin_amdgcn_cvt_pk_fp8_f32(p0[4 * g], p0[4 * g + 1], 0, false); p8[g] = __builtin_amdgcn_cvt_pk_fp8_f32(p0[4 * g + 2], p0[4 * g + 3], w, true);
;     int u = __builtin_amdgcn_cvt_pk_fp8_f32(p1[4 * g], p1[4 * g + 1], 0, false); p8[4 + g] = __builtin_amdgcn_cvt_pk_fp8_f32(p1[4 * g + 2], p1[4 * g + 3], u, true); }
; }
; __device__ __forceinline__ void pv8(f32x16* o, const char* Vt, const v8i32 p8, int r32, int hi) {
;   const int sw = (r32 >> 2) & 3, a0 = r32 * 64 + (((hi * 2) ^ sw) << 4), a1 = r32 * 64 + (((hi * 2 + 1) ^ sw) << 4);
; #pragma unroll
;   for (int d0 = 0; d0 < 4; ++d0) {
;     const v8i32 vf = cat8(*reinterpret_cast<const v4i32*>(Vt + d0 * 2048 + a0), *reinterpret_cast<const v4i32*>(Vt + d0 * 2048 + a1));
;     o[d0] = __builtin_amdgcn_mfma_scale_f32_32x32x64_f8f6f4(p8, vf, o[d0], 0, 0, 0, 127, 0, 127); }
; }
; __device__ __forceinline__ void qkt9(f32x16& p0, f32x16& p1, const char* Kn, const char* Kr, const v8i32* qf, const float init, int r32, int hi) {
; #pragma unroll
;   for (int r = 0; r < 16; ++r) { p0[r] = init; p1[r] = init; }
; #pragma unroll
;   for (int s = 0; s < 2; ++s) { const int c0 = s * 4 + hi * 2;
;     const v8i32 a0 = cat8(*reinterpret_cast<const v4i32*>(Kn + KN8SW(r32, c0)), *reinterpret_cast<const v4i32*>(Kn + KN8SW(r32, c0 + 1)));
;     const v8i32 a1 = cat8(*reinterpret_cast<const v4i32*>(Kn + 4096 + KN8SW(r32, c0)), *reinterpret_cast<const v4i32*>(Kn + 4096 + KN8SW(r32, c0 + 1)));
;     p0 = __builtin_amdgcn_mfma_scale_f32_32x32x64_f8f6f4(a0, qf[s], p0, 0, 0, 0, 127, 0, 124);
;     p1 = __builtin_amdgcn_mfma_scale_f32_32x32x64_f8f6f4(a1, qf[s], p1, 0, 0, 0, 127, 0, 124); }
;   { const int c0 = hi * 2;
.Lmla_h2_cont:
	s_waitcnt lgkmcnt(0)
	s_barrier
	global_load_dwordx4 v[158:161], v176, s[18:19]
	global_load_dwordx4 v[162:165], v178, s[16:17]
	global_load_dwordx4 v[154:157], v[180:181], off
	ds_read_b128 v[82:85], v215 offset:24576
	ds_read_b128 v[86:89], v216 offset:24576
	ds_read_b128 v[222:225], v215 offset:28672
	ds_read_b128 v[226:229], v216 offset:28672
	v_add_u32_e32 v176, 0x2000, v176
	v_add_u32_e32 v178, 0x20000, v178
	s_mov_b64 s[20:21], 0x1000
	v_lshl_add_u64 v[180:181], v[180:181], 0, s[20:21]
	v_exp_f32_e32 v0, v114
	v_exp_f32_e32 v177, v115
	v_exp_f32_e32 v179, v116
	v_exp_f32_e32 v254, v117
	v_add_f32_e32 v219, v0, v177
	v_cvt_pk_fp8_f32 v246, v0, v177
	v_add_f32_e32 v219, v179, v219
	v_add_f32_e32 v219, v254, v219
	v_cvt_pk_fp8_f32 v246, v179, v254 op_sel:[0,0,1]
	s_waitcnt lgkmcnt(2)
	v_mfma_scale_f32_32x32x64_f8f6f4 v[82:97], v[82:89], v[146:153], v[230:245], v194, v193 op_sel_hi:[0,0,0]
	v_exp_f32_e32 v0, v118
	v_exp_f32_e32 v177, v119
	v_exp_f32_e32 v179, v120
	v_exp_f32_e32 v254, v121
	v_add_f32_e32 v219, v0, v219
	v_add_f32_e32 v219, v177, v219
	v_cvt_pk_fp8_f32 v247, v0, v177
	v_add_f32_e32 v219, v179, v219
	v_add_f32_e32 v219, v254, v219
	v_cvt_pk_fp8_f32 v247, v179, v254 op_sel:[0,0,1]
	ds_read_b128 v[114:117], v213 offset:24576
	ds_read_b128 v[118:121], v214 offset:24576
	s_waitcnt lgkmcnt(2)
	v_mfma_scale_f32_32x32x64_f8f6f4 v[66:81], v[222:229], v[146:153], v[230:245], v194, v193 op_sel_hi:[0,0,0]
	ds_read_b128 v[222:225], v213 offset:28672
	ds_read_b128 v[226:229], v214 offset:28672
	v_exp_f32_e32 v0, v122
	v_exp_f32_e32 v177, v123
	v_exp_f32_e32 v179, v124
	v_exp_f32_e32 v254, v125
	v_add_f32_e32 v219, v0, v219
	v_add_f32_e32 v219, v177, v219
	v_cvt_pk_fp8_f32 v248, v0, v177
	v_add_f32_e32 v219, v179, v219
	v_add_f32_e32 v219, v254, v219
	v_cvt_pk_fp8_f32 v248, v179, v254 op_sel:[0,0,1]
	v_exp_f32_e32 v0, v126
	v_exp_f32_e32 v177, v127
	v_exp_f32_e32 v179, v128
	v_exp_f32_e32 v254, v129
	v_add_f32_e32 v219, v0, v219
	v_add_f32_e32 v219, v177, v219
	v_cvt_pk_fp8_f32 v249, v0, v177
	v_add_f32_e32 v219, v179, v219
	v_add_f32_e32 v219, v254, v219
	v_cvt_pk_fp8_f32 v249, v179, v254 op_sel:[0,0,1]
	ds_read_b128 v[122:125], v185 offset:36864
	ds_read_b128 v[126:129], v186 offset:36864
	s_waitcnt lgkmcnt(4)
	v_mfma_scale_f32_32x32x64_f8f6f4 v[82:97], v[114:121], v[138:145], v[82:97], v194, v193 op_sel_hi:[0,0,0]
	v_exp_f32_e32 v0, v98
	v_exp_f32_e32 v177, v99
	v_exp_f32_e32 v179, v100
	v_exp_f32_e32 v254, v101
	v_add_f32_e32 v219, v0, v219
	v_add_f32_e32 v219, v177, v219
	v_cvt_pk_fp8_f32 v250, v0, v177
	v_add_f32_e32 v219, v179, v219
	v_add_f32_e32 v219, v254, v219
	v_cvt_pk_fp8_f32 v250, v179, v254 op_sel:[0,0,1]
	s_waitcnt lgkmcnt(2)
	v_mfma_scale_f32_32x32x64_f8f6f4 v[66:81], v[222:229], v[138:145], v[66:81], v194, v193 op_sel_hi:[0,0,0]
	ds_read_b128 v[222:225], v185 offset:38912
	ds_read_b128 v[226:229], v186 offset:38912
	v_exp_f32_e32 v0, v102
	v_exp_f32_e32 v177, v103
	v_exp_f32_e32 v179, v104
	v_exp_f32_e32 v254, v105
	v_add_f32_e32 v219, v0, v219
	v_add_f32_e32 v219, v177, v219
	v_cvt_pk_fp8_f32 v251, v0, v177
	v_add_f32_e32 v219, v179, v219
	v_add_f32_e32 v219, v254, v219
	v_cvt_pk_fp8_f32 v251, v179, v254 op_sel:[0,0,1]
	v_exp_f32_e32 v0, v106
	v_exp_f32_e32 v177, v107
	v_exp_f32_e32 v179, v108
	v_exp_f32_e32 v254, v109
	v_add_f32_e32 v219, v0, v219
	v_add_f32_e32 v219, v177, v219
	v_cvt_pk_fp8_f32 v252, v0, v177
	v_add_f32_e32 v219, v179, v219
	v_add_f32_e32 v219, v254, v219
	v_cvt_pk_fp8_f32 v252, v179, v254 op_sel:[0,0,1]
	s_waitcnt lgkmcnt(2)
	v_mfma_scale_f32_32x32x64_f8f6f4 v[82:97], v[122:129], v[130:137], v[82:97], v194, v193 op_sel_hi:[0,0,0]
	v_exp_f32_e32 v0, v110
	v_exp_f32_e32 v177, v111
	v_exp_f32_e32 v179, v112
	v_exp_f32_e32 v254, v113
	v_add_f32_e32 v219, v0, v219
	v_add_f32_e32 v219, v177, v219
	v_cvt_pk_fp8_f32 v253, v0, v177
	v_add_f32_e32 v219, v179, v219
	v_add_f32_e32 v219, v254, v219
	v_cvt_pk_fp8_f32 v253, v179, v254 op_sel:[0,0,1]
	ds_read_b128 v[122:125], v185 offset:0
	ds_read_b128 v[126:129], v186 offset:0
	ds_read_b128 v[114:117], v185 offset:2048
	ds_read_b128 v[118:121], v186 offset:2048
	ds_read_b128 v[106:109], v185 offset:4096
	ds_read_b128 v[110:113], v186 offset:4096
	ds_read_b128 v[98:101], v185 offset:6144
	ds_read_b128 v[102:105], v186 offset:6144
	s_waitcnt lgkmcnt(8)
	v_mfma_scale_f32_32x32x64_f8f6f4 v[66:81], v[222:229], v[130:137], v[66:81], v194, v193 op_sel_hi:[0,0,0]
	v_mov_b32_e32 v0, v219
	s_nop 1
	v_permlane32_swap_b32_e32 v219, v0
	v_add_f32_e32 v219, v219, v0
	v_add_f32_e32 v209, v209, v219
	v_max_f32_e32 v177, v82, v83
	v_max3_f32 v177, v177, v84, v85
	v_max3_f32 v177, v177, v86, v87
	v_max3_f32 v177, v177, v88, v89
	v_max3_f32 v177, v177, v90, v91
	v_max3_f32 v177, v177, v92, v93
	v_max3_f32 v177, v177, v94, v95
	v_max3_f32 v177, v177, v96, v97
	s_waitcnt lgkmcnt(6)
	v_mfma_scale_f32_32x32x64_f8f6f4 v[50:65], v[246:253], v[122:129], v[50:65], v194, v194 op_sel_hi:[0,0,0]
	s_waitcnt lgkmcnt(4)
	v_mfma_scale_f32_32x32x64_f8f6f4 v[34:49], v[246:253], v[114:121], v[34:49], v194, v194 op_sel_hi:[0,0,0]
	s_waitcnt lgkmcnt(2)
	v_mfma_scale_f32_32x32x64_f8f6f4 v[18:33], v[246:253], v[106:113], v[18:33], v194, v194 op_sel_hi:[0,0,0]
	s_waitcnt lgkmcnt(0)
	v_mfma_scale_f32_32x32x64_f8f6f4 v[2:17], v[246:253], v[98:105], v[2:17], v194, v194 op_sel_hi:[0,0,0]
	s_waitcnt vmcnt(0)
	ds_write_b128 v210, v[158:161] offset:43008
	ds_write_b128 v211, v[162:165] offset:51200
	ds_write_b128 v212, v[154:157] offset:59392
	v_max_f32_e32 v0, v66, v67
	v_max3_f32 v0, v0, v68, v69
	v_max3_f32 v0, v0, v70, v71
	v_max3_f32 v0, v0, v72, v73
	v_max3_f32 v0, v0, v74, v75
	v_max3_f32 v0, v0, v76, v77
	v_max3_f32 v0, v0, v78, v79
	v_max3_f32 v0, v0, v80, v81
	v_max_f32_e32 v177, v177, v0
	v_mov_b32_e32 v0, v177
	s_nop 1
	v_permlane32_swap_b32_e32 v177, v0
	v_max_f32_e32 v177, v177, v0
	v_cmp_ge_f32_e32 vcc, s90, v177
	s_cmp_eq_u64 vcc, exec
	s_cbranch_scc0 .Lmla_h3_newmax
; __device__ __forceinline__ void finishSM9(f32x16& p0, f32x16& p1, float alpha, float& l_reg, v8i32& p8) {
; #pragma unroll
;   for (int r = 0; r < 16; ++r) { p0[r] = __builtin_amdgcn_exp2f(p0[r]); p1[r] = __builtin_amdgcn_exp2f(p1[r]); }
;   float ps = 0;
; #pragma unroll
;   for (int r = 0; r < 16; ++r) ps += p0[r];
; #pragma unroll
;   for (int r = 0; r < 16; ++r) ps += p1[r];
;   { auto rr = __builtin_amdgcn_permlane32_swap(__float_as_uint(ps), __float_as_uint(ps), false, false);
;     ps = __uint_as_float(rr[0]) + __uint_as_float(rr[1]); }
;   l_reg = l_reg * alpha + ps;
; #pragma unroll
;   for (int g = 0; g < 4; ++g) {
;     int w = __builtin_amdgcn_cvt_pk_fp8_f32(p0[4 * g], p0[4 * g + 1], 0, false); p8[g] = __builtin_amdgcn_cvt_pk_fp8_f32(p0[4 * g + 2], p0[4 * g + 3], w, true);
;     int u = __builtin_amdgcn_cvt_pk_fp8_f32(p1[4 * g], p1[4 * g + 1], 0, false); p8[4 + g] = __builtin_amdgcn_cvt_pk_fp8_f32(p1[4 * g + 2], p1[4 * g + 3], u, true); }
; }
; __device__ __forceinline__ void pv8(f32x16* o, const char* Vt, const v8i32 p8, int r32, int hi) {
;   const int sw = (r32 >> 2) & 3, a0 = r32 * 64 + (((hi * 2) ^ sw) << 4), a1 = r32 * 64 + (((hi * 2 + 1) ^ sw) << 4);
; #pragma unroll
;   for (int d0 = 0; d0 < 4; ++d0) {
;     const v8i32 vf = cat8(*reinterpret_cast<const v4i32*>(Vt + d0 * 2048 + a0), *reinterpret_cast<const v4i32*>(Vt + d0 * 2048 + a1));
;     o[d0] = __builtin_amdgcn_mfma_scale_f32_32x32x64_f8f6f4(p8, vf, o[d0], 0, 0, 0, 127, 0, 127); }
; }
; __device__ __forceinline__ void qkt9(f32x16& p0, f32x16& p1, const char* Kn, const char* Kr, const v8i32* qf, const float init, int r32, int hi) {
; #pragma unroll
;   for (int r = 0; r < 16; ++r) { p0[r] = init; p1[r] = init; }
; #pragma unroll
;   for (int s = 0; s < 2; ++s) { const int c0 = s * 4 + hi * 2;
;     const v8i32 a0 = cat8(*reinterpret_cast<const v4i32*>(Kn + KN8SW(r32, c0)), *reinterpret_cast<const v4i32*>(Kn + KN8SW(r32, c0 + 1)));
;     const v8i32 a1 = cat8(*reinterpret_cast<const v4i32*>(Kn + 4096 + KN8SW(r32, c0)), *reinterpret_cast<const v4i32*>(Kn + 4096 + KN8SW(r32, c0 + 1)));
;     p0 = __builtin_amdgcn_mfma_scale_f32_32x32x64_f8f6f4(a0, qf[s], p0, 0, 0, 0, 127, 0, 124);
;     p1 = __builtin_amdgcn_mfma_scale_f32_32x32x64_f8f6f4(a1, qf[s], p1, 0, 0, 0, 127, 0, 124); }
;   { const int c0 = hi * 2;
.Lmla_h3_cont:
	s_waitcnt lgkmcnt(0)
	s_barrier
	global_load_dwordx4 v[158:161], v176, s[18:19]
	global_load_dwordx4 v[162:165], v178, s[16:17]
	global_load_dwordx4 v[154:157], v[180:181], off
	ds_read_b128 v[114:117], v215 offset:51200
	ds_read_b128 v[118:121], v216 offset:51200
	ds_read_b128 v[222:225], v215 offset:55296
	ds_read_b128 v[226:229], v216 offset:55296
	v_add_u32_e32 v176, 0x2000, v176
	v_add_u32_e32 v178, 0x20000, v178
	s_mov_b64 s[20:21], 0x1000
	v_lshl_add_u64 v[180:181], v[180:181], 0, s[20:21]
	v_exp_f32_e32 v0, v82
	v_exp_f32_e32 v177, v83
	v_exp_f32_e32 v179, v84
	v_exp_f32_e32 v254, v85
	v_add_f32_e32 v219, v0, v177
	v_cvt_pk_fp8_f32 v246, v0, v177
	v_add_f32_e32 v219, v179, v219
	v_add_f32_e32 v219, v254, v219
	v_cvt_pk_fp8_f32 v246, v179, v254 op_sel:[0,0,1]
	s_waitcnt lgkmcnt(2)
	v_mfma_scale_f32_32x32x64_f8f6f4 v[114:129], v[114:121], v[146:153], v[230:245], v194, v193 op_sel_hi:[0,0,0]
	v_exp_f32_e32 v0, v86
	v_exp_f32_e32 v177, v87
	v_exp_f32_e32 v179, v88
	v_exp_f32_e32 v254, v89
	v_add_f32_e32 v219, v0, v219
	v_add_f32_e32 v219, v177, v219
	v_cvt_pk_fp8_f32 v247, v0, v177
	v_add_f32_e32 v219, v179, v219
	v_add_f32_e32 v219, v254, v219
	v_cvt_pk_fp8_f32 v247, v179, v254 op_sel:[0,0,1]
	ds_read_b128 v[82:85], v213 offset:51200
	ds_read_b128 v[86:89], v214 offset:51200
	s_waitcnt lgkmcnt(2)
	v_mfma_scale_f32_32x32x64_f8f6f4 v[98:113], v[222:229], v[146:153], v[230:245], v194, v193 op_sel_hi:[0,0,0]
	ds_read_b128 v[222:225], v213 offset:55296
	ds_read_b128 v[226:229], v214 offset:55296
	v_exp_f32_e32 v0, v90
	v_exp_f32_e32 v177, v91
	v_exp_f32_e32 v179, v92
	v_exp_f32_e32 v254, v93
	v_add_f32_e32 v219, v0, v219
	v_add_f32_e32 v219, v177, v219
	v_cvt_pk_fp8_f32 v248, v0, v177
	v_add_f32_e32 v219, v179, v219
	v_add_f32_e32 v219, v254, v219
	v_cvt_pk_fp8_f32 v248, v179, v254 op_sel:[0,0,1]
	v_exp_f32_e32 v0, v94
	v_exp_f32_e32 v177, v95
	v_exp_f32_e32 v179, v96
	v_exp_f32_e32 v254, v97
	v_add_f32_e32 v219, v0, v219
	v_add_f32_e32 v219, v177, v219
	v_cvt_pk_fp8_f32 v249, v0, v177
	v_add_f32_e32 v219, v179, v219
	v_add_f32_e32 v219, v254, v219
	v_cvt_pk_fp8_f32 v249, v179, v254 op_sel:[0,0,1]
	ds_read_b128 v[90:93], v185 offset:59392
	ds_read_b128 v[94:97], v186 offset:59392
	s_waitcnt lgkmcnt(4)
	v_mfma_scale_f32_32x32x64_f8f6f4 v[114:129], v[82:89], v[138:145], v[114:129], v194, v193 op_sel_hi:[0,0,0]
	v_exp_f32_e32 v0, v66
	v_exp_f32_e32 v177, v67
	v_exp_f32_e32 v179, v68
	v_exp_f32_e32 v254, v69
	v_add_f32_e32 v219, v0, v219
	v_add_f32_e32 v219, v177, v219
	v_cvt_pk_fp8_f32 v250, v0, v177
	v_add_f32_e32 v219, v179, v219
	v_add_f32_e32 v219, v254, v219
	v_cvt_pk_fp8_f32 v250, v179, v254 op_sel:[0,0,1]
	s_waitcnt lgkmcnt(2)
	v_mfma_scale_f32_32x32x64_f8f6f4 v[98:113], v[222:229], v[138:145], v[98:113], v194, v193 op_sel_hi:[0,0,0]
	ds_read_b128 v[222:225], v185 offset:61440
	ds_read_b128 v[226:229], v186 offset:61440
	v_exp_f32_e32 v0, v70
	v_exp_f32_e32 v177, v71
	v_exp_f32_e32 v179, v72
	v_exp_f32_e32 v254, v73
	v_add_f32_e32 v219, v0, v219
	v_add_f32_e32 v219, v177, v219
	v_cvt_pk_fp8_f32 v251, v0, v177
	v_add_f32_e32 v219, v179, v219
	v_add_f32_e32 v219, v254, v219
	v_cvt_pk_fp8_f32 v251, v179, v254 op_sel:[0,0,1]
	v_exp_f32_e32 v0, v74
	v_exp_f32_e32 v177, v75
	v_exp_f32_e32 v179, v76
	v_exp_f32_e32 v254, v77
	v_add_f32_e32 v219, v0, v219
	v_add_f32_e32 v219, v177, v219
	v_cvt_pk_fp8_f32 v252, v0, v177
	v_add_f32_e32 v219, v179, v219
	v_add_f32_e32 v219, v254, v219
	v_cvt_pk_fp8_f32 v252, v179, v254 op_sel:[0,0,1]
	s_waitcnt lgkmcnt(2)
	v_mfma_scale_f32_32x32x64_f8f6f4 v[114:129], v[90:97], v[130:137], v[114:129], v194, v193 op_sel_hi:[0,0,0]
	v_exp_f32_e32 v0, v78
	v_exp_f32_e32 v177, v79
	v_exp_f32_e32 v179, v80
	v_exp_f32_e32 v254, v81
	v_add_f32_e32 v219, v0, v219
	v_add_f32_e32 v219, v177, v219
	v_cvt_pk_fp8_f32 v253, v0, v177
	v_add_f32_e32 v219, v179, v219
	v_add_f32_e32 v219, v254, v219
	v_cvt_pk_fp8_f32 v253, v179, v254 op_sel:[0,0,1]
	ds_read_b128 v[90:93], v185 offset:8192
	ds_read_b128 v[94:97], v186 offset:8192
	ds_read_b128 v[82:85], v185 offset:10240
	ds_read_b128 v[86:89], v186 offset:10240
	ds_read_b128 v[74:77], v185 offset:12288
	ds_read_b128 v[78:81], v186 offset:12288
	ds_read_b128 v[66:69], v185 offset:14336
	ds_read_b128 v[70:73], v186 offset:14336
	s_waitcnt lgkmcnt(8)
	v_mfma_scale_f32_32x32x64_f8f6f4 v[98:113], v[222:229], v[130:137], v[98:113], v194, v193 op_sel_hi:[0,0,0]
	v_mov_b32_e32 v0, v219
	s_nop 1
	v_permlane32_swap_b32_e32 v219, v0
	v_add_f32_e32 v219, v219, v0
	v_add_f32_e32 v209, v209, v219
	v_max_f32_e32 v177, v114, v115
	v_max3_f32 v177, v177, v116, v117
	v_max3_f32 v177, v177, v118, v119
	v_max3_f32 v177, v177, v120, v121
	v_max3_f32 v177, v177, v122, v123
	v_max3_f32 v177, v177, v124, v125
	v_max3_f32 v177, v177, v126, v127
	v_max3_f32 v177, v177, v128, v129
	s_waitcnt lgkmcnt(6)
	v_mfma_scale_f32_32x32x64_f8f6f4 v[50:65], v[246:253], v[90:97], v[50:65], v194, v194 op_sel_hi:[0,0,0]
	s_waitcnt lgkmcnt(4)
	v_mfma_scale_f32_32x32x64_f8f6f4 v[34:49], v[246:253], v[82:89], v[34:49], v194, v194 op_sel_hi:[0,0,0]
	s_waitcnt lgkmcnt(2)
	v_mfma_scale_f32_32x32x64_f8f6f4 v[18:33], v[246:253], v[74:81], v[18:33], v194, v194 op_sel_hi:[0,0,0]
	s_waitcnt lgkmcnt(0)
	v_mfma_scale_f32_32x32x64_f8f6f4 v[2:17], v[246:253], v[66:73], v[2:17], v194, v194 op_sel_hi:[0,0,0]
	s_waitcnt vmcnt(0)
	ds_write_b128 v210, v[158:161]
	ds_write_b128 v211, v[162:165] offset:16384
	ds_write_b128 v212, v[154:157] offset:32768
	v_max_f32_e32 v0, v98, v99
	v_max3_f32 v0, v0, v100, v101
	v_max3_f32 v0, v0, v102, v103
	v_max3_f32 v0, v0, v104, v105
	v_max3_f32 v0, v0, v106, v107
	v_max3_f32 v0, v0, v108, v109
	v_max3_f32 v0, v0, v110, v111
	v_max3_f32 v0, v0, v112, v113
	v_max_f32_e32 v177, v177, v0
	v_mov_b32_e32 v0, v177
	s_nop 1
	v_permlane32_swap_b32_e32 v177, v0
	v_max_f32_e32 v177, v177, v0
	v_cmp_ge_f32_e32 vcc, s90, v177
	s_cmp_eq_u64 vcc, exec
	s_cbranch_scc0 .Lmla_h4_newmax
; __device__ __forceinline__ void finishSM9(f32x16& p0, f32x16& p1, float alpha, float& l_reg, v8i32& p8) {
; #pragma unroll
;   for (int r = 0; r < 16; ++r) { p0[r] = __builtin_amdgcn_exp2f(p0[r]); p1[r] = __builtin_amdgcn_exp2f(p1[r]); }
;   float ps = 0;
; #pragma unroll
;   for (int r = 0; r < 16; ++r) ps += p0[r];
; #pragma unroll
;   for (int r = 0; r < 16; ++r) ps += p1[r];
;   { auto rr = __builtin_amdgcn_permlane32_swap(__float_as_uint(ps), __float_as_uint(ps), false, false);
;     ps = __uint_as_float(rr[0]) + __uint_as_float(rr[1]); }
;   l_reg = l_reg * alpha + ps;
; #pragma unroll
;   for (int g = 0; g < 4; ++g) {
;     int w = __builtin_amdgcn_cvt_pk_fp8_f32(p0[4 * g], p0[4 * g + 1], 0, false); p8[g] = __builtin_amdgcn_cvt_pk_fp8_f32(p0[4 * g + 2], p0[4 * g + 3], w, true);
;     int u = __builtin_amdgcn_cvt_pk_fp8_f32(p1[4 * g], p1[4 * g + 1], 0, false); p8[4 + g] = __builtin_amdgcn_cvt_pk_fp8_f32(p1[4 * g + 2], p1[4 * g + 3], u, true); }
; }
; __device__ __forceinline__ void pv8(f32x16* o, const char* Vt, const v8i32 p8, int r32, int hi) {
;   const int sw = (r32 >> 2) & 3, a0 = r32 * 64 + (((hi * 2) ^ sw) << 4), a1 = r32 * 64 + (((hi * 2 + 1) ^ sw) << 4);
; #pragma unroll
;   for (int d0 = 0; d0 < 4; ++d0) {
;     const v8i32 vf = cat8(*reinterpret_cast<const v4i32*>(Vt + d0 * 2048 + a0), *reinterpret_cast<const v4i32*>(Vt + d0 * 2048 + a1));
;     o[d0] = __builtin_amdgcn_mfma_scale_f32_32x32x64_f8f6f4(p8, vf, o[d0], 0, 0, 0, 127, 0, 127); }
; }
; __device__ __forceinline__ void qkt9(f32x16& p0, f32x16& p1, const char* Kn, const char* Kr, const v8i32* qf, const float init, int r32, int hi) {
; #pragma unroll
;   for (int r = 0; r < 16; ++r) { p0[r] = init; p1[r] = init; }
; #pragma unroll
;   for (int s = 0; s < 2; ++s) { const int c0 = s * 4 + hi * 2;
;     const v8i32 a0 = cat8(*reinterpret_cast<const v4i32*>(Kn + KN8SW(r32, c0)), *reinterpret_cast<const v4i32*>(Kn + KN8SW(r32, c0 + 1)));
;     const v8i32 a1 = cat8(*reinterpret_cast<const v4i32*>(Kn + 4096 + KN8SW(r32, c0)), *reinterpret_cast<const v4i32*>(Kn + 4096 + KN8SW(r32, c0 + 1)));
;     p0 = __builtin_amdgcn_mfma_scale_f32_32x32x64_f8f6f4(a0, qf[s], p0, 0, 0, 0, 127, 0, 124);
;     p1 = __builtin_amdgcn_mfma_scale_f32_32x32x64_f8f6f4(a1, qf[s], p1, 0, 0, 0, 127, 0, 124); }
;   { const int c0 = hi * 2;
.Lmla_h4_cont:
	s_waitcnt lgkmcnt(0)
	s_barrier
	global_load_dwordx4 v[158:161], v176, s[18:19]
	global_load_dwordx4 v[162:165], v178, s[16:17]
	global_load_dwordx4 v[154:157], v[180:181], off
	ds_read_b128 v[82:85], v215 offset:16384
	ds_read_b128 v[86:89], v216 offset:16384
	ds_read_b128 v[222:225], v215 offset:20480
	ds_read_b128 v[226:229], v216 offset:20480
	v_add_u32_e32 v176, 0x2000, v176
	v_add_u32_e32 v178, 0x20000, v178
	s_mov_b64 s[20:21], 0x1000
	v_lshl_add_u64 v[180:181], v[180:181], 0, s[20:21]
	v_exp_f32_e32 v0, v114
	v_exp_f32_e32 v177, v115
	v_exp_f32_e32 v179, v116
	v_exp_f32_e32 v254, v117
	v_add_f32_e32 v219, v0, v177
	v_cvt_pk_fp8_f32 v246, v0, v177
	v_add_f32_e32 v219, v179, v219
	v_add_f32_e32 v219, v254, v219
	v_cvt_pk_fp8_f32 v246, v179, v254 op_sel:[0,0,1]
	s_waitcnt lgkmcnt(2)
	v_mfma_scale_f32_32x32x64_f8f6f4 v[82:97], v[82:89], v[146:153], v[230:245], v194, v193 op_sel_hi:[0,0,0]
	v_exp_f32_e32 v0, v118
	v_exp_f32_e32 v177, v119
	v_exp_f32_e32 v179, v120
	v_exp_f32_e32 v254, v121
	v_add_f32_e32 v219, v0, v219
	v_add_f32_e32 v219, v177, v219
	v_cvt_pk_fp8_f32 v247, v0, v177
	v_add_f32_e32 v219, v179, v219
	v_add_f32_e32 v219, v254, v219
	v_cvt_pk_fp8_f32 v247, v179, v254 op_sel:[0,0,1]
	ds_read_b128 v[114:117], v213 offset:16384
	ds_read_b128 v[118:121], v214 offset:16384
	s_waitcnt lgkmcnt(2)
	v_mfma_scale_f32_32x32x64_f8f6f4 v[66:81], v[222:229], v[146:153], v[230:245], v194, v193 op_sel_hi:[0,0,0]
	ds_read_b128 v[222:225], v213 offset:20480
	ds_read_b128 v[226:229], v214 offset:20480
	v_exp_f32_e32 v0, v122
	v_exp_f32_e32 v177, v123
	v_exp_f32_e32 v179, v124
	v_exp_f32_e32 v254, v125
	v_add_f32_e32 v219, v0, v219
	v_add_f32_e32 v219, v177, v219
	v_cvt_pk_fp8_f32 v248, v0, v177
	v_add_f32_e32 v219, v179, v219
	v_add_f32_e32 v219, v254, v219
	v_cvt_pk_fp8_f32 v248, v179, v254 op_sel:[0,0,1]
	v_exp_f32_e32 v0, v126
	v_exp_f32_e32 v177, v127
	v_exp_f32_e32 v179, v128
	v_exp_f32_e32 v254, v129
	v_add_f32_e32 v219, v0, v219
	v_add_f32_e32 v219, v177, v219
	v_cvt_pk_fp8_f32 v249, v0, v177
	v_add_f32_e32 v219, v179, v219
	v_add_f32_e32 v219, v254, v219
	v_cvt_pk_fp8_f32 v249, v179, v254 op_sel:[0,0,1]
	ds_read_b128 v[122:125], v185 offset:32768
	ds_read_b128 v[126:129], v186 offset:32768
	s_waitcnt lgkmcnt(4)
	v_mfma_scale_f32_32x32x64_f8f6f4 v[82:97], v[114:121], v[138:145], v[82:97], v194, v193 op_sel_hi:[0,0,0]
	v_exp_f32_e32 v0, v98
	v_exp_f32_e32 v177, v99
	v_exp_f32_e32 v179, v100
	v_exp_f32_e32 v254, v101
	v_add_f32_e32 v219, v0, v219
	v_add_f32_e32 v219, v177, v219
	v_cvt_pk_fp8_f32 v250, v0, v177
	v_add_f32_e32 v219, v179, v219
	v_add_f32_e32 v219, v254, v219
	v_cvt_pk_fp8_f32 v250, v179, v254 op_sel:[0,0,1]
	s_waitcnt lgkmcnt(2)
	v_mfma_scale_f32_32x32x64_f8f6f4 v[66:81], v[222:229], v[138:145], v[66:81], v194, v193 op_sel_hi:[0,0,0]
	ds_read_b128 v[222:225], v185 offset:34816
	ds_read_b128 v[226:229], v186 offset:34816
	v_exp_f32_e32 v0, v102
	v_exp_f32_e32 v177, v103
	v_exp_f32_e32 v179, v104
	v_exp_f32_e32 v254, v105
	v_add_f32_e32 v219, v0, v219
	v_add_f32_e32 v219, v177, v219
	v_cvt_pk_fp8_f32 v251, v0, v177
	v_add_f32_e32 v219, v179, v219
	v_add_f32_e32 v219, v254, v219
	v_cvt_pk_fp8_f32 v251, v179, v254 op_sel:[0,0,1]
	v_exp_f32_e32 v0, v106
	v_exp_f32_e32 v177, v107
	v_exp_f32_e32 v179, v108
	v_exp_f32_e32 v254, v109
	v_add_f32_e32 v219, v0, v219
	v_add_f32_e32 v219, v177, v219
	v_cvt_pk_fp8_f32 v252, v0, v177
	v_add_f32_e32 v219, v179, v219
	v_add_f32_e32 v219, v254, v219
	v_cvt_pk_fp8_f32 v252, v179, v254 op_sel:[0,0,1]
	s_waitcnt lgkmcnt(2)
	v_mfma_scale_f32_32x32x64_f8f6f4 v[82:97], v[122:129], v[130:137], v[82:97], v194, v193 op_sel_hi:[0,0,0]
	v_exp_f32_e32 v0, v110
	v_exp_f32_e32 v177, v111
	v_exp_f32_e32 v179, v112
	v_exp_f32_e32 v254, v113
	v_add_f32_e32 v219, v0, v219
	v_add_f32_e32 v219, v177, v219
	v_cvt_pk_fp8_f32 v253, v0, v177
	v_add_f32_e32 v219, v179, v219
	v_add_f32_e32 v219, v254, v219
	v_cvt_pk_fp8_f32 v253, v179, v254 op_sel:[0,0,1]
	ds_read_b128 v[122:125], v185 offset:43008
	ds_read_b128 v[126:129], v186 offset:43008
	ds_read_b128 v[114:117], v185 offset:45056
	ds_read_b128 v[118:121], v186 offset:45056
	ds_read_b128 v[106:109], v185 offset:47104
	ds_read_b128 v[110:113], v186 offset:47104
	ds_read_b128 v[98:101], v185 offset:49152
	ds_read_b128 v[102:105], v186 offset:49152
	s_waitcnt lgkmcnt(8)
	v_mfma_scale_f32_32x32x64_f8f6f4 v[66:81], v[222:229], v[130:137], v[66:81], v194, v193 op_sel_hi:[0,0,0]
	v_mov_b32_e32 v0, v219
	s_nop 1
	v_permlane32_swap_b32_e32 v219, v0
	v_add_f32_e32 v219, v219, v0
	v_add_f32_e32 v209, v209, v219
	v_max_f32_e32 v177, v82, v83
	v_max3_f32 v177, v177, v84, v85
	v_max3_f32 v177, v177, v86, v87
	v_max3_f32 v177, v177, v88, v89
	v_max3_f32 v177, v177, v90, v91
	v_max3_f32 v177, v177, v92, v93
	v_max3_f32 v177, v177, v94, v95
	v_max3_f32 v177, v177, v96, v97
	s_waitcnt lgkmcnt(6)
	v_mfma_scale_f32_32x32x64_f8f6f4 v[50:65], v[246:253], v[122:129], v[50:65], v194, v194 op_sel_hi:[0,0,0]
	s_waitcnt lgkmcnt(4)
	v_mfma_scale_f32_32x32x64_f8f6f4 v[34:49], v[246:253], v[114:121], v[34:49], v194, v194 op_sel_hi:[0,0,0]
	s_waitcnt lgkmcnt(2)
	v_mfma_scale_f32_32x32x64_f8f6f4 v[18:33], v[246:253], v[106:113], v[18:33], v194, v194 op_sel_hi:[0,0,0]
	s_waitcnt lgkmcnt(0)
	v_mfma_scale_f32_32x32x64_f8f6f4 v[2:17], v[246:253], v[98:105], v[2:17], v194, v194 op_sel_hi:[0,0,0]
	s_waitcnt vmcnt(0)
	ds_write_b128 v210, v[158:161] offset:8192
	ds_write_b128 v211, v[162:165] offset:24576
	ds_write_b128 v212, v[154:157] offset:36864
	v_max_f32_e32 v0, v66, v67
	v_max3_f32 v0, v0, v68, v69
	v_max3_f32 v0, v0, v70, v71
	v_max3_f32 v0, v0, v72, v73
	v_max3_f32 v0, v0, v74, v75
	v_max3_f32 v0, v0, v76, v77
	v_max3_f32 v0, v0, v78, v79
	v_max3_f32 v0, v0, v80, v81
	v_max_f32_e32 v177, v177, v0
	v_mov_b32_e32 v0, v177
	s_nop 1
	v_permlane32_swap_b32_e32 v177, v0
	v_max_f32_e32 v177, v177, v0
	v_cmp_ge_f32_e32 vcc, s90, v177
	s_cmp_eq_u64 vcc, exec
	s_cbranch_scc0 .Lmla_h5_newmax
; __device__ __forceinline__ void finishSM9(f32x16& p0, f32x16& p1, float alpha, float& l_reg, v8i32& p8) {
; #pragma unroll
;   for (int r = 0; r < 16; ++r) { p0[r] = __builtin_amdgcn_exp2f(p0[r]); p1[r] = __builtin_amdgcn_exp2f(p1[r]); }
;   float ps = 0;
; #pragma unroll
;   for (int r = 0; r < 16; ++r) ps += p0[r];
; #pragma unroll
;   for (int r = 0; r < 16; ++r) ps += p1[r];
;   { auto rr = __builtin_amdgcn_permlane32_swap(__float_as_uint(ps), __float_as_uint(ps), false, false);
;     ps = __uint_as_float(rr[0]) + __uint_as_float(rr[1]); }
;   l_reg = l_reg * alpha + ps;
; #pragma unroll
;   for (int g = 0; g < 4; ++g) {
;     int w = __builtin_amdgcn_cvt_pk_fp8_f32(p0[4 * g], p0[4 * g + 1], 0, false); p8[g] = __builtin_amdgcn_cvt_pk_fp8_f32(p0[4 * g + 2], p0[4 * g + 3], w, true);
;     int u = __builtin_amdgcn_cvt_pk_fp8_f32(p1[4 * g], p1[4 * g + 1], 0, false); p8[4 + g] = __builtin_amdgcn_cvt_pk_fp8_f32(p1[4 * g + 2], p1[4 * g + 3], u, true); }
; }
; __device__ __forceinline__ void pv8(f32x16* o, const char* Vt, const v8i32 p8, int r32, int hi) {
;   const int sw = (r32 >> 2) & 3, a0 = r32 * 64 + (((hi * 2) ^ sw) << 4), a1 = r32 * 64 + (((hi * 2 + 1) ^ sw) << 4);
; #pragma unroll
;   for (int d0 = 0; d0 < 4; ++d0) {
;     const v8i32 vf = cat8(*reinterpret_cast<const v4i32*>(Vt + d0 * 2048 + a0), *reinterpret_cast<const v4i32*>(Vt + d0 * 2048 + a1));
;     o[d0] = __builtin_amdgcn_mfma_scale_f32_32x32x64_f8f6f4(p8, vf, o[d0], 0, 0, 0, 127, 0, 127); }
; }
; __device__ __forceinline__ void qkt9(f32x16& p0, f32x16& p1, const char* Kn, const char* Kr, const v8i32* qf, const float init, int r32, int hi) {
; #pragma unroll
;   for (int r = 0; r < 16; ++r) { p0[r] = init; p1[r] = init; }
; #pragma unroll
;   for (int s = 0; s < 2; ++s) { const int c0 = s * 4 + hi * 2;
;     const v8i32 a0 = cat8(*reinterpret_cast<const v4i32*>(Kn + KN8SW(r32, c0)), *reinterpret_cast<const v4i32*>(Kn + KN8SW(r32, c0 + 1)));
;     const v8i32 a1 = cat8(*reinterpret_cast<const v4i32*>(Kn + 4096 + KN8SW(r32, c0)), *reinterpret_cast<const v4i32*>(Kn + 4096 + KN8SW(r32, c0 + 1)));
;     p0 = __builtin_amdgcn_mfma_scale_f32_32x32x64_f8f6f4(a0, qf[s], p0, 0, 0, 0, 127, 0, 124);
;     p1 = __builtin_amdgcn_mfma_scale_f32_32x32x64_f8f6f4(a1, qf[s], p1, 0, 0, 0, 127, 0, 124); }
;   { const int c0 = hi * 2;
.Lmla_h5_cont:
	s_waitcnt lgkmcnt(0)
	s_barrier
	s_add_i32 s30, s30, 1
	s_cmpk_lt_u32 s30, 42
	s_cbranch_scc1 .LBB0_1321
	global_load_dwordx4 v[158:161], v176, s[18:19]
	global_load_dwordx4 v[162:165], v178, s[16:17]
	global_load_dwordx4 v[154:157], v[180:181], off
	ds_read_b128 v[114:117], v215 offset:24576
	ds_read_b128 v[118:121], v216 offset:24576
	ds_read_b128 v[222:225], v215 offset:28672
	ds_read_b128 v[226:229], v216 offset:28672
	v_add_u32_e32 v176, 0x2000, v176
	v_add_u32_e32 v178, 0x20000, v178
	s_mov_b64 s[20:21], 0x1000
	v_lshl_add_u64 v[180:181], v[180:181], 0, s[20:21]
	v_exp_f32_e32 v0, v82
	v_exp_f32_e32 v177, v83
	v_exp_f32_e32 v179, v84
	v_exp_f32_e32 v254, v85
	v_add_f32_e32 v219, v0, v177
	v_cvt_pk_fp8_f32 v246, v0, v177
	v_add_f32_e32 v219, v179, v219
	v_add_f32_e32 v219, v254, v219
	v_cvt_pk_fp8_f32 v246, v179, v254 op_sel:[0,0,1]
	s_waitcnt lgkmcnt(2)
	v_mfma_scale_f32_32x32x64_f8f6f4 v[114:129], v[114:121], v[146:153], v[230:245], v194, v193 op_sel_hi:[0,0,0]
	v_exp_f32_e32 v0, v86
	v_exp_f32_e32 v177, v87
	v_exp_f32_e32 v179, v88
	v_exp_f32_e32 v254, v89
	v_add_f32_e32 v219, v0, v219
	v_add_f32_e32 v219, v177, v219
	v_cvt_pk_fp8_f32 v247, v0, v177
	v_add_f32_e32 v219, v179, v219
	v_add_f32_e32 v219, v254, v219
	v_cvt_pk_fp8_f32 v247, v179, v254 op_sel:[0,0,1]
	ds_read_b128 v[82:85], v213 offset:24576
	ds_read_b128 v[86:89], v214 offset:24576
	s_waitcnt lgkmcnt(2)
	v_mfma_scale_f32_32x32x64_f8f6f4 v[98:113], v[222:229], v[146:153], v[230:245], v194, v193 op_sel_hi:[0,0,0]
	ds_read_b128 v[222:225], v213 offset:28672
	ds_read_b128 v[226:229], v214 offset:28672
	v_exp_f32_e32 v0, v90
	v_exp_f32_e32 v177, v91
	v_exp_f32_e32 v179, v92
	v_exp_f32_e32 v254, v93
	v_add_f32_e32 v219, v0, v219
	v_add_f32_e32 v219, v177, v219
	v_cvt_pk_fp8_f32 v248, v0, v177
	v_add_f32_e32 v219, v179, v219
	v_add_f32_e32 v219, v254, v219
	v_cvt_pk_fp8_f32 v248, v179, v254 op_sel:[0,0,1]
	v_exp_f32_e32 v0, v94
	v_exp_f32_e32 v177, v95
	v_exp_f32_e32 v179, v96
	v_exp_f32_e32 v254, v97
	v_add_f32_e32 v219, v0, v219
	v_add_f32_e32 v219, v177, v219
	v_cvt_pk_fp8_f32 v249, v0, v177
	v_add_f32_e32 v219, v179, v219
	v_add_f32_e32 v219, v254, v219
	v_cvt_pk_fp8_f32 v249, v179, v254 op_sel:[0,0,1]
	ds_read_b128 v[90:93], v185 offset:36864
	ds_read_b128 v[94:97], v186 offset:36864
	s_waitcnt lgkmcnt(4)
	v_mfma_scale_f32_32x32x64_f8f6f4 v[114:129], v[82:89], v[138:145], v[114:129], v194, v193 op_sel_hi:[0,0,0]
	v_exp_f32_e32 v0, v66
	v_exp_f32_e32 v177, v67
	v_exp_f32_e32 v179, v68
	v_exp_f32_e32 v254, v69
	v_add_f32_e32 v219, v0, v219
	v_add_f32_e32 v219, v177, v219
	v_cvt_pk_fp8_f32 v250, v0, v177
	v_add_f32_e32 v219, v179, v219
	v_add_f32_e32 v219, v254, v219
	v_cvt_pk_fp8_f32 v250, v179, v254 op_sel:[0,0,1]
	s_waitcnt lgkmcnt(2)
	v_mfma_scale_f32_32x32x64_f8f6f4 v[98:113], v[222:229], v[138:145], v[98:113], v194, v193 op_sel_hi:[0,0,0]
	ds_read_b128 v[222:225], v185 offset:38912
	ds_read_b128 v[226:229], v186 offset:38912
	v_exp_f32_e32 v0, v70
	v_exp_f32_e32 v177, v71
	v_exp_f32_e32 v179, v72
	v_exp_f32_e32 v254, v73
	v_add_f32_e32 v219, v0, v219
	v_add_f32_e32 v219, v177, v219
	v_cvt_pk_fp8_f32 v251, v0, v177
	v_add_f32_e32 v219, v179, v219
	v_add_f32_e32 v219, v254, v219
	v_cvt_pk_fp8_f32 v251, v179, v254 op_sel:[0,0,1]
	v_exp_f32_e32 v0, v74
	v_exp_f32_e32 v177, v75
	v_exp_f32_e32 v179, v76
	v_exp_f32_e32 v254, v77
	v_add_f32_e32 v219, v0, v219
	v_add_f32_e32 v219, v177, v219
	v_cvt_pk_fp8_f32 v252, v0, v177
	v_add_f32_e32 v219, v179, v219
	v_add_f32_e32 v219, v254, v219
	v_cvt_pk_fp8_f32 v252, v179, v254 op_sel:[0,0,1]
	s_waitcnt lgkmcnt(2)
	v_mfma_scale_f32_32x32x64_f8f6f4 v[114:129], v[90:97], v[130:137], v[114:129], v194, v193 op_sel_hi:[0,0,0]
	v_exp_f32_e32 v0, v78
	v_exp_f32_e32 v177, v79
	v_exp_f32_e32 v179, v80
	v_exp_f32_e32 v254, v81
	v_add_f32_e32 v219, v0, v219
	v_add_f32_e32 v219, v177, v219
	v_cvt_pk_fp8_f32 v253, v0, v177
	v_add_f32_e32 v219, v179, v219
	v_add_f32_e32 v219, v254, v219
	v_cvt_pk_fp8_f32 v253, v179, v254 op_sel:[0,0,1]
	ds_read_b128 v[90:93], v185 offset:0
	ds_read_b128 v[94:97], v186 offset:0
	ds_read_b128 v[82:85], v185 offset:2048
	ds_read_b128 v[86:89], v186 offset:2048
	ds_read_b128 v[74:77], v185 offset:4096
	ds_read_b128 v[78:81], v186 offset:4096
	ds_read_b128 v[66:69], v185 offset:6144
	ds_read_b128 v[70:73], v186 offset:6144
	s_waitcnt lgkmcnt(8)
	v_mfma_scale_f32_32x32x64_f8f6f4 v[98:113], v[222:229], v[130:137], v[98:113], v194, v193 op_sel_hi:[0,0,0]
	v_mov_b32_e32 v0, v219
	s_nop 1
	v_permlane32_swap_b32_e32 v219, v0
	v_add_f32_e32 v219, v219, v0
	v_add_f32_e32 v209, v209, v219
	v_max_f32_e32 v177, v114, v115
	v_max3_f32 v177, v177, v116, v117
	v_max3_f32 v177, v177, v118, v119
	v_max3_f32 v177, v177, v120, v121
	v_max3_f32 v177, v177, v122, v123
	v_max3_f32 v177, v177, v124, v125
	v_max3_f32 v177, v177, v126, v127
	v_max3_f32 v177, v177, v128, v129
	s_waitcnt lgkmcnt(6)
	v_mfma_scale_f32_32x32x64_f8f6f4 v[50:65], v[246:253], v[90:97], v[50:65], v194, v194 op_sel_hi:[0,0,0]
	s_waitcnt lgkmcnt(4)
	v_mfma_scale_f32_32x32x64_f8f6f4 v[34:49], v[246:253], v[82:89], v[34:49], v194, v194 op_sel_hi:[0,0,0]
	s_waitcnt lgkmcnt(2)
	v_mfma_scale_f32_32x32x64_f8f6f4 v[18:33], v[246:253], v[74:81], v[18:33], v194, v194 op_sel_hi:[0,0,0]
	s_waitcnt lgkmcnt(0)
	v_mfma_scale_f32_32x32x64_f8f6f4 v[2:17], v[246:253], v[66:73], v[2:17], v194, v194 op_sel_hi:[0,0,0]
	s_waitcnt vmcnt(0)
	ds_write_b128 v210, v[158:161] offset:43008
	ds_write_b128 v211, v[162:165] offset:51200
	ds_write_b128 v212, v[154:157] offset:59392
	v_max_f32_e32 v0, v98, v99
	v_max3_f32 v0, v0, v100, v101
	v_max3_f32 v0, v0, v102, v103
	v_max3_f32 v0, v0, v104, v105
	v_max3_f32 v0, v0, v106, v107
	v_max3_f32 v0, v0, v108, v109
	v_max3_f32 v0, v0, v110, v111
	v_max3_f32 v0, v0, v112, v113
	v_max_f32_e32 v177, v177, v0
	v_mov_b32_e32 v0, v177
	s_nop 1
	v_permlane32_swap_b32_e32 v177, v0
	v_max_f32_e32 v177, v177, v0
	v_cmp_ge_f32_e32 vcc, s90, v177
	s_cmp_eq_u64 vcc, exec
	s_cbranch_scc0 .Lmla_p0_newmax

; #define RESC(a) do { if (__any((a) < 1.f)) { if (hi == 0) al_l[r32] = (a); asm volatile("s_waitcnt lgkmcnt(0)" ::: "memory"); \
;     _Pragma("unroll") for (int d = 0; d < 4; ++d) _Pragma("unroll") for (int r = 0; r < 16; ++r) o[d][r] *= al_l[crow(r, hi)]; } } while (0)
; #define RESC(a) do { if (__any((a) < 1.f)) { if (hi == 0) al_l[r32] = (a); asm volatile("s_waitcnt lgkmcnt(0)" ::: "memory"); \
;     _Pragma("unroll") for (int d = 0; d < 4; ++d) _Pragma("unroll") for (int r = 0; r < 16; ++r) o[d][r] *= al_l[crow(r, hi)]; } } while (0)
; #define RESC(a) do { if (__any((a) < 1.f)) { if (hi == 0) al_l[r32] = (a); asm volatile("s_waitcnt lgkmcnt(0)" ::: "memory"); \
;     _Pragma("unroll") for (int d = 0; d < 4; ++d) _Pragma("unroll") for (int r = 0; r < 16; ++r) o[d][r] *= al_l[crow(r, hi)]; } } while (0)
; __device__ __forceinline__ void attn_unit7(const unsigned char* __restrict__ Q8, int ldq, const unsigned char* __restrict__ Kn8, int ldk, const unsigned char* __restrict__ Kr8, ...
;     ...
;   qkt9(pB0, pB1, Kn_lds + 8192, Kr_lds + 4096, qf, 7.0f - m_reg, r32, hi);
;   finishSM9(pA0, pA1, alA, l_reg, p8);
;   pv8(o, Vt_lds, p8, r32, hi); partialSM9(pB0, pB1, m_reg, alB, thr_raw);
;   RESC(alB);
;   finishSM9(pB0, pB1, alB, l_reg, p8);
;   pv8(o, Vt_lds + 8192, p8, r32, hi);
;   if (hi == 0) li_l[r32] = l_reg; asm volatile("s_waitcnt lgkmcnt(0)" ::: "memory");
.Lmla_p1_cont:
	v_mov_b32_e32 v0, 1.0
	s_waitcnt lgkmcnt(0)
	s_barrier
	s_branch .LBB0_1343

; __device__ __forceinline__ void finishSM9(f32x16& p0, f32x16& p1, float alpha, float& l_reg, v8i32& p8) {
; #pragma unroll
;   for (int r = 0; r < 16; ++r) { p0[r] = __builtin_amdgcn_exp2f(p0[r]); p1[r] = __builtin_amdgcn_exp2f(p1[r]); }
;   float ps = 0;
; #pragma unroll
;   for (int r = 0; r < 16; ++r) ps += p0[r];
; #pragma unroll
;   for (int r = 0; r < 16; ++r) ps += p1[r];
;   { auto rr = __builtin_amdgcn_permlane32_swap(__float_as_uint(ps), __float_as_uint(ps), false, false);
;     ps = __uint_as_float(rr[0]) + __uint_as_float(rr[1]); }
;   l_reg = l_reg * alpha + ps;
; #pragma unroll
;   for (int g = 0; g < 4; ++g) {
;     int w = __builtin_amdgcn_cvt_pk_fp8_f32(p0[4 * g], p0[4 * g + 1], 0, false); p8[g] = __builtin_amdgcn_cvt_pk_fp8_f32(p0[4 * g + 2], p0[4 * g + 3], w, true);
;     int u = __builtin_amdgcn_cvt_pk_fp8_f32(p1[4 * g], p1[4 * g + 1], 0, false); p8[4 + g] = __builtin_amdgcn_cvt_pk_fp8_f32(p1[4 * g + 2], p1[4 * g + 3], u, true); }
; }
; __device__ __forceinline__ void pv8(f32x16* o, const char* Vt, const v8i32 p8, int r32, int hi) {
;   const int sw = (r32 >> 2) & 3, a0 = r32 * 64 + (((hi * 2) ^ sw) << 4), a1 = r32 * 64 + (((hi * 2 + 1) ^ sw) << 4);
; #pragma unroll
;   for (int d0 = 0; d0 < 4; ++d0) {
;     const v8i32 vf = cat8(*reinterpret_cast<const v4i32*>(Vt + d0 * 2048 + a0), *reinterpret_cast<const v4i32*>(Vt + d0 * 2048 + a1));
;     o[d0] = __builtin_amdgcn_mfma_scale_f32_32x32x64_f8f6f4(p8, vf, o[d0], 0, 0, 0, 127, 0, 127); }
; }
; __device__ __forceinline__ void qkt9(f32x16& p0, f32x16& p1, const char* Kn, const char* Kr, const v8i32* qf, const float init, int r32, int hi) {
; #pragma unroll
;   for (int r = 0; r < 16; ++r) { p0[r] = init; p1[r] = init; }
; #pragma unroll
;   for (int s = 0; s < 2; ++s) { const int c0 = s * 4 + hi * 2;
;     const v8i32 a0 = cat8(*reinterpret_cast<const v4i32*>(Kn + KN8SW(r32, c0)), *reinterpret_cast<const v4i32*>(Kn + KN8SW(r32, c0 + 1)));
;     const v8i32 a1 = cat8(*reinterpret_cast<const v4i32*>(Kn + 4096 + KN8SW(r32, c0)), *reinterpret_cast<const v4i32*>(Kn + 4096 + KN8SW(r32, c0 + 1)));
;     p0 = __builtin_amdgcn_mfma_scale_f32_32x32x64_f8f6f4(a0, qf[s], p0, 0, 0, 0, 127, 0, 124);
;     p1 = __builtin_amdgcn_mfma_scale_f32_32x32x64_f8f6f4(a1, qf[s], p1, 0, 0, 0, 127, 0, 124); }
;   { const int c0 = hi * 2;
.Lmla_stag_loop:
	ds_read_b128 v[114:117], v215 offset:24576
	ds_read_b128 v[118:121], v216 offset:24576
	ds_read_b128 v[222:225], v215 offset:28672
	ds_read_b128 v[226:229], v216 offset:28672
	v_exp_f32_e32 v0, v82
	v_exp_f32_e32 v177, v83
	v_exp_f32_e32 v179, v84
	v_exp_f32_e32 v254, v85
	v_add_f32_e32 v219, v0, v177
	v_cvt_pk_fp8_f32 v246, v0, v177
	v_add_f32_e32 v219, v179, v219
	v_add_f32_e32 v219, v254, v219
	v_cvt_pk_fp8_f32 v246, v179, v254 op_sel:[0,0,1]
	s_waitcnt lgkmcnt(2)
	v_mfma_scale_f32_32x32x64_f8f6f4 v[114:129], v[114:121], v[146:153], v[230:245], v194, v193 op_sel_hi:[0,0,0]
	v_exp_f32_e32 v0, v86
	v_exp_f32_e32 v177, v87
	v_exp_f32_e32 v179, v88
	v_exp_f32_e32 v254, v89
	v_add_f32_e32 v219, v0, v219
	v_add_f32_e32 v219, v177, v219
	v_cvt_pk_fp8_f32 v247, v0, v177
	v_add_f32_e32 v219, v179, v219
	v_add_f32_e32 v219, v254, v219
	v_cvt_pk_fp8_f32 v247, v179, v254 op_sel:[0,0,1]
	ds_read_b128 v[82:85], v213 offset:24576
	ds_read_b128 v[86:89], v214 offset:24576
	s_waitcnt lgkmcnt(2)
	v_mfma_scale_f32_32x32x64_f8f6f4 v[98:113], v[222:229], v[146:153], v[230:245], v194, v193 op_sel_hi:[0,0,0]
	ds_read_b128 v[222:225], v213 offset:28672
	ds_read_b128 v[226:229], v214 offset:28672
	v_exp_f32_e32 v0, v90
	v_exp_f32_e32 v177, v91
	v_exp_f32_e32 v179, v92
	v_exp_f32_e32 v254, v93
	v_add_f32_e32 v219, v0, v219
	v_add_f32_e32 v219, v177, v219
	v_cvt_pk_fp8_f32 v248, v0, v177
	v_add_f32_e32 v219, v179, v219
	v_add_f32_e32 v219, v254, v219
	v_cvt_pk_fp8_f32 v248, v179, v254 op_sel:[0,0,1]
	v_exp_f32_e32 v0, v94
	v_exp_f32_e32 v177, v95
	v_exp_f32_e32 v179, v96
	v_exp_f32_e32 v254, v97
	v_add_f32_e32 v219, v0, v219
	v_add_f32_e32 v219, v177, v219
	v_cvt_pk_fp8_f32 v249, v0, v177
	v_add_f32_e32 v219, v179, v219
	v_add_f32_e32 v219, v254, v219
	v_cvt_pk_fp8_f32 v249, v179, v254 op_sel:[0,0,1]
	ds_read_b128 v[90:93], v185 offset:36864
	ds_read_b128 v[94:97], v186 offset:36864
	s_waitcnt lgkmcnt(4)
	v_mfma_scale_f32_32x32x64_f8f6f4 v[114:129], v[82:89], v[138:145], v[114:129], v194, v193 op_sel_hi:[0,0,0]
	v_exp_f32_e32 v0, v66
	v_exp_f32_e32 v177, v67
	v_exp_f32_e32 v179, v68
	v_exp_f32_e32 v254, v69
	v_add_f32_e32 v219, v0, v219
	v_add_f32_e32 v219, v177, v219
	v_cvt_pk_fp8_f32 v250, v0, v177
	v_add_f32_e32 v219, v179, v219
	v_add_f32_e32 v219, v254, v219
	v_cvt_pk_fp8_f32 v250, v179, v254 op_sel:[0,0,1]
	s_waitcnt lgkmcnt(2)
	v_mfma_scale_f32_32x32x64_f8f6f4 v[98:113], v[222:229], v[138:145], v[98:113], v194, v193 op_sel_hi:[0,0,0]
	ds_read_b128 v[222:225], v185 offset:38912
	ds_read_b128 v[226:229], v186 offset:38912
	v_exp_f32_e32 v0, v70
	v_exp_f32_e32 v177, v71
	v_exp_f32_e32 v179, v72
	v_exp_f32_e32 v254, v73
	v_add_f32_e32 v219, v0, v219
	v_add_f32_e32 v219, v177, v219
	v_cvt_pk_fp8_f32 v251, v0, v177
	v_add_f32_e32 v219, v179, v219
	v_add_f32_e32 v219, v254, v219
	v_cvt_pk_fp8_f32 v251, v179, v254 op_sel:[0,0,1]
	v_exp_f32_e32 v0, v74
	v_exp_f32_e32 v177, v75
	v_exp_f32_e32 v179, v76
	v_exp_f32_e32 v254, v77
	v_add_f32_e32 v219, v0, v219
	v_add_f32_e32 v219, v177, v219
	v_cvt_pk_fp8_f32 v252, v0, v177
	v_add_f32_e32 v219, v179, v219
	v_add_f32_e32 v219, v254, v219
	v_cvt_pk_fp8_f32 v252, v179, v254 op_sel:[0,0,1]
	s_waitcnt lgkmcnt(2)
	v_mfma_scale_f32_32x32x64_f8f6f4 v[114:129], v[90:97], v[130:137], v[114:129], v194, v193 op_sel_hi:[0,0,0]
	v_exp_f32_e32 v0, v78
	v_exp_f32_e32 v177, v79
	v_exp_f32_e32 v179, v80
	v_exp_f32_e32 v254, v81
	v_add_f32_e32 v219, v0, v219
	v_add_f32_e32 v219, v177, v219
	v_cvt_pk_fp8_f32 v253, v0, v177
	v_add_f32_e32 v219, v179, v219
	v_add_f32_e32 v219, v254, v219
	v_cvt_pk_fp8_f32 v253, v179, v254 op_sel:[0,0,1]
	ds_read_b128 v[90:93], v185 offset:0
	ds_read_b128 v[94:97], v186 offset:0
	ds_read_b128 v[82:85], v185 offset:2048
	ds_read_b128 v[86:89], v186 offset:2048
	ds_read_b128 v[74:77], v185 offset:4096
	ds_read_b128 v[78:81], v186 offset:4096
	ds_read_b128 v[66:69], v185 offset:6144
	ds_read_b128 v[70:73], v186 offset:6144
	s_waitcnt lgkmcnt(8)
	v_mfma_scale_f32_32x32x64_f8f6f4 v[98:113], v[222:229], v[130:137], v[98:113], v194, v193 op_sel_hi:[0,0,0]
	v_mov_b32_e32 v0, v219
	s_nop 1
	v_permlane32_swap_b32_e32 v219, v0
	v_add_f32_e32 v219, v219, v0
	v_add_f32_e32 v209, v209, v219
	s_waitcnt vmcnt(0)
	ds_write_b128 v210, v[158:161] offset:43008
	ds_write_b128 v211, v[162:165] offset:51200
	s_waitcnt lgkmcnt(0)
	s_barrier
	global_load_dwordx4 v[158:161], v176, s[18:19]
	global_load_dwordx4 v[162:165], v178, s[16:17]
	v_add_u32_e32 v176, 0x2000, v176
	v_add_u32_e32 v178, 0x20000, v178
	v_max_f32_e32 v177, v114, v115
	v_max3_f32 v177, v177, v116, v117
	v_max3_f32 v177, v177, v118, v119
	v_max3_f32 v177, v177, v120, v121
	v_max3_f32 v177, v177, v122, v123
	v_max3_f32 v177, v177, v124, v125
	v_max3_f32 v177, v177, v126, v127
	v_max3_f32 v177, v177, v128, v129
	s_waitcnt lgkmcnt(6)
	v_mfma_scale_f32_32x32x64_f8f6f4 v[50:65], v[246:253], v[90:97], v[50:65], v194, v194 op_sel_hi:[0,0,0]
	s_waitcnt lgkmcnt(4)
	v_mfma_scale_f32_32x32x64_f8f6f4 v[34:49], v[246:253], v[82:89], v[34:49], v194, v194 op_sel_hi:[0,0,0]
	s_waitcnt lgkmcnt(2)
	v_mfma_scale_f32_32x32x64_f8f6f4 v[18:33], v[246:253], v[74:81], v[18:33], v194, v194 op_sel_hi:[0,0,0]
	s_waitcnt lgkmcnt(0)
	v_mfma_scale_f32_32x32x64_f8f6f4 v[2:17], v[246:253], v[66:73], v[2:17], v194, v194 op_sel_hi:[0,0,0]
	v_max_f32_e32 v0, v98, v99
	v_max3_f32 v0, v0, v100, v101
	v_max3_f32 v0, v0, v102, v103
	v_max3_f32 v0, v0, v104, v105
	v_max3_f32 v0, v0, v106, v107
	v_max3_f32 v0, v0, v108, v109
	v_max3_f32 v0, v0, v110, v111
	v_max3_f32 v0, v0, v112, v113
	v_max_f32_e32 v177, v177, v0
	v_mov_b32_e32 v0, v177
	s_nop 1
	v_permlane32_swap_b32_e32 v177, v0
	v_max_f32_e32 v177, v177, v0
	v_cmp_ge_f32_e32 vcc, s90, v177
	s_cmp_eq_u64 vcc, exec
	s_cbranch_scc0 .Lmla_s0_newmax
; __device__ __forceinline__ void finishSM9(f32x16& p0, f32x16& p1, float alpha, float& l_reg, v8i32& p8) {
; #pragma unroll
;   for (int r = 0; r < 16; ++r) { p0[r] = __builtin_amdgcn_exp2f(p0[r]); p1[r] = __builtin_amdgcn_exp2f(p1[r]); }
;   float ps = 0;
; #pragma unroll
;   for (int r = 0; r < 16; ++r) ps += p0[r];
; #pragma unroll
;   for (int r = 0; r < 16; ++r) ps += p1[r];
;   { auto rr = __builtin_amdgcn_permlane32_swap(__float_as_uint(ps), __float_as_uint(ps), false, false);
;     ps = __uint_as_float(rr[0]) + __uint_as_float(rr[1]); }
;   l_reg = l_reg * alpha + ps;
; #pragma unroll
;   for (int g = 0; g < 4; ++g) {
;     int w = __builtin_amdgcn_cvt_pk_fp8_f32(p0[4 * g], p0[4 * g + 1], 0, false); p8[g] = __builtin_amdgcn_cvt_pk_fp8_f32(p0[4 * g + 2], p0[4 * g + 3], w, true);
;     int u = __builtin_amdgcn_cvt_pk_fp8_f32(p1[4 * g], p1[4 * g + 1], 0, false); p8[4 + g] = __builtin_amdgcn_cvt_pk_fp8_f32(p1[4 * g + 2], p1[4 * g + 3], u, true); }
; }
; __device__ __forceinline__ void pv8(f32x16* o, const char* Vt, const v8i32 p8, int r32, int hi) {
;   const int sw = (r32 >> 2) & 3, a0 = r32 * 64 + (((hi * 2) ^ sw) << 4), a1 = r32 * 64 + (((hi * 2 + 1) ^ sw) << 4);
; #pragma unroll
;   for (int d0 = 0; d0 < 4; ++d0) {
;     const v8i32 vf = cat8(*reinterpret_cast<const v4i32*>(Vt + d0 * 2048 + a0), *reinterpret_cast<const v4i32*>(Vt + d0 * 2048 + a1));
;     o[d0] = __builtin_amdgcn_mfma_scale_f32_32x32x64_f8f6f4(p8, vf, o[d0], 0, 0, 0, 127, 0, 127); }
; }
; __device__ __forceinline__ void qkt9(f32x16& p0, f32x16& p1, const char* Kn, const char* Kr, const v8i32* qf, const float init, int r32, int hi) {
; #pragma unroll
;   for (int r = 0; r < 16; ++r) { p0[r] = init; p1[r] = init; }
; #pragma unroll
;   for (int s = 0; s < 2; ++s) { const int c0 = s * 4 + hi * 2;
;     const v8i32 a0 = cat8(*reinterpret_cast<const v4i32*>(Kn + KN8SW(r32, c0)), *reinterpret_cast<const v4i32*>(Kn + KN8SW(r32, c0 + 1)));
;     const v8i32 a1 = cat8(*reinterpret_cast<const v4i32*>(Kn + 4096 + KN8SW(r32, c0)), *reinterpret_cast<const v4i32*>(Kn + 4096 + KN8SW(r32, c0 + 1)));
;     p0 = __builtin_amdgcn_mfma_scale_f32_32x32x64_f8f6f4(a0, qf[s], p0, 0, 0, 0, 127, 0, 124);
;     p1 = __builtin_amdgcn_mfma_scale_f32_32x32x64_f8f6f4(a1, qf[s], p1, 0, 0, 0, 127, 0, 124); }
;   { const int c0 = hi * 2;
.Lmla_s0_cont:
	ds_read_b128 v[82:85], v215 offset:51200
	ds_read_b128 v[86:89], v216 offset:51200
	ds_read_b128 v[222:225], v215 offset:55296
	ds_read_b128 v[226:229], v216 offset:55296
	v_exp_f32_e32 v0, v114
	v_exp_f32_e32 v177, v115
	v_exp_f32_e32 v179, v116
	v_exp_f32_e32 v254, v117
	v_add_f32_e32 v219, v0, v177
	v_cvt_pk_fp8_f32 v246, v0, v177
	v_add_f32_e32 v219, v179, v219
	v_add_f32_e32 v219, v254, v219
	v_cvt_pk_fp8_f32 v246, v179, v254 op_sel:[0,0,1]
	s_waitcnt lgkmcnt(2)
	v_mfma_scale_f32_32x32x64_f8f6f4 v[82:97], v[82:89], v[146:153], v[230:245], v194, v193 op_sel_hi:[0,0,0]
	v_exp_f32_e32 v0, v118
	v_exp_f32_e32 v177, v119
	v_exp_f32_e32 v179, v120
	v_exp_f32_e32 v254, v121
	v_add_f32_e32 v219, v0, v219
	v_add_f32_e32 v219, v177, v219
	v_cvt_pk_fp8_f32 v247, v0, v177
	v_add_f32_e32 v219, v179, v219
	v_add_f32_e32 v219, v254, v219
	v_cvt_pk_fp8_f32 v247, v179, v254 op_sel:[0,0,1]
	ds_read_b128 v[114:117], v213 offset:51200
	ds_read_b128 v[118:121], v214 offset:51200
	s_waitcnt lgkmcnt(2)
	v_mfma_scale_f32_32x32x64_f8f6f4 v[66:81], v[222:229], v[146:153], v[230:245], v194, v193 op_sel_hi:[0,0,0]
	ds_read_b128 v[222:225], v213 offset:55296
	ds_read_b128 v[226:229], v214 offset:55296
	v_exp_f32_e32 v0, v122
	v_exp_f32_e32 v177, v123
	v_exp_f32_e32 v179, v124
	v_exp_f32_e32 v254, v125
	v_add_f32_e32 v219, v0, v219
	v_add_f32_e32 v219, v177, v219
	v_cvt_pk_fp8_f32 v248, v0, v177
	v_add_f32_e32 v219, v179, v219
	v_add_f32_e32 v219, v254, v219
	v_cvt_pk_fp8_f32 v248, v179, v254 op_sel:[0,0,1]
	v_exp_f32_e32 v0, v126
	v_exp_f32_e32 v177, v127
	v_exp_f32_e32 v179, v128
	v_exp_f32_e32 v254, v129
	v_add_f32_e32 v219, v0, v219
	v_add_f32_e32 v219, v177, v219
	v_cvt_pk_fp8_f32 v249, v0, v177
	v_add_f32_e32 v219, v179, v219
	v_add_f32_e32 v219, v254, v219
	v_cvt_pk_fp8_f32 v249, v179, v254 op_sel:[0,0,1]
	ds_read_b128 v[122:125], v185 offset:59392
	ds_read_b128 v[126:129], v186 offset:59392
	s_waitcnt lgkmcnt(4)
	v_mfma_scale_f32_32x32x64_f8f6f4 v[82:97], v[114:121], v[138:145], v[82:97], v194, v193 op_sel_hi:[0,0,0]
	v_exp_f32_e32 v0, v98
	v_exp_f32_e32 v177, v99
	v_exp_f32_e32 v179, v100
	v_exp_f32_e32 v254, v101
	v_add_f32_e32 v219, v0, v219
	v_add_f32_e32 v219, v177, v219
	v_cvt_pk_fp8_f32 v250, v0, v177
	v_add_f32_e32 v219, v179, v219
	v_add_f32_e32 v219, v254, v219
	v_cvt_pk_fp8_f32 v250, v179, v254 op_sel:[0,0,1]
	s_waitcnt lgkmcnt(2)
	v_mfma_scale_f32_32x32x64_f8f6f4 v[66:81], v[222:229], v[138:145], v[66:81], v194, v193 op_sel_hi:[0,0,0]
	ds_read_b128 v[222:225], v185 offset:61440
	ds_read_b128 v[226:229], v186 offset:61440
	v_exp_f32_e32 v0, v102
	v_exp_f32_e32 v177, v103
	v_exp_f32_e32 v179, v104
	v_exp_f32_e32 v254, v105
	v_add_f32_e32 v219, v0, v219
	v_add_f32_e32 v219, v177, v219
	v_cvt_pk_fp8_f32 v251, v0, v177
	v_add_f32_e32 v219, v179, v219
	v_add_f32_e32 v219, v254, v219
	v_cvt_pk_fp8_f32 v251, v179, v254 op_sel:[0,0,1]
	v_exp_f32_e32 v0, v106
	v_exp_f32_e32 v177, v107
	v_exp_f32_e32 v179, v108
	v_exp_f32_e32 v254, v109
	v_add_f32_e32 v219, v0, v219
	v_add_f32_e32 v219, v177, v219
	v_cvt_pk_fp8_f32 v252, v0, v177
	v_add_f32_e32 v219, v179, v219
	v_add_f32_e32 v219, v254, v219
	v_cvt_pk_fp8_f32 v252, v179, v254 op_sel:[0,0,1]
	s_waitcnt lgkmcnt(2)
	v_mfma_scale_f32_32x32x64_f8f6f4 v[82:97], v[122:129], v[130:137], v[82:97], v194, v193 op_sel_hi:[0,0,0]
	v_exp_f32_e32 v0, v110
	v_exp_f32_e32 v177, v111
	v_exp_f32_e32 v179, v112
	v_exp_f32_e32 v254, v113
	v_add_f32_e32 v219, v0, v219
	v_add_f32_e32 v219, v177, v219
	v_cvt_pk_fp8_f32 v253, v0, v177
	v_add_f32_e32 v219, v179, v219
	v_add_f32_e32 v219, v254, v219
	v_cvt_pk_fp8_f32 v253, v179, v254 op_sel:[0,0,1]
	ds_read_b128 v[122:125], v185 offset:8192
	ds_read_b128 v[126:129], v186 offset:8192
	ds_read_b128 v[114:117], v185 offset:10240
	ds_read_b128 v[118:121], v186 offset:10240
	ds_read_b128 v[106:109], v185 offset:12288
	ds_read_b128 v[110:113], v186 offset:12288
	ds_read_b128 v[98:101], v185 offset:14336
	ds_read_b128 v[102:105], v186 offset:14336
	s_waitcnt lgkmcnt(8)
	v_mfma_scale_f32_32x32x64_f8f6f4 v[66:81], v[222:229], v[130:137], v[66:81], v194, v193 op_sel_hi:[0,0,0]
	v_mov_b32_e32 v0, v219
	s_nop 1
	v_permlane32_swap_b32_e32 v219, v0
	v_add_f32_e32 v219, v219, v0
	v_add_f32_e32 v209, v209, v219
	s_waitcnt vmcnt(0)
	ds_write_b128 v210, v[158:161]
	ds_write_b128 v211, v[162:165] offset:16384
	s_waitcnt lgkmcnt(0)
	s_barrier
	global_load_dwordx4 v[158:161], v176, s[18:19]
	global_load_dwordx4 v[162:165], v178, s[16:17]
	v_add_u32_e32 v176, 0x2000, v176
	v_add_u32_e32 v178, 0x20000, v178
	v_max_f32_e32 v177, v82, v83
	v_max3_f32 v177, v177, v84, v85
	v_max3_f32 v177, v177, v86, v87
	v_max3_f32 v177, v177, v88, v89
	v_max3_f32 v177, v177, v90, v91
	v_max3_f32 v177, v177, v92, v93
	v_max3_f32 v177, v177, v94, v95
	v_max3_f32 v177, v177, v96, v97
	s_waitcnt lgkmcnt(6)
	v_mfma_scale_f32_32x32x64_f8f6f4 v[50:65], v[246:253], v[122:129], v[50:65], v194, v194 op_sel_hi:[0,0,0]
	s_waitcnt lgkmcnt(4)
	v_mfma_scale_f32_32x32x64_f8f6f4 v[34:49], v[246:253], v[114:121], v[34:49], v194, v194 op_sel_hi:[0,0,0]
	s_waitcnt lgkmcnt(2)
	v_mfma_scale_f32_32x32x64_f8f6f4 v[18:33], v[246:253], v[106:113], v[18:33], v194, v194 op_sel_hi:[0,0,0]
	s_waitcnt lgkmcnt(0)
	v_mfma_scale_f32_32x32x64_f8f6f4 v[2:17], v[246:253], v[98:105], v[2:17], v194, v194 op_sel_hi:[0,0,0]
	v_max_f32_e32 v0, v66, v67
	v_max3_f32 v0, v0, v68, v69
	v_max3_f32 v0, v0, v70, v71
	v_max3_f32 v0, v0, v72, v73
	v_max3_f32 v0, v0, v74, v75
	v_max3_f32 v0, v0, v76, v77
	v_max3_f32 v0, v0, v78, v79
	v_max3_f32 v0, v0, v80, v81
	v_max_f32_e32 v177, v177, v0
	v_mov_b32_e32 v0, v177
	s_nop 1
	v_permlane32_swap_b32_e32 v177, v0
	v_max_f32_e32 v177, v177, v0
	v_cmp_ge_f32_e32 vcc, s90, v177
	s_cmp_eq_u64 vcc, exec
	s_cbranch_scc0 .Lmla_s1_newmax
; __device__ __forceinline__ void finishSM9(f32x16& p0, f32x16& p1, float alpha, float& l_reg, v8i32& p8) {
; #pragma unroll
;   for (int r = 0; r < 16; ++r) { p0[r] = __builtin_amdgcn_exp2f(p0[r]); p1[r] = __builtin_amdgcn_exp2f(p1[r]); }
;   float ps = 0;
; #pragma unroll
;   for (int r = 0; r < 16; ++r) ps += p0[r];
; #pragma unroll
;   for (int r = 0; r < 16; ++r) ps += p1[r];
;   { auto rr = __builtin_amdgcn_permlane32_swap(__float_as_uint(ps), __float_as_uint(ps), false, false);
;     ps = __uint_as_float(rr[0]) + __uint_as_float(rr[1]); }
;   l_reg = l_reg * alpha + ps;
; #pragma unroll
;   for (int g = 0; g < 4; ++g) {
;     int w = __builtin_amdgcn_cvt_pk_fp8_f32(p0[4 * g], p0[4 * g + 1], 0, false); p8[g] = __builtin_amdgcn_cvt_pk_fp8_f32(p0[4 * g + 2], p0[4 * g + 3], w, true);
;     int u = __builtin_amdgcn_cvt_pk_fp8_f32(p1[4 * g], p1[4 * g + 1], 0, false); p8[4 + g] = __builtin_amdgcn_cvt_pk_fp8_f32(p1[4 * g + 2], p1[4 * g + 3], u, true); }
; }
; __device__ __forceinline__ void pv8(f32x16* o, const char* Vt, const v8i32 p8, int r32, int hi) {
;   const int sw = (r32 >> 2) & 3, a0 = r32 * 64 + (((hi * 2) ^ sw) << 4), a1 = r32 * 64 + (((hi * 2 + 1) ^ sw) << 4);
; #pragma unroll
;   for (int d0 = 0; d0 < 4; ++d0) {
;     const v8i32 vf = cat8(*reinterpret_cast<const v4i32*>(Vt + d0 * 2048 + a0), *reinterpret_cast<const v4i32*>(Vt + d0 * 2048 + a1));
;     o[d0] = __builtin_amdgcn_mfma_scale_f32_32x32x64_f8f6f4(p8, vf, o[d0], 0, 0, 0, 127, 0, 127); }
; }
; __device__ __forceinline__ void qkt9(f32x16& p0, f32x16& p1, const char* Kn, const char* Kr, const v8i32* qf, const float init, int r32, int hi) {
; #pragma unroll
;   for (int r = 0; r < 16; ++r) { p0[r] = init; p1[r] = init; }
; #pragma unroll
;   for (int s = 0; s < 2; ++s) { const int c0 = s * 4 + hi * 2;
;     const v8i32 a0 = cat8(*reinterpret_cast<const v4i32*>(Kn + KN8SW(r32, c0)), *reinterpret_cast<const v4i32*>(Kn + KN8SW(r32, c0 + 1)));
;     const v8i32 a1 = cat8(*reinterpret_cast<const v4i32*>(Kn + 4096 + KN8SW(r32, c0)), *reinterpret_cast<const v4i32*>(Kn + 4096 + KN8SW(r32, c0 + 1)));
;     p0 = __builtin_amdgcn_mfma_scale_f32_32x32x64_f8f6f4(a0, qf[s], p0, 0, 0, 0, 127, 0, 124);
;     p1 = __builtin_amdgcn_mfma_scale_f32_32x32x64_f8f6f4(a1, qf[s], p1, 0, 0, 0, 127, 0, 124); }
;   { const int c0 = hi * 2;
.Lmla_s1_cont:
	ds_read_b128 v[114:117], v215 offset:16384
	ds_read_b128 v[118:121], v216 offset:16384
	ds_read_b128 v[222:225], v215 offset:20480
	ds_read_b128 v[226:229], v216 offset:20480
	v_exp_f32_e32 v0, v82
	v_exp_f32_e32 v177, v83
	v_exp_f32_e32 v179, v84
	v_exp_f32_e32 v254, v85
	v_add_f32_e32 v219, v0, v177
	v_cvt_pk_fp8_f32 v246, v0, v177
	v_add_f32_e32 v219, v179, v219
	v_add_f32_e32 v219, v254, v219
	v_cvt_pk_fp8_f32 v246, v179, v254 op_sel:[0,0,1]
	s_waitcnt lgkmcnt(2)
	v_mfma_scale_f32_32x32x64_f8f6f4 v[114:129], v[114:121], v[146:153], v[230:245], v194, v193 op_sel_hi:[0,0,0]
	v_exp_f32_e32 v0, v86
	v_exp_f32_e32 v177, v87
	v_exp_f32_e32 v179, v88
	v_exp_f32_e32 v254, v89
	v_add_f32_e32 v219, v0, v219
	v_add_f32_e32 v219, v177, v219
	v_cvt_pk_fp8_f32 v247, v0, v177
	v_add_f32_e32 v219, v179, v219
	v_add_f32_e32 v219, v254, v219
	v_cvt_pk_fp8_f32 v247, v179, v254 op_sel:[0,0,1]
	ds_read_b128 v[82:85], v213 offset:16384
	ds_read_b128 v[86:89], v214 offset:16384
	s_waitcnt lgkmcnt(2)
	v_mfma_scale_f32_32x32x64_f8f6f4 v[98:113], v[222:229], v[146:153], v[230:245], v194, v193 op_sel_hi:[0,0,0]
	ds_read_b128 v[222:225], v213 offset:20480
	ds_read_b128 v[226:229], v214 offset:20480
	v_exp_f32_e32 v0, v90
	v_exp_f32_e32 v177, v91
	v_exp_f32_e32 v179, v92
	v_exp_f32_e32 v254, v93
	v_add_f32_e32 v219, v0, v219
	v_add_f32_e32 v219, v177, v219
	v_cvt_pk_fp8_f32 v248, v0, v177
	v_add_f32_e32 v219, v179, v219
	v_add_f32_e32 v219, v254, v219
	v_cvt_pk_fp8_f32 v248, v179, v254 op_sel:[0,0,1]
	v_exp_f32_e32 v0, v94
	v_exp_f32_e32 v177, v95
	v_exp_f32_e32 v179, v96
	v_exp_f32_e32 v254, v97
	v_add_f32_e32 v219, v0, v219
	v_add_f32_e32 v219, v177, v219
	v_cvt_pk_fp8_f32 v249, v0, v177
	v_add_f32_e32 v219, v179, v219
	v_add_f32_e32 v219, v254, v219
	v_cvt_pk_fp8_f32 v249, v179, v254 op_sel:[0,0,1]
	ds_read_b128 v[90:93], v185 offset:32768
	ds_read_b128 v[94:97], v186 offset:32768
	s_waitcnt lgkmcnt(4)
	v_mfma_scale_f32_32x32x64_f8f6f4 v[114:129], v[82:89], v[138:145], v[114:129], v194, v193 op_sel_hi:[0,0,0]
	v_exp_f32_e32 v0, v66
	v_exp_f32_e32 v177, v67
	v_exp_f32_e32 v179, v68
	v_exp_f32_e32 v254, v69
	v_add_f32_e32 v219, v0, v219
	v_add_f32_e32 v219, v177, v219
	v_cvt_pk_fp8_f32 v250, v0, v177
	v_add_f32_e32 v219, v179, v219
	v_add_f32_e32 v219, v254, v219
	v_cvt_pk_fp8_f32 v250, v179, v254 op_sel:[0,0,1]
	s_waitcnt lgkmcnt(2)
	v_mfma_scale_f32_32x32x64_f8f6f4 v[98:113], v[222:229], v[138:145], v[98:113], v194, v193 op_sel_hi:[0,0,0]
	ds_read_b128 v[222:225], v185 offset:34816
	ds_read_b128 v[226:229], v186 offset:34816
	v_exp_f32_e32 v0, v70
	v_exp_f32_e32 v177, v71
	v_exp_f32_e32 v179, v72
	v_exp_f32_e32 v254, v73
	v_add_f32_e32 v219, v0, v219
	v_add_f32_e32 v219, v177, v219
	v_cvt_pk_fp8_f32 v251, v0, v177
	v_add_f32_e32 v219, v179, v219
	v_add_f32_e32 v219, v254, v219
	v_cvt_pk_fp8_f32 v251, v179, v254 op_sel:[0,0,1]
	v_exp_f32_e32 v0, v74
	v_exp_f32_e32 v177, v75
	v_exp_f32_e32 v179, v76
	v_exp_f32_e32 v254, v77
	v_add_f32_e32 v219, v0, v219
	v_add_f32_e32 v219, v177, v219
	v_cvt_pk_fp8_f32 v252, v0, v177
	v_add_f32_e32 v219, v179, v219
	v_add_f32_e32 v219, v254, v219
	v_cvt_pk_fp8_f32 v252, v179, v254 op_sel:[0,0,1]
	s_waitcnt lgkmcnt(2)
	v_mfma_scale_f32_32x32x64_f8f6f4 v[114:129], v[90:97], v[130:137], v[114:129], v194, v193 op_sel_hi:[0,0,0]
	v_exp_f32_e32 v0, v78
	v_exp_f32_e32 v177, v79
	v_exp_f32_e32 v179, v80
	v_exp_f32_e32 v254, v81
	v_add_f32_e32 v219, v0, v219
	v_add_f32_e32 v219, v177, v219
	v_cvt_pk_fp8_f32 v253, v0, v177
	v_add_f32_e32 v219, v179, v219
	v_add_f32_e32 v219, v254, v219
	v_cvt_pk_fp8_f32 v253, v179, v254 op_sel:[0,0,1]
	ds_read_b128 v[90:93], v185 offset:43008
	ds_read_b128 v[94:97], v186 offset:43008
	ds_read_b128 v[82:85], v185 offset:45056
	ds_read_b128 v[86:89], v186 offset:45056
	ds_read_b128 v[74:77], v185 offset:47104
	ds_read_b128 v[78:81], v186 offset:47104
	ds_read_b128 v[66:69], v185 offset:49152
	ds_read_b128 v[70:73], v186 offset:49152
	s_waitcnt lgkmcnt(8)
	v_mfma_scale_f32_32x32x64_f8f6f4 v[98:113], v[222:229], v[130:137], v[98:113], v194, v193 op_sel_hi:[0,0,0]
	v_mov_b32_e32 v0, v219
	s_nop 1
	v_permlane32_swap_b32_e32 v219, v0
	v_add_f32_e32 v219, v219, v0
	v_add_f32_e32 v209, v209, v219
	s_waitcnt vmcnt(0)
	ds_write_b128 v210, v[158:161] offset:8192
	ds_write_b128 v211, v[162:165] offset:24576
	s_waitcnt lgkmcnt(0)
	s_barrier
	global_load_dwordx4 v[158:161], v176, s[18:19]
	global_load_dwordx4 v[162:165], v178, s[16:17]
	v_add_u32_e32 v176, 0x2000, v176
	v_add_u32_e32 v178, 0x20000, v178
	v_max_f32_e32 v177, v114, v115
	v_max3_f32 v177, v177, v116, v117
	v_max3_f32 v177, v177, v118, v119
	v_max3_f32 v177, v177, v120, v121
	v_max3_f32 v177, v177, v122, v123
	v_max3_f32 v177, v177, v124, v125
	v_max3_f32 v177, v177, v126, v127
	v_max3_f32 v177, v177, v128, v129
	s_waitcnt lgkmcnt(6)
	v_mfma_scale_f32_32x32x64_f8f6f4 v[50:65], v[246:253], v[90:97], v[50:65], v194, v194 op_sel_hi:[0,0,0]
	s_waitcnt lgkmcnt(4)
	v_mfma_scale_f32_32x32x64_f8f6f4 v[34:49], v[246:253], v[82:89], v[34:49], v194, v194 op_sel_hi:[0,0,0]
	s_waitcnt lgkmcnt(2)
	v_mfma_scale_f32_32x32x64_f8f6f4 v[18:33], v[246:253], v[74:81], v[18:33], v194, v194 op_sel_hi:[0,0,0]
	s_waitcnt lgkmcnt(0)
	v_mfma_scale_f32_32x32x64_f8f6f4 v[2:17], v[246:253], v[66:73], v[2:17], v194, v194 op_sel_hi:[0,0,0]
	v_max_f32_e32 v0, v98, v99
	v_max3_f32 v0, v0, v100, v101
	v_max3_f32 v0, v0, v102, v103
	v_max3_f32 v0, v0, v104, v105
	v_max3_f32 v0, v0, v106, v107
	v_max3_f32 v0, v0, v108, v109
	v_max3_f32 v0, v0, v110, v111
	v_max3_f32 v0, v0, v112, v113
	v_max_f32_e32 v177, v177, v0
	v_mov_b32_e32 v0, v177
	s_nop 1
	v_permlane32_swap_b32_e32 v177, v0
	v_max_f32_e32 v177, v177, v0
	v_cmp_ge_f32_e32 vcc, s90, v177
	s_cmp_eq_u64 vcc, exec
	s_cbranch_scc0 .Lmla_s2_newmax
; __device__ __forceinline__ void finishSM9(f32x16& p0, f32x16& p1, float alpha, float& l_reg, v8i32& p8) {
; #pragma unroll
;   for (int r = 0; r < 16; ++r) { p0[r] = __builtin_amdgcn_exp2f(p0[r]); p1[r] = __builtin_amdgcn_exp2f(p1[r]); }
;   float ps = 0;
; #pragma unroll
;   for (int r = 0; r < 16; ++r) ps += p0[r];
; #pragma unroll
;   for (int r = 0; r < 16; ++r) ps += p1[r];
;   { auto rr = __builtin_amdgcn_permlane32_swap(__float_as_uint(ps), __float_as_uint(ps), false, false);
;     ps = __uint_as_float(rr[0]) + __uint_as_float(rr[1]); }
;   l_reg = l_reg * alpha + ps;
; #pragma unroll
;   for (int g = 0; g < 4; ++g) {
;     int w = __builtin_amdgcn_cvt_pk_fp8_f32(p0[4 * g], p0[4 * g + 1], 0, false); p8[g] = __builtin_amdgcn_cvt_pk_fp8_f32(p0[4 * g + 2], p0[4 * g + 3], w, true);
;     int u = __builtin_amdgcn_cvt_pk_fp8_f32(p1[4 * g], p1[4 * g + 1], 0, false); p8[4 + g] = __builtin_amdgcn_cvt_pk_fp8_f32(p1[4 * g + 2], p1[4 * g + 3], u, true); }
; }
; __device__ __forceinline__ void pv8(f32x16* o, const char* Vt, const v8i32 p8, int r32, int hi) {
;   const int sw = (r32 >> 2) & 3, a0 = r32 * 64 + (((hi * 2) ^ sw) << 4), a1 = r32 * 64 + (((hi * 2 + 1) ^ sw) << 4);
; #pragma unroll
;   for (int d0 = 0; d0 < 4; ++d0) {
;     const v8i32 vf = cat8(*reinterpret_cast<const v4i32*>(Vt + d0 * 2048 + a0), *reinterpret_cast<const v4i32*>(Vt + d0 * 2048 + a1));
;     o[d0] = __builtin_amdgcn_mfma_scale_f32_32x32x64_f8f6f4(p8, vf, o[d0], 0, 0, 0, 127, 0, 127); }
; }
; __device__ __forceinline__ void qkt9(f32x16& p0, f32x16& p1, const char* Kn, const char* Kr, const v8i32* qf, const float init, int r32, int hi) {
; #pragma unroll
;   for (int r = 0; r < 16; ++r) { p0[r] = init; p1[r] = init; }
; #pragma unroll
;   for (int s = 0; s < 2; ++s) { const int c0 = s * 4 + hi * 2;
;     const v8i32 a0 = cat8(*reinterpret_cast<const v4i32*>(Kn + KN8SW(r32, c0)), *reinterpret_cast<const v4i32*>(Kn + KN8SW(r32, c0 + 1)));
;     const v8i32 a1 = cat8(*reinterpret_cast<const v4i32*>(Kn + 4096 + KN8SW(r32, c0)), *reinterpret_cast<const v4i32*>(Kn + 4096 + KN8SW(r32, c0 + 1)));
;     p0 = __builtin_amdgcn_mfma_scale_f32_32x32x64_f8f6f4(a0, qf[s], p0, 0, 0, 0, 127, 0, 124);
;     p1 = __builtin_amdgcn_mfma_scale_f32_32x32x64_f8f6f4(a1, qf[s], p1, 0, 0, 0, 127, 0, 124); }
;   { const int c0 = hi * 2;
.Lmla_s2_cont:
	ds_read_b128 v[82:85], v215 offset:24576
	ds_read_b128 v[86:89], v216 offset:24576
	ds_read_b128 v[222:225], v215 offset:28672
	ds_read_b128 v[226:229], v216 offset:28672
	v_exp_f32_e32 v0, v114
	v_exp_f32_e32 v177, v115
	v_exp_f32_e32 v179, v116
	v_exp_f32_e32 v254, v117
	v_add_f32_e32 v219, v0, v177
	v_cvt_pk_fp8_f32 v246, v0, v177
	v_add_f32_e32 v219, v179, v219
	v_add_f32_e32 v219, v254, v219
	v_cvt_pk_fp8_f32 v246, v179, v254 op_sel:[0,0,1]
	s_waitcnt lgkmcnt(2)
	v_mfma_scale_f32_32x32x64_f8f6f4 v[82:97], v[82:89], v[146:153], v[230:245], v194, v193 op_sel_hi:[0,0,0]
	v_exp_f32_e32 v0, v118
	v_exp_f32_e32 v177, v119
	v_exp_f32_e32 v179, v120
	v_exp_f32_e32 v254, v121
	v_add_f32_e32 v219, v0, v219
	v_add_f32_e32 v219, v177, v219
	v_cvt_pk_fp8_f32 v247, v0, v177
	v_add_f32_e32 v219, v179, v219
	v_add_f32_e32 v219, v254, v219
	v_cvt_pk_fp8_f32 v247, v179, v254 op_sel:[0,0,1]
	ds_read_b128 v[114:117], v213 offset:24576
	ds_read_b128 v[118:121], v214 offset:24576
	s_waitcnt lgkmcnt(2)
	v_mfma_scale_f32_32x32x64_f8f6f4 v[66:81], v[222:229], v[146:153], v[230:245], v194, v193 op_sel_hi:[0,0,0]
	ds_read_b128 v[222:225], v213 offset:28672
	ds_read_b128 v[226:229], v214 offset:28672
	v_exp_f32_e32 v0, v122
	v_exp_f32_e32 v177, v123
	v_exp_f32_e32 v179, v124
	v_exp_f32_e32 v254, v125
	v_add_f32_e32 v219, v0, v219
	v_add_f32_e32 v219, v177, v219
	v_cvt_pk_fp8_f32 v248, v0, v177
	v_add_f32_e32 v219, v179, v219
	v_add_f32_e32 v219, v254, v219
	v_cvt_pk_fp8_f32 v248, v179, v254 op_sel:[0,0,1]
	v_exp_f32_e32 v0, v126
	v_exp_f32_e32 v177, v127
	v_exp_f32_e32 v179, v128
	v_exp_f32_e32 v254, v129
	v_add_f32_e32 v219, v0, v219
	v_add_f32_e32 v219, v177, v219
	v_cvt_pk_fp8_f32 v249, v0, v177
	v_add_f32_e32 v219, v179, v219
	v_add_f32_e32 v219, v254, v219
	v_cvt_pk_fp8_f32 v249, v179, v254 op_sel:[0,0,1]
	ds_read_b128 v[122:125], v185 offset:36864
	ds_read_b128 v[126:129], v186 offset:36864
	s_waitcnt lgkmcnt(4)
	v_mfma_scale_f32_32x32x64_f8f6f4 v[82:97], v[114:121], v[138:145], v[82:97], v194, v193 op_sel_hi:[0,0,0]
	v_exp_f32_e32 v0, v98
	v_exp_f32_e32 v177, v99
	v_exp_f32_e32 v179, v100
	v_exp_f32_e32 v254, v101
	v_add_f32_e32 v219, v0, v219
	v_add_f32_e32 v219, v177, v219
	v_cvt_pk_fp8_f32 v250, v0, v177
	v_add_f32_e32 v219, v179, v219
	v_add_f32_e32 v219, v254, v219
	v_cvt_pk_fp8_f32 v250, v179, v254 op_sel:[0,0,1]
	s_waitcnt lgkmcnt(2)
	v_mfma_scale_f32_32x32x64_f8f6f4 v[66:81], v[222:229], v[138:145], v[66:81], v194, v193 op_sel_hi:[0,0,0]
	ds_read_b128 v[222:225], v185 offset:38912
	ds_read_b128 v[226:229], v186 offset:38912
	v_exp_f32_e32 v0, v102
	v_exp_f32_e32 v177, v103
	v_exp_f32_e32 v179, v104
	v_exp_f32_e32 v254, v105
	v_add_f32_e32 v219, v0, v219
	v_add_f32_e32 v219, v177, v219
	v_cvt_pk_fp8_f32 v251, v0, v177
	v_add_f32_e32 v219, v179, v219
	v_add_f32_e32 v219, v254, v219
	v_cvt_pk_fp8_f32 v251, v179, v254 op_sel:[0,0,1]
	v_exp_f32_e32 v0, v106
	v_exp_f32_e32 v177, v107
	v_exp_f32_e32 v179, v108
	v_exp_f32_e32 v254, v109
	v_add_f32_e32 v219, v0, v219
	v_add_f32_e32 v219, v177, v219
	v_cvt_pk_fp8_f32 v252, v0, v177
	v_add_f32_e32 v219, v179, v219
	v_add_f32_e32 v219, v254, v219
	v_cvt_pk_fp8_f32 v252, v179, v254 op_sel:[0,0,1]
	s_waitcnt lgkmcnt(2)
	v_mfma_scale_f32_32x32x64_f8f6f4 v[82:97], v[122:129], v[130:137], v[82:97], v194, v193 op_sel_hi:[0,0,0]
	v_exp_f32_e32 v0, v110
	v_exp_f32_e32 v177, v111
	v_exp_f32_e32 v179, v112
	v_exp_f32_e32 v254, v113
	v_add_f32_e32 v219, v0, v219
	v_add_f32_e32 v219, v177, v219
	v_cvt_pk_fp8_f32 v253, v0, v177
	v_add_f32_e32 v219, v179, v219
	v_add_f32_e32 v219, v254, v219
	v_cvt_pk_fp8_f32 v253, v179, v254 op_sel:[0,0,1]
	ds_read_b128 v[122:125], v185 offset:0
	ds_read_b128 v[126:129], v186 offset:0
	ds_read_b128 v[114:117], v185 offset:2048
	ds_read_b128 v[118:121], v186 offset:2048
	ds_read_b128 v[106:109], v185 offset:4096
	ds_read_b128 v[110:113], v186 offset:4096
	ds_read_b128 v[98:101], v185 offset:6144
	ds_read_b128 v[102:105], v186 offset:6144
	s_waitcnt lgkmcnt(8)
	v_mfma_scale_f32_32x32x64_f8f6f4 v[66:81], v[222:229], v[130:137], v[66:81], v194, v193 op_sel_hi:[0,0,0]
	v_mov_b32_e32 v0, v219
	s_nop 1
	v_permlane32_swap_b32_e32 v219, v0
	v_add_f32_e32 v219, v219, v0
	v_add_f32_e32 v209, v209, v219
	s_waitcnt vmcnt(0)
	ds_write_b128 v210, v[158:161] offset:43008
	ds_write_b128 v211, v[162:165] offset:51200
	s_waitcnt lgkmcnt(0)
	s_barrier
	global_load_dwordx4 v[158:161], v176, s[18:19]
	global_load_dwordx4 v[162:165], v178, s[16:17]
	v_add_u32_e32 v176, 0x2000, v176
	v_add_u32_e32 v178, 0x20000, v178
	v_max_f32_e32 v177, v82, v83
	v_max3_f32 v177, v177, v84, v85
	v_max3_f32 v177, v177, v86, v87
	v_max3_f32 v177, v177, v88, v89
	v_max3_f32 v177, v177, v90, v91
	v_max3_f32 v177, v177, v92, v93
	v_max3_f32 v177, v177, v94, v95
	v_max3_f32 v177, v177, v96, v97
	s_waitcnt lgkmcnt(6)
	v_mfma_scale_f32_32x32x64_f8f6f4 v[50:65], v[246:253], v[122:129], v[50:65], v194, v194 op_sel_hi:[0,0,0]
	s_waitcnt lgkmcnt(4)
	v_mfma_scale_f32_32x32x64_f8f6f4 v[34:49], v[246:253], v[114:121], v[34:49], v194, v194 op_sel_hi:[0,0,0]
	s_waitcnt lgkmcnt(2)
	v_mfma_scale_f32_32x32x64_f8f6f4 v[18:33], v[246:253], v[106:113], v[18:33], v194, v194 op_sel_hi:[0,0,0]
	s_waitcnt lgkmcnt(0)
	v_mfma_scale_f32_32x32x64_f8f6f4 v[2:17], v[246:253], v[98:105], v[2:17], v194, v194 op_sel_hi:[0,0,0]
	v_max_f32_e32 v0, v66, v67
	v_max3_f32 v0, v0, v68, v69
	v_max3_f32 v0, v0, v70, v71
	v_max3_f32 v0, v0, v72, v73
	v_max3_f32 v0, v0, v74, v75
	v_max3_f32 v0, v0, v76, v77
	v_max3_f32 v0, v0, v78, v79
	v_max3_f32 v0, v0, v80, v81
	v_max_f32_e32 v177, v177, v0
	v_mov_b32_e32 v0, v177
	s_nop 1
	v_permlane32_swap_b32_e32 v177, v0
	v_max_f32_e32 v177, v177, v0
	v_cmp_ge_f32_e32 vcc, s90, v177
	s_cmp_eq_u64 vcc, exec
	s_cbranch_scc0 .Lmla_s3_newmax
; __device__ __forceinline__ void finishSM9(f32x16& p0, f32x16& p1, float alpha, float& l_reg, v8i32& p8) {
; #pragma unroll
;   for (int r = 0; r < 16; ++r) { p0[r] = __builtin_amdgcn_exp2f(p0[r]); p1[r] = __builtin_amdgcn_exp2f(p1[r]); }
;   float ps = 0;
; #pragma unroll
;   for (int r = 0; r < 16; ++r) ps += p0[r];
; #pragma unroll
;   for (int r = 0; r < 16; ++r) ps += p1[r];
;   { auto rr = __builtin_amdgcn_permlane32_swap(__float_as_uint(ps), __float_as_uint(ps), false, false);
;     ps = __uint_as_float(rr[0]) + __uint_as_float(rr[1]); }
;   l_reg = l_reg * alpha + ps;
; #pragma unroll
;   for (int g = 0; g < 4; ++g) {
;     int w = __builtin_amdgcn_cvt_pk_fp8_f32(p0[4 * g], p0[4 * g + 1], 0, false); p8[g] = __builtin_amdgcn_cvt_pk_fp8_f32(p0[4 * g + 2], p0[4 * g + 3], w, true);
;     int u = __builtin_amdgcn_cvt_pk_fp8_f32(p1[4 * g], p1[4 * g + 1], 0, false); p8[4 + g] = __builtin_amdgcn_cvt_pk_fp8_f32(p1[4 * g + 2], p1[4 * g + 3], u, true); }
; }
; __device__ __forceinline__ void pv8(f32x16* o, const char* Vt, const v8i32 p8, int r32, int hi) {
;   const int sw = (r32 >> 2) & 3, a0 = r32 * 64 + (((hi * 2) ^ sw) << 4), a1 = r32 * 64 + (((hi * 2 + 1) ^ sw) << 4);
; #pragma unroll
;   for (int d0 = 0; d0 < 4; ++d0) {
;     const v8i32 vf = cat8(*reinterpret_cast<const v4i32*>(Vt + d0 * 2048 + a0), *reinterpret_cast<const v4i32*>(Vt + d0 * 2048 + a1));
;     o[d0] = __builtin_amdgcn_mfma_scale_f32_32x32x64_f8f6f4(p8, vf, o[d0], 0, 0, 0, 127, 0, 127); }
; }
; __device__ __forceinline__ void qkt9(f32x16& p0, f32x16& p1, const char* Kn, const char* Kr, const v8i32* qf, const float init, int r32, int hi) {
; #pragma unroll
;   for (int r = 0; r < 16; ++r) { p0[r] = init; p1[r] = init; }
; #pragma unroll
;   for (int s = 0; s < 2; ++s) { const int c0 = s * 4 + hi * 2;
;     const v8i32 a0 = cat8(*reinterpret_cast<const v4i32*>(Kn + KN8SW(r32, c0)), *reinterpret_cast<const v4i32*>(Kn + KN8SW(r32, c0 + 1)));
;     const v8i32 a1 = cat8(*reinterpret_cast<const v4i32*>(Kn + 4096 + KN8SW(r32, c0)), *reinterpret_cast<const v4i32*>(Kn + 4096 + KN8SW(r32, c0 + 1)));
;     p0 = __builtin_amdgcn_mfma_scale_f32_32x32x64_f8f6f4(a0, qf[s], p0, 0, 0, 0, 127, 0, 124);
;     p1 = __builtin_amdgcn_mfma_scale_f32_32x32x64_f8f6f4(a1, qf[s], p1, 0, 0, 0, 127, 0, 124); }
;   { const int c0 = hi * 2;
.Lmla_s3_cont:
	ds_read_b128 v[114:117], v215 offset:51200
	ds_read_b128 v[118:121], v216 offset:51200
	ds_read_b128 v[222:225], v215 offset:55296
	ds_read_b128 v[226:229], v216 offset:55296
	v_exp_f32_e32 v0, v82
	v_exp_f32_e32 v177, v83
	v_exp_f32_e32 v179, v84
	v_exp_f32_e32 v254, v85
	v_add_f32_e32 v219, v0, v177
	v_cvt_pk_fp8_f32 v246, v0, v177
	v_add_f32_e32 v219, v179, v219
	v_add_f32_e32 v219, v254, v219
	v_cvt_pk_fp8_f32 v246, v179, v254 op_sel:[0,0,1]
	s_waitcnt lgkmcnt(2)
	v_mfma_scale_f32_32x32x64_f8f6f4 v[114:129], v[114:121], v[146:153], v[230:245], v194, v193 op_sel_hi:[0,0,0]
	v_exp_f32_e32 v0, v86
	v_exp_f32_e32 v177, v87
	v_exp_f32_e32 v179, v88
	v_exp_f32_e32 v254, v89
	v_add_f32_e32 v219, v0, v219
	v_add_f32_e32 v219, v177, v219
	v_cvt_pk_fp8_f32 v247, v0, v177
	v_add_f32_e32 v219, v179, v219
	v_add_f32_e32 v219, v254, v219
	v_cvt_pk_fp8_f32 v247, v179, v254 op_sel:[0,0,1]
	ds_read_b128 v[82:85], v213 offset:51200
	ds_read_b128 v[86:89], v214 offset:51200
	s_waitcnt lgkmcnt(2)
	v_mfma_scale_f32_32x32x64_f8f6f4 v[98:113], v[222:229], v[146:153], v[230:245], v194, v193 op_sel_hi:[0,0,0]
	ds_read_b128 v[222:225], v213 offset:55296
	ds_read_b128 v[226:229], v214 offset:55296
	v_exp_f32_e32 v0, v90
	v_exp_f32_e32 v177, v91
	v_exp_f32_e32 v179, v92
	v_exp_f32_e32 v254, v93
	v_add_f32_e32 v219, v0, v219
	v_add_f32_e32 v219, v177, v219
	v_cvt_pk_fp8_f32 v248, v0, v177
	v_add_f32_e32 v219, v179, v219
	v_add_f32_e32 v219, v254, v219
	v_cvt_pk_fp8_f32 v248, v179, v254 op_sel:[0,0,1]
	v_exp_f32_e32 v0, v94
	v_exp_f32_e32 v177, v95
	v_exp_f32_e32 v179, v96
	v_exp_f32_e32 v254, v97
	v_add_f32_e32 v219, v0, v219
	v_add_f32_e32 v219, v177, v219
	v_cvt_pk_fp8_f32 v249, v0, v177
	v_add_f32_e32 v219, v179, v219
	v_add_f32_e32 v219, v254, v219
	v_cvt_pk_fp8_f32 v249, v179, v254 op_sel:[0,0,1]
	ds_read_b128 v[90:93], v185 offset:59392
	ds_read_b128 v[94:97], v186 offset:59392
	s_waitcnt lgkmcnt(4)
	v_mfma_scale_f32_32x32x64_f8f6f4 v[114:129], v[82:89], v[138:145], v[114:129], v194, v193 op_sel_hi:[0,0,0]
	v_exp_f32_e32 v0, v66
	v_exp_f32_e32 v177, v67
	v_exp_f32_e32 v179, v68
	v_exp_f32_e32 v254, v69
	v_add_f32_e32 v219, v0, v219
	v_add_f32_e32 v219, v177, v219
	v_cvt_pk_fp8_f32 v250, v0, v177
	v_add_f32_e32 v219, v179, v219
	v_add_f32_e32 v219, v254, v219
	v_cvt_pk_fp8_f32 v250, v179, v254 op_sel:[0,0,1]
	s_waitcnt lgkmcnt(2)
	v_mfma_scale_f32_32x32x64_f8f6f4 v[98:113], v[222:229], v[138:145], v[98:113], v194, v193 op_sel_hi:[0,0,0]
	ds_read_b128 v[222:225], v185 offset:61440
	ds_read_b128 v[226:229], v186 offset:61440
	v_exp_f32_e32 v0, v70
	v_exp_f32_e32 v177, v71
	v_exp_f32_e32 v179, v72
	v_exp_f32_e32 v254, v73
	v_add_f32_e32 v219, v0, v219
	v_add_f32_e32 v219, v177, v219
	v_cvt_pk_fp8_f32 v251, v0, v177
	v_add_f32_e32 v219, v179, v219
	v_add_f32_e32 v219, v254, v219
	v_cvt_pk_fp8_f32 v251, v179, v254 op_sel:[0,0,1]
	v_exp_f32_e32 v0, v74
	v_exp_f32_e32 v177, v75
	v_exp_f32_e32 v179, v76
	v_exp_f32_e32 v254, v77
	v_add_f32_e32 v219, v0, v219
	v_add_f32_e32 v219, v177, v219
	v_cvt_pk_fp8_f32 v252, v0, v177
	v_add_f32_e32 v219, v179, v219
	v_add_f32_e32 v219, v254, v219
	v_cvt_pk_fp8_f32 v252, v179, v254 op_sel:[0,0,1]
	s_waitcnt lgkmcnt(2)
	v_mfma_scale_f32_32x32x64_f8f6f4 v[114:129], v[90:97], v[130:137], v[114:129], v194, v193 op_sel_hi:[0,0,0]
	v_exp_f32_e32 v0, v78
	v_exp_f32_e32 v177, v79
	v_exp_f32_e32 v179, v80
	v_exp_f32_e32 v254, v81
	v_add_f32_e32 v219, v0, v219
	v_add_f32_e32 v219, v177, v219
	v_cvt_pk_fp8_f32 v253, v0, v177
	v_add_f32_e32 v219, v179, v219
	v_add_f32_e32 v219, v254, v219
	v_cvt_pk_fp8_f32 v253, v179, v254 op_sel:[0,0,1]
	ds_read_b128 v[90:93], v185 offset:8192
	ds_read_b128 v[94:97], v186 offset:8192
	ds_read_b128 v[82:85], v185 offset:10240
	ds_read_b128 v[86:89], v186 offset:10240
	ds_read_b128 v[74:77], v185 offset:12288
	ds_read_b128 v[78:81], v186 offset:12288
	ds_read_b128 v[66:69], v185 offset:14336
	ds_read_b128 v[70:73], v186 offset:14336
	s_waitcnt lgkmcnt(8)
	v_mfma_scale_f32_32x32x64_f8f6f4 v[98:113], v[222:229], v[130:137], v[98:113], v194, v193 op_sel_hi:[0,0,0]
	v_mov_b32_e32 v0, v219
	s_nop 1
	v_permlane32_swap_b32_e32 v219, v0
	v_add_f32_e32 v219, v219, v0
	v_add_f32_e32 v209, v209, v219
	s_waitcnt vmcnt(0)
	ds_write_b128 v210, v[158:161]
	ds_write_b128 v211, v[162:165] offset:16384
	s_waitcnt lgkmcnt(0)
	s_barrier
	global_load_dwordx4 v[158:161], v176, s[18:19]
	global_load_dwordx4 v[162:165], v178, s[16:17]
	v_add_u32_e32 v176, 0x2000, v176
	v_add_u32_e32 v178, 0x20000, v178
	v_max_f32_e32 v177, v114, v115
	v_max3_f32 v177, v177, v116, v117
	v_max3_f32 v177, v177, v118, v119
	v_max3_f32 v177, v177, v120, v121
	v_max3_f32 v177, v177, v122, v123
	v_max3_f32 v177, v177, v124, v125
	v_max3_f32 v177, v177, v126, v127
	v_max3_f32 v177, v177, v128, v129
	s_waitcnt lgkmcnt(6)
	v_mfma_scale_f32_32x32x64_f8f6f4 v[50:65], v[246:253], v[90:97], v[50:65], v194, v194 op_sel_hi:[0,0,0]
	s_waitcnt lgkmcnt(4)
	v_mfma_scale_f32_32x32x64_f8f6f4 v[34:49], v[246:253], v[82:89], v[34:49], v194, v194 op_sel_hi:[0,0,0]
	s_waitcnt lgkmcnt(2)
	v_mfma_scale_f32_32x32x64_f8f6f4 v[18:33], v[246:253], v[74:81], v[18:33], v194, v194 op_sel_hi:[0,0,0]
	s_waitcnt lgkmcnt(0)
	v_mfma_scale_f32_32x32x64_f8f6f4 v[2:17], v[246:253], v[66:73], v[2:17], v194, v194 op_sel_hi:[0,0,0]
	v_max_f32_e32 v0, v98, v99
	v_max3_f32 v0, v0, v100, v101
	v_max3_f32 v0, v0, v102, v103
	v_max3_f32 v0, v0, v104, v105
	v_max3_f32 v0, v0, v106, v107
	v_max3_f32 v0, v0, v108, v109
	v_max3_f32 v0, v0, v110, v111
	v_max3_f32 v0, v0, v112, v113
	v_max_f32_e32 v177, v177, v0
	v_mov_b32_e32 v0, v177
	s_nop 1
	v_permlane32_swap_b32_e32 v177, v0
	v_max_f32_e32 v177, v177, v0
	v_cmp_ge_f32_e32 vcc, s90, v177
	s_cmp_eq_u64 vcc, exec
	s_cbranch_scc0 .Lmla_s4_newmax
; __device__ __forceinline__ void finishSM9(f32x16& p0, f32x16& p1, float alpha, float& l_reg, v8i32& p8) {
; #pragma unroll
;   for (int r = 0; r < 16; ++r) { p0[r] = __builtin_amdgcn_exp2f(p0[r]); p1[r] = __builtin_amdgcn_exp2f(p1[r]); }
;   float ps = 0;
; #pragma unroll
;   for (int r = 0; r < 16; ++r) ps += p0[r];
; #pragma unroll
;   for (int r = 0; r < 16; ++r) ps += p1[r];
;   { auto rr = __builtin_amdgcn_permlane32_swap(__float_as_uint(ps), __float_as_uint(ps), false, false);
;     ps = __uint_as_float(rr[0]) + __uint_as_float(rr[1]); }
;   l_reg = l_reg * alpha + ps;
; #pragma unroll
;   for (int g = 0; g < 4; ++g) {
;     int w = __builtin_amdgcn_cvt_pk_fp8_f32(p0[4 * g], p0[4 * g + 1], 0, false); p8[g] = __builtin_amdgcn_cvt_pk_fp8_f32(p0[4 * g + 2], p0[4 * g + 3], w, true);
;     int u = __builtin_amdgcn_cvt_pk_fp8_f32(p1[4 * g], p1[4 * g + 1], 0, false); p8[4 + g] = __builtin_amdgcn_cvt_pk_fp8_f32(p1[4 * g + 2], p1[4 * g + 3], u, true); }
; }
; __device__ __forceinline__ void pv8(f32x16* o, const char* Vt, const v8i32 p8, int r32, int hi) {
;   const int sw = (r32 >> 2) & 3, a0 = r32 * 64 + (((hi * 2) ^ sw) << 4), a1 = r32 * 64 + (((hi * 2 + 1) ^ sw) << 4);
; #pragma unroll
;   for (int d0 = 0; d0 < 4; ++d0) {
;     const v8i32 vf = cat8(*reinterpret_cast<const v4i32*>(Vt + d0 * 2048 + a0), *reinterpret_cast<const v4i32*>(Vt + d0 * 2048 + a1));
;     o[d0] = __builtin_amdgcn_mfma_scale_f32_32x32x64_f8f6f4(p8, vf, o[d0], 0, 0, 0, 127, 0, 127); }
; }
; __device__ __forceinline__ void qkt9(f32x16& p0, f32x16& p1, const char* Kn, const char* Kr, const v8i32* qf, const float init, int r32, int hi) {
; #pragma unroll
;   for (int r = 0; r < 16; ++r) { p0[r] = init; p1[r] = init; }
; #pragma unroll
;   for (int s = 0; s < 2; ++s) { const int c0 = s * 4 + hi * 2;
;     const v8i32 a0 = cat8(*reinterpret_cast<const v4i32*>(Kn + KN8SW(r32, c0)), *reinterpret_cast<const v4i32*>(Kn + KN8SW(r32, c0 + 1)));
;     const v8i32 a1 = cat8(*reinterpret_cast<const v4i32*>(Kn + 4096 + KN8SW(r32, c0)), *reinterpret_cast<const v4i32*>(Kn + 4096 + KN8SW(r32, c0 + 1)));
;     p0 = __builtin_amdgcn_mfma_scale_f32_32x32x64_f8f6f4(a0, qf[s], p0, 0, 0, 0, 127, 0, 124);
;     p1 = __builtin_amdgcn_mfma_scale_f32_32x32x64_f8f6f4(a1, qf[s], p1, 0, 0, 0, 127, 0, 124); }
;   { const int c0 = hi * 2;
.Lmla_s4_cont:
	ds_read_b128 v[82:85], v215 offset:16384
	ds_read_b128 v[86:89], v216 offset:16384
	ds_read_b128 v[222:225], v215 offset:20480
	ds_read_b128 v[226:229], v216 offset:20480
	v_exp_f32_e32 v0, v114
	v_exp_f32_e32 v177, v115
	v_exp_f32_e32 v179, v116
	v_exp_f32_e32 v254, v117
	v_add_f32_e32 v219, v0, v177
	v_cvt_pk_fp8_f32 v246, v0, v177
	v_add_f32_e32 v219, v179, v219
	v_add_f32_e32 v219, v254, v219
	v_cvt_pk_fp8_f32 v246, v179, v254 op_sel:[0,0,1]
	s_waitcnt lgkmcnt(2)
	v_mfma_scale_f32_32x32x64_f8f6f4 v[82:97], v[82:89], v[146:153], v[230:245], v194, v193 op_sel_hi:[0,0,0]
	v_exp_f32_e32 v0, v118
	v_exp_f32_e32 v177, v119
	v_exp_f32_e32 v179, v120
	v_exp_f32_e32 v254, v121
	v_add_f32_e32 v219, v0, v219
	v_add_f32_e32 v219, v177, v219
	v_cvt_pk_fp8_f32 v247, v0, v177
	v_add_f32_e32 v219, v179, v219
	v_add_f32_e32 v219, v254, v219
	v_cvt_pk_fp8_f32 v247, v179, v254 op_sel:[0,0,1]
	ds_read_b128 v[114:117], v213 offset:16384
	ds_read_b128 v[118:121], v214 offset:16384
	s_waitcnt lgkmcnt(2)
	v_mfma_scale_f32_32x32x64_f8f6f4 v[66:81], v[222:229], v[146:153], v[230:245], v194, v193 op_sel_hi:[0,0,0]
	ds_read_b128 v[222:225], v213 offset:20480
	ds_read_b128 v[226:229], v214 offset:20480
	v_exp_f32_e32 v0, v122
	v_exp_f32_e32 v177, v123
	v_exp_f32_e32 v179, v124
	v_exp_f32_e32 v254, v125
	v_add_f32_e32 v219, v0, v219
	v_add_f32_e32 v219, v177, v219
	v_cvt_pk_fp8_f32 v248, v0, v177
	v_add_f32_e32 v219, v179, v219
	v_add_f32_e32 v219, v254, v219
	v_cvt_pk_fp8_f32 v248, v179, v254 op_sel:[0,0,1]
	v_exp_f32_e32 v0, v126
	v_exp_f32_e32 v177, v127
	v_exp_f32_e32 v179, v128
	v_exp_f32_e32 v254, v129
	v_add_f32_e32 v219, v0, v219
	v_add_f32_e32 v219, v177, v219
	v_cvt_pk_fp8_f32 v249, v0, v177
	v_add_f32_e32 v219, v179, v219
	v_add_f32_e32 v219, v254, v219
	v_cvt_pk_fp8_f32 v249, v179, v254 op_sel:[0,0,1]
	ds_read_b128 v[122:125], v185 offset:32768
	ds_read_b128 v[126:129], v186 offset:32768
	s_waitcnt lgkmcnt(4)
	v_mfma_scale_f32_32x32x64_f8f6f4 v[82:97], v[114:121], v[138:145], v[82:97], v194, v193 op_sel_hi:[0,0,0]
	v_exp_f32_e32 v0, v98
	v_exp_f32_e32 v177, v99
	v_exp_f32_e32 v179, v100
	v_exp_f32_e32 v254, v101
	v_add_f32_e32 v219, v0, v219
	v_add_f32_e32 v219, v177, v219
	v_cvt_pk_fp8_f32 v250, v0, v177
	v_add_f32_e32 v219, v179, v219
	v_add_f32_e32 v219, v254, v219
	v_cvt_pk_fp8_f32 v250, v179, v254 op_sel:[0,0,1]
	s_waitcnt lgkmcnt(2)
	v_mfma_scale_f32_32x32x64_f8f6f4 v[66:81], v[222:229], v[138:145], v[66:81], v194, v193 op_sel_hi:[0,0,0]
	ds_read_b128 v[222:225], v185 offset:34816
	ds_read_b128 v[226:229], v186 offset:34816
	v_exp_f32_e32 v0, v102
	v_exp_f32_e32 v177, v103
	v_exp_f32_e32 v179, v104
	v_exp_f32_e32 v254, v105
	v_add_f32_e32 v219, v0, v219
	v_add_f32_e32 v219, v177, v219
	v_cvt_pk_fp8_f32 v251, v0, v177
	v_add_f32_e32 v219, v179, v219
	v_add_f32_e32 v219, v254, v219
	v_cvt_pk_fp8_f32 v251, v179, v254 op_sel:[0,0,1]
	v_exp_f32_e32 v0, v106
	v_exp_f32_e32 v177, v107
	v_exp_f32_e32 v179, v108
	v_exp_f32_e32 v254, v109
	v_add_f32_e32 v219, v0, v219
	v_add_f32_e32 v219, v177, v219
	v_cvt_pk_fp8_f32 v252, v0, v177
	v_add_f32_e32 v219, v179, v219
	v_add_f32_e32 v219, v254, v219
	v_cvt_pk_fp8_f32 v252, v179, v254 op_sel:[0,0,1]
	s_waitcnt lgkmcnt(2)
	v_mfma_scale_f32_32x32x64_f8f6f4 v[82:97], v[122:129], v[130:137], v[82:97], v194, v193 op_sel_hi:[0,0,0]
	v_exp_f32_e32 v0, v110
	v_exp_f32_e32 v177, v111
	v_exp_f32_e32 v179, v112
	v_exp_f32_e32 v254, v113
	v_add_f32_e32 v219, v0, v219
	v_add_f32_e32 v219, v177, v219
	v_cvt_pk_fp8_f32 v253, v0, v177
	v_add_f32_e32 v219, v179, v219
	v_add_f32_e32 v219, v254, v219
	v_cvt_pk_fp8_f32 v253, v179, v254 op_sel:[0,0,1]
	ds_read_b128 v[122:125], v185 offset:43008
	ds_read_b128 v[126:129], v186 offset:43008
	ds_read_b128 v[114:117], v185 offset:45056
	ds_read_b128 v[118:121], v186 offset:45056
	ds_read_b128 v[106:109], v185 offset:47104
	ds_read_b128 v[110:113], v186 offset:47104
	ds_read_b128 v[98:101], v185 offset:49152
	ds_read_b128 v[102:105], v186 offset:49152
	s_waitcnt lgkmcnt(8)
	v_mfma_scale_f32_32x32x64_f8f6f4 v[66:81], v[222:229], v[130:137], v[66:81], v194, v193 op_sel_hi:[0,0,0]
	v_mov_b32_e32 v0, v219
	s_nop 1
	v_permlane32_swap_b32_e32 v219, v0
	v_add_f32_e32 v219, v219, v0
	v_add_f32_e32 v209, v209, v219
	s_waitcnt vmcnt(0)
	ds_write_b128 v210, v[158:161] offset:8192
	ds_write_b128 v211, v[162:165] offset:24576
	s_waitcnt lgkmcnt(0)
	s_barrier
	global_load_dwordx4 v[158:161], v176, s[18:19]
	global_load_dwordx4 v[162:165], v178, s[16:17]
	v_add_u32_e32 v176, 0x2000, v176
	v_add_u32_e32 v178, 0x20000, v178
	v_max_f32_e32 v177, v82, v83
	v_max3_f32 v177, v177, v84, v85
	v_max3_f32 v177, v177, v86, v87
	v_max3_f32 v177, v177, v88, v89
	v_max3_f32 v177, v177, v90, v91
	v_max3_f32 v177, v177, v92, v93
	v_max3_f32 v177, v177, v94, v95
	v_max3_f32 v177, v177, v96, v97
	s_waitcnt lgkmcnt(6)
	v_mfma_scale_f32_32x32x64_f8f6f4 v[50:65], v[246:253], v[122:129], v[50:65], v194, v194 op_sel_hi:[0,0,0]
	s_waitcnt lgkmcnt(4)
	v_mfma_scale_f32_32x32x64_f8f6f4 v[34:49], v[246:253], v[114:121], v[34:49], v194, v194 op_sel_hi:[0,0,0]
	s_waitcnt lgkmcnt(2)
	v_mfma_scale_f32_32x32x64_f8f6f4 v[18:33], v[246:253], v[106:113], v[18:33], v194, v194 op_sel_hi:[0,0,0]
	s_waitcnt lgkmcnt(0)
	v_mfma_scale_f32_32x32x64_f8f6f4 v[2:17], v[246:253], v[98:105], v[2:17], v194, v194 op_sel_hi:[0,0,0]
	v_max_f32_e32 v0, v66, v67
	v_max3_f32 v0, v0, v68, v69
	v_max3_f32 v0, v0, v70, v71
	v_max3_f32 v0, v0, v72, v73
	v_max3_f32 v0, v0, v74, v75
	v_max3_f32 v0, v0, v76, v77
	v_max3_f32 v0, v0, v78, v79
	v_max3_f32 v0, v0, v80, v81
	v_max_f32_e32 v177, v177, v0
	v_mov_b32_e32 v0, v177
	s_nop 1
	v_permlane32_swap_b32_e32 v177, v0
	v_max_f32_e32 v177, v177, v0
	v_cmp_ge_f32_e32 vcc, s90, v177
	s_cmp_eq_u64 vcc, exec
	s_cbranch_scc0 .Lmla_s5_newmax
; __device__ __forceinline__ void finishSM9(f32x16& p0, f32x16& p1, float alpha, float& l_reg, v8i32& p8) {
; #pragma unroll
;   for (int r = 0; r < 16; ++r) { p0[r] = __builtin_amdgcn_exp2f(p0[r]); p1[r] = __builtin_amdgcn_exp2f(p1[r]); }
;   float ps = 0;
; #pragma unroll
;   for (int r = 0; r < 16; ++r) ps += p0[r];
; #pragma unroll
;   for (int r = 0; r < 16; ++r) ps += p1[r];
;   { auto rr = __builtin_amdgcn_permlane32_swap(__float_as_uint(ps), __float_as_uint(ps), false, false);
;     ps = __uint_as_float(rr[0]) + __uint_as_float(rr[1]); }
;   l_reg = l_reg * alpha + ps;
; #pragma unroll
;   for (int g = 0; g < 4; ++g) {
;     int w = __builtin_amdgcn_cvt_pk_fp8_f32(p0[4 * g], p0[4 * g + 1], 0, false); p8[g] = __builtin_amdgcn_cvt_pk_fp8_f32(p0[4 * g + 2], p0[4 * g + 3], w, true);
;     int u = __builtin_amdgcn_cvt_pk_fp8_f32(p1[4 * g], p1[4 * g + 1], 0, false); p8[4 + g] = __builtin_amdgcn_cvt_pk_fp8_f32(p1[4 * g + 2], p1[4 * g + 3], u, true); }
; }
; __device__ __forceinline__ void pv8(f32x16* o, const char* Vt, const v8i32 p8, int r32, int hi) {
;   const int sw = (r32 >> 2) & 3, a0 = r32 * 64 + (((hi * 2) ^ sw) << 4), a1 = r32 * 64 + (((hi * 2 + 1) ^ sw) << 4);
; #pragma unroll
;   for (int d0 = 0; d0 < 4; ++d0) {
;     const v8i32 vf = cat8(*reinterpret_cast<const v4i32*>(Vt + d0 * 2048 + a0), *reinterpret_cast<const v4i32*>(Vt + d0 * 2048 + a1));
;     o[d0] = __builtin_amdgcn_mfma_scale_f32_32x32x64_f8f6f4(p8, vf, o[d0], 0, 0, 0, 127, 0, 127); }
; }
; __device__ __forceinline__ void qkt9(f32x16& p0, f32x16& p1, const char* Kn, const char* Kr, const v8i32* qf, const float init, int r32, int hi) {
; #pragma unroll
;   for (int r = 0; r < 16; ++r) { p0[r] = init; p1[r] = init; }
; #pragma unroll
;   for (int s = 0; s < 2; ++s) { const int c0 = s * 4 + hi * 2;
;     const v8i32 a0 = cat8(*reinterpret_cast<const v4i32*>(Kn + KN8SW(r32, c0)), *reinterpret_cast<const v4i32*>(Kn + KN8SW(r32, c0 + 1)));
;     const v8i32 a1 = cat8(*reinterpret_cast<const v4i32*>(Kn + 4096 + KN8SW(r32, c0)), *reinterpret_cast<const v4i32*>(Kn + 4096 + KN8SW(r32, c0 + 1)));
;     p0 = __builtin_amdgcn_mfma_scale_f32_32x32x64_f8f6f4(a0, qf[s], p0, 0, 0, 0, 127, 0, 124);
;     p1 = __builtin_amdgcn_mfma_scale_f32_32x32x64_f8f6f4(a1, qf[s], p1, 0, 0, 0, 127, 0, 124); }
;   { const int c0 = hi * 2;
.Lmla_s5_cont:
	s_add_i32 s30, s30, 1
	s_cmpk_lt_u32 s30, 42
	s_cbranch_scc1 .Lmla_stag_loop
	ds_read_b128 v[114:117], v215 offset:24576
	ds_read_b128 v[118:121], v216 offset:24576
	ds_read_b128 v[222:225], v215 offset:28672
	ds_read_b128 v[226:229], v216 offset:28672
	v_exp_f32_e32 v0, v82
	v_exp_f32_e32 v177, v83
	v_exp_f32_e32 v179, v84
	v_exp_f32_e32 v254, v85
	v_add_f32_e32 v219, v0, v177
	v_cvt_pk_fp8_f32 v246, v0, v177
	v_add_f32_e32 v219, v179, v219
	v_add_f32_e32 v219, v254, v219
	v_cvt_pk_fp8_f32 v246, v179, v254 op_sel:[0,0,1]
	s_waitcnt lgkmcnt(2)
	v_mfma_scale_f32_32x32x64_f8f6f4 v[114:129], v[114:121], v[146:153], v[230:245], v194, v193 op_sel_hi:[0,0,0]
	v_exp_f32_e32 v0, v86
	v_exp_f32_e32 v177, v87
	v_exp_f32_e32 v179, v88
	v_exp_f32_e32 v254, v89
	v_add_f32_e32 v219, v0, v219
	v_add_f32_e32 v219, v177, v219
	v_cvt_pk_fp8_f32 v247, v0, v177
	v_add_f32_e32 v219, v179, v219
	v_add_f32_e32 v219, v254, v219
	v_cvt_pk_fp8_f32 v247, v179, v254 op_sel:[0,0,1]
	ds_read_b128 v[82:85], v213 offset:24576
	ds_read_b128 v[86:89], v214 offset:24576
	s_waitcnt lgkmcnt(2)
	v_mfma_scale_f32_32x32x64_f8f6f4 v[98:113], v[222:229], v[146:153], v[230:245], v194, v193 op_sel_hi:[0,0,0]
	ds_read_b128 v[222:225], v213 offset:28672
	ds_read_b128 v[226:229], v214 offset:28672
	v_exp_f32_e32 v0, v90
	v_exp_f32_e32 v177, v91
	v_exp_f32_e32 v179, v92
	v_exp_f32_e32 v254, v93
	v_add_f32_e32 v219, v0, v219
	v_add_f32_e32 v219, v177, v219
	v_cvt_pk_fp8_f32 v248, v0, v177
	v_add_f32_e32 v219, v179, v219
	v_add_f32_e32 v219, v254, v219
	v_cvt_pk_fp8_f32 v248, v179, v254 op_sel:[0,0,1]
	v_exp_f32_e32 v0, v94
	v_exp_f32_e32 v177, v95
	v_exp_f32_e32 v179, v96
	v_exp_f32_e32 v254, v97
	v_add_f32_e32 v219, v0, v219
	v_add_f32_e32 v219, v177, v219
	v_cvt_pk_fp8_f32 v249, v0, v177
	v_add_f32_e32 v219, v179, v219
	v_add_f32_e32 v219, v254, v219
	v_cvt_pk_fp8_f32 v249, v179, v254 op_sel:[0,0,1]
	ds_read_b128 v[90:93], v185 offset:36864
	ds_read_b128 v[94:97], v186 offset:36864
	s_waitcnt lgkmcnt(4)
	v_mfma_scale_f32_32x32x64_f8f6f4 v[114:129], v[82:89], v[138:145], v[114:129], v194, v193 op_sel_hi:[0,0,0]
	v_exp_f32_e32 v0, v66
	v_exp_f32_e32 v177, v67
	v_exp_f32_e32 v179, v68
	v_exp_f32_e32 v254, v69
	v_add_f32_e32 v219, v0, v219
	v_add_f32_e32 v219, v177, v219
	v_cvt_pk_fp8_f32 v250, v0, v177
	v_add_f32_e32 v219, v179, v219
	v_add_f32_e32 v219, v254, v219
	v_cvt_pk_fp8_f32 v250, v179, v254 op_sel:[0,0,1]
	s_waitcnt lgkmcnt(2)
	v_mfma_scale_f32_32x32x64_f8f6f4 v[98:113], v[222:229], v[138:145], v[98:113], v194, v193 op_sel_hi:[0,0,0]
	ds_read_b128 v[222:225], v185 offset:38912
	ds_read_b128 v[226:229], v186 offset:38912
	v_exp_f32_e32 v0, v70
	v_exp_f32_e32 v177, v71
	v_exp_f32_e32 v179, v72
	v_exp_f32_e32 v254, v73
	v_add_f32_e32 v219, v0, v219
	v_add_f32_e32 v219, v177, v219
	v_cvt_pk_fp8_f32 v251, v0, v177
	v_add_f32_e32 v219, v179, v219
	v_add_f32_e32 v219, v254, v219
	v_cvt_pk_fp8_f32 v251, v179, v254 op_sel:[0,0,1]
	v_exp_f32_e32 v0, v74
	v_exp_f32_e32 v177, v75
	v_exp_f32_e32 v179, v76
	v_exp_f32_e32 v254, v77
	v_add_f32_e32 v219, v0, v219
	v_add_f32_e32 v219, v177, v219
	v_cvt_pk_fp8_f32 v252, v0, v177
	v_add_f32_e32 v219, v179, v219
	v_add_f32_e32 v219, v254, v219
	v_cvt_pk_fp8_f32 v252, v179, v254 op_sel:[0,0,1]
	s_waitcnt lgkmcnt(2)
	v_mfma_scale_f32_32x32x64_f8f6f4 v[114:129], v[90:97], v[130:137], v[114:129], v194, v193 op_sel_hi:[0,0,0]
	v_exp_f32_e32 v0, v78
	v_exp_f32_e32 v177, v79
	v_exp_f32_e32 v179, v80
	v_exp_f32_e32 v254, v81
	v_add_f32_e32 v219, v0, v219
	v_add_f32_e32 v219, v177, v219
	v_cvt_pk_fp8_f32 v253, v0, v177
	v_add_f32_e32 v219, v179, v219
	v_add_f32_e32 v219, v254, v219
	v_cvt_pk_fp8_f32 v253, v179, v254 op_sel:[0,0,1]
	ds_read_b128 v[90:93], v185 offset:0
	ds_read_b128 v[94:97], v186 offset:0
	ds_read_b128 v[82:85], v185 offset:2048
	ds_read_b128 v[86:89], v186 offset:2048
	ds_read_b128 v[74:77], v185 offset:4096
	ds_read_b128 v[78:81], v186 offset:4096
	ds_read_b128 v[66:69], v185 offset:6144
	ds_read_b128 v[70:73], v186 offset:6144
	s_waitcnt lgkmcnt(8)
	v_mfma_scale_f32_32x32x64_f8f6f4 v[98:113], v[222:229], v[130:137], v[98:113], v194, v193 op_sel_hi:[0,0,0]
	v_mov_b32_e32 v0, v219
	s_nop 1
	v_permlane32_swap_b32_e32 v219, v0
	v_add_f32_e32 v219, v219, v0
	v_add_f32_e32 v209, v209, v219
	s_waitcnt vmcnt(0)
	ds_write_b128 v210, v[158:161] offset:43008
	ds_write_b128 v211, v[162:165] offset:51200
	s_waitcnt lgkmcnt(0)
	s_barrier
	global_load_dwordx4 v[158:161], v176, s[18:19]
	global_load_dwordx4 v[162:165], v178, s[16:17]
	v_add_u32_e32 v176, 0x2000, v176
	v_add_u32_e32 v178, 0x20000, v178
	v_max_f32_e32 v177, v114, v115
	v_max3_f32 v177, v177, v116, v117
	v_max3_f32 v177, v177, v118, v119
	v_max3_f32 v177, v177, v120, v121
	v_max3_f32 v177, v177, v122, v123
	v_max3_f32 v177, v177, v124, v125
	v_max3_f32 v177, v177, v126, v127
	v_max3_f32 v177, v177, v128, v129
	s_waitcnt lgkmcnt(6)
	v_mfma_scale_f32_32x32x64_f8f6f4 v[50:65], v[246:253], v[90:97], v[50:65], v194, v194 op_sel_hi:[0,0,0]
	s_waitcnt lgkmcnt(4)
	v_mfma_scale_f32_32x32x64_f8f6f4 v[34:49], v[246:253], v[82:89], v[34:49], v194, v194 op_sel_hi:[0,0,0]
	s_waitcnt lgkmcnt(2)
	v_mfma_scale_f32_32x32x64_f8f6f4 v[18:33], v[246:253], v[74:81], v[18:33], v194, v194 op_sel_hi:[0,0,0]
	s_waitcnt lgkmcnt(0)
	v_mfma_scale_f32_32x32x64_f8f6f4 v[2:17], v[246:253], v[66:73], v[2:17], v194, v194 op_sel_hi:[0,0,0]
	v_max_f32_e32 v0, v98, v99
	v_max3_f32 v0, v0, v100, v101
	v_max3_f32 v0, v0, v102, v103
	v_max3_f32 v0, v0, v104, v105
	v_max3_f32 v0, v0, v106, v107
	v_max3_f32 v0, v0, v108, v109
	v_max3_f32 v0, v0, v110, v111
	v_max3_f32 v0, v0, v112, v113
	v_max_f32_e32 v177, v177, v0
	v_mov_b32_e32 v0, v177
	s_nop 1
	v_permlane32_swap_b32_e32 v177, v0
	v_max_f32_e32 v177, v177, v0
	v_cmp_ge_f32_e32 vcc, s90, v177
	s_cmp_eq_u64 vcc, exec
	s_cbranch_scc0 .Lmla_q0_newmax
; __device__ __forceinline__ v8i32 cat8(v4i32 a, v4i32 b) { return (v8i32){a[0], a[1], a[2], a[3], b[0], b[1], b[2], b[3]}; }
; __device__ __forceinline__ void finishSM9(f32x16& p0, f32x16& p1, float alpha, float& l_reg, v8i32& p8) {
; #pragma unroll
;   for (int r = 0; r < 16; ++r) { p0[r] = __builtin_amdgcn_exp2f(p0[r]); p1[r] = __builtin_amdgcn_exp2f(p1[r]); }
;   float ps = 0;
; #pragma unroll
;   for (int r = 0; r < 16; ++r) ps += p0[r];
; #pragma unroll
;   for (int r = 0; r < 16; ++r) ps += p1[r];
;   { auto rr = __builtin_amdgcn_permlane32_swap(__float_as_uint(ps), __float_as_uint(ps), false, false);
;     ps = __uint_as_float(rr[0]) + __uint_as_float(rr[1]); }
;   l_reg = l_reg * alpha + ps;
; #pragma unroll
;   for (int g = 0; g < 4; ++g) {
;     int w = __builtin_amdgcn_cvt_pk_fp8_f32(p0[4 * g], p0[4 * g + 1], 0, false); p8[g] = __builtin_amdgcn_cvt_pk_fp8_f32(p0[4 * g + 2], p0[4 * g + 3], w, true);
;     int u = __builtin_amdgcn_cvt_pk_fp8_f32(p1[4 * g], p1[4 * g + 1], 0, false); p8[4 + g] = __builtin_amdgcn_cvt_pk_fp8_f32(p1[4 * g + 2], p1[4 * g + 3], u, true); }
; }
; __device__ __forceinline__ void pv8(f32x16* o, const char* Vt, const v8i32 p8, int r32, int hi) {
;   const int sw = (r32 >> 2) & 3, a0 = r32 * 64 + (((hi * 2) ^ sw) << 4), a1 = r32 * 64 + (((hi * 2 + 1) ^ sw) << 4);
; #pragma unroll
;   for (int d0 = 0; d0 < 4; ++d0) {
;     const v8i32 vf = cat8(*reinterpret_cast<const v4i32*>(Vt + d0 * 2048 + a0), *reinterpret_cast<const v4i32*>(Vt + d0 * 2048 + a1));
;     o[d0] = __builtin_amdgcn_mfma_scale_f32_32x32x64_f8f6f4(p8, vf, o[d0], 0, 0, 0, 127, 0, 127); }
; }
; __device__ __forceinline__ void qkt9(f32x16& p0, f32x16& p1, const char* Kn, const char* Kr, const v8i32* qf, const float init, int r32, int hi) {
; #pragma unroll
;   for (int r = 0; r < 16; ++r) { p0[r] = init; p1[r] = init; }
; #pragma unroll
;   for (int s = 0; s < 2; ++s) { const int c0 = s * 4 + hi * 2;
; __device__ __forceinline__ void attn_unit7(const unsigned char* __restrict__ Q8, int ldq, const unsigned char* __restrict__ Kn8, int ldk, const unsigned char* __restrict__ Kr8, ...
;     ...
;   qkt9(pB0, pB1, Kn_lds + 8192, Kr_lds + 4096, qf, 7.0f - m_reg, r32, hi);
;   finishSM9(pA0, pA1, alA, l_reg, p8);
;   pv8(o, Vt_lds, p8, r32, hi); partialSM9(pB0, pB1, m_reg, alB, thr_raw);
;   RESC(alB);
;   finishSM9(pB0, pB1, alB, l_reg, p8);
;   pv8(o, Vt_lds + 8192, p8, r32, hi);
.Lmla_q0_cont:
	ds_read_b128 v[82:85], v215 offset:51200
	ds_read_b128 v[86:89], v216 offset:51200
	ds_read_b128 v[222:225], v215 offset:55296
	ds_read_b128 v[226:229], v216 offset:55296
	v_exp_f32_e32 v0, v114
	v_exp_f32_e32 v177, v115
	v_exp_f32_e32 v179, v116
	v_exp_f32_e32 v254, v117
	v_add_f32_e32 v219, v0, v177
	v_cvt_pk_fp8_f32 v246, v0, v177
	v_add_f32_e32 v219, v179, v219
	v_add_f32_e32 v219, v254, v219
	v_cvt_pk_fp8_f32 v246, v179, v254 op_sel:[0,0,1]
	s_waitcnt lgkmcnt(2)
	v_mfma_scale_f32_32x32x64_f8f6f4 v[82:97], v[82:89], v[146:153], v[230:245], v194, v193 op_sel_hi:[0,0,0]
	v_exp_f32_e32 v0, v118
	v_exp_f32_e32 v177, v119
	v_exp_f32_e32 v179, v120
	v_exp_f32_e32 v254, v121
	v_add_f32_e32 v219, v0, v219
	v_add_f32_e32 v219, v177, v219
	v_cvt_pk_fp8_f32 v247, v0, v177
	v_add_f32_e32 v219, v179, v219
	v_add_f32_e32 v219, v254, v219
	v_cvt_pk_fp8_f32 v247, v179, v254 op_sel:[0,0,1]
	ds_read_b128 v[114:117], v213 offset:51200
	ds_read_b128 v[118:121], v214 offset:51200
	s_waitcnt lgkmcnt(2)
	v_mfma_scale_f32_32x32x64_f8f6f4 v[66:81], v[222:229], v[146:153], v[230:245], v194, v193 op_sel_hi:[0,0,0]
	ds_read_b128 v[222:225], v213 offset:55296
	ds_read_b128 v[226:229], v214 offset:55296
	v_exp_f32_e32 v0, v122
	v_exp_f32_e32 v177, v123
	v_exp_f32_e32 v179, v124
	v_exp_f32_e32 v254, v125
	v_add_f32_e32 v219, v0, v219
	v_add_f32_e32 v219, v177, v219
	v_cvt_pk_fp8_f32 v248, v0, v177
	v_add_f32_e32 v219, v179, v219
	v_add_f32_e32 v219, v254, v219
	v_cvt_pk_fp8_f32 v248, v179, v254 op_sel:[0,0,1]
	v_exp_f32_e32 v0, v126
	v_exp_f32_e32 v177, v127
	v_exp_f32_e32 v179, v128
	v_exp_f32_e32 v254, v129
	v_add_f32_e32 v219, v0, v219
	v_add_f32_e32 v219, v177, v219
	v_cvt_pk_fp8_f32 v249, v0, v177
	v_add_f32_e32 v219, v179, v219
	v_add_f32_e32 v219, v254, v219
	v_cvt_pk_fp8_f32 v249, v179, v254 op_sel:[0,0,1]
	ds_read_b128 v[122:125], v185 offset:59392
	ds_read_b128 v[126:129], v186 offset:59392
	s_waitcnt lgkmcnt(4)
	v_mfma_scale_f32_32x32x64_f8f6f4 v[82:97], v[114:121], v[138:145], v[82:97], v194, v193 op_sel_hi:[0,0,0]
	v_exp_f32_e32 v0, v98
	v_exp_f32_e32 v177, v99
	v_exp_f32_e32 v179, v100
	v_exp_f32_e32 v254, v101
	v_add_f32_e32 v219, v0, v219
	v_add_f32_e32 v219, v177, v219
	v_cvt_pk_fp8_f32 v250, v0, v177
	v_add_f32_e32 v219, v179, v219
	v_add_f32_e32 v219, v254, v219
	v_cvt_pk_fp8_f32 v250, v179, v254 op_sel:[0,0,1]
	s_waitcnt lgkmcnt(2)
	v_mfma_scale_f32_32x32x64_f8f6f4 v[66:81], v[222:229], v[138:145], v[66:81], v194, v193 op_sel_hi:[0,0,0]
	ds_read_b128 v[222:225], v185 offset:61440
	ds_read_b128 v[226:229], v186 offset:61440
	v_exp_f32_e32 v0, v102
	v_exp_f32_e32 v177, v103
	v_exp_f32_e32 v179, v104
	v_exp_f32_e32 v254, v105
	v_add_f32_e32 v219, v0, v219
	v_add_f32_e32 v219, v177, v219
	v_cvt_pk_fp8_f32 v251, v0, v177
	v_add_f32_e32 v219, v179, v219
	v_add_f32_e32 v219, v254, v219
	v_cvt_pk_fp8_f32 v251, v179, v254 op_sel:[0,0,1]
	v_exp_f32_e32 v0, v106
	v_exp_f32_e32 v177, v107
	v_exp_f32_e32 v179, v108
	v_exp_f32_e32 v254, v109
	v_add_f32_e32 v219, v0, v219
	v_add_f32_e32 v219, v177, v219
	v_cvt_pk_fp8_f32 v252, v0, v177
	v_add_f32_e32 v219, v179, v219
	v_add_f32_e32 v219, v254, v219
	v_cvt_pk_fp8_f32 v252, v179, v254 op_sel:[0,0,1]
	s_waitcnt lgkmcnt(2)
	v_mfma_scale_f32_32x32x64_f8f6f4 v[82:97], v[122:129], v[130:137], v[82:97], v194, v193 op_sel_hi:[0,0,0]
	v_exp_f32_e32 v0, v110
	v_exp_f32_e32 v177, v111
	v_exp_f32_e32 v179, v112
	v_exp_f32_e32 v254, v113
	v_add_f32_e32 v219, v0, v219
	v_add_f32_e32 v219, v177, v219
	v_cvt_pk_fp8_f32 v253, v0, v177
	v_add_f32_e32 v219, v179, v219
	v_add_f32_e32 v219, v254, v219
	v_cvt_pk_fp8_f32 v253, v179, v254 op_sel:[0,0,1]
	ds_read_b128 v[122:125], v185 offset:8192
	ds_read_b128 v[126:129], v186 offset:8192
	ds_read_b128 v[114:117], v185 offset:10240
	ds_read_b128 v[118:121], v186 offset:10240
	ds_read_b128 v[106:109], v185 offset:12288
	ds_read_b128 v[110:113], v186 offset:12288
	ds_read_b128 v[98:101], v185 offset:14336
	ds_read_b128 v[102:105], v186 offset:14336
	s_waitcnt lgkmcnt(8)
	v_mfma_scale_f32_32x32x64_f8f6f4 v[66:81], v[222:229], v[130:137], v[66:81], v194, v193 op_sel_hi:[0,0,0]
	v_mov_b32_e32 v0, v219
	s_nop 1
	v_permlane32_swap_b32_e32 v219, v0
	v_add_f32_e32 v219, v219, v0
	v_add_f32_e32 v209, v209, v219
	s_waitcnt vmcnt(0)
	ds_write_b128 v210, v[158:161]
	ds_write_b128 v211, v[162:165] offset:16384
	s_waitcnt lgkmcnt(0)
	s_barrier
	v_max_f32_e32 v177, v82, v83
	v_max3_f32 v177, v177, v84, v85
	v_max3_f32 v177, v177, v86, v87
	v_max3_f32 v177, v177, v88, v89
	v_max3_f32 v177, v177, v90, v91
	v_max3_f32 v177, v177, v92, v93
	v_max3_f32 v177, v177, v94, v95
	v_max3_f32 v177, v177, v96, v97
	s_waitcnt lgkmcnt(6)
	v_mfma_scale_f32_32x32x64_f8f6f4 v[50:65], v[246:253], v[122:129], v[50:65], v194, v194 op_sel_hi:[0,0,0]
	s_waitcnt lgkmcnt(4)
	v_mfma_scale_f32_32x32x64_f8f6f4 v[34:49], v[246:253], v[114:121], v[34:49], v194, v194 op_sel_hi:[0,0,0]
	s_waitcnt lgkmcnt(2)
	v_mfma_scale_f32_32x32x64_f8f6f4 v[18:33], v[246:253], v[106:113], v[18:33], v194, v194 op_sel_hi:[0,0,0]
	s_waitcnt lgkmcnt(0)
	v_mfma_scale_f32_32x32x64_f8f6f4 v[2:17], v[246:253], v[98:105], v[2:17], v194, v194 op_sel_hi:[0,0,0]
	v_max_f32_e32 v0, v66, v67
	v_max3_f32 v0, v0, v68, v69
	v_max3_f32 v0, v0, v70, v71
	v_max3_f32 v0, v0, v72, v73
	v_max3_f32 v0, v0, v74, v75
	v_max3_f32 v0, v0, v76, v77
	v_max3_f32 v0, v0, v78, v79
	v_max3_f32 v0, v0, v80, v81
	v_max_f32_e32 v177, v177, v0
	v_mov_b32_e32 v0, v177
	s_nop 1
	v_permlane32_swap_b32_e32 v177, v0
	v_max_f32_e32 v177, v177, v0
	v_cmp_ge_f32_e32 vcc, s90, v177
	s_cmp_eq_u64 vcc, exec
	s_cbranch_scc0 .Lmla_q1_newmax
.Lmla_q1_cont:
	v_mov_b32_e32 v0, 1.0
	s_branch .LBB0_1343
; __device__ __forceinline__ void partialSM9(f32x16& p0, f32x16& p1, float& m_run, float& alpha, const float thr2) {
;     ...
;   else { const float delta = fmaxf(pmax - 7.0f, 0.f); alpha = __builtin_amdgcn_exp2f(-delta); m_run += delta;
; #pragma unroll
;     for (int r = 0; r < 16; ++r) { p0[r] -= delta; p1[r] -= delta; } }
.Lmla_h0_newmax:
	v_add_f32_e32 v0, 0xc0a00000, v177
	v_max_f32_e32 v177, 0, v0
	v_exp_f32_e64 v221, -v177
	v_add_f32_e32 v217, v217, v177
	v_sub_f32_e32 v129, v129, v177
	v_sub_f32_e32 v128, v128, v177
	v_sub_f32_e32 v127, v127, v177
	v_sub_f32_e32 v126, v126, v177
	v_sub_f32_e32 v125, v125, v177
	v_sub_f32_e32 v124, v124, v177
	v_sub_f32_e32 v123, v123, v177
	v_sub_f32_e32 v122, v122, v177
	v_sub_f32_e32 v121, v121, v177
	v_sub_f32_e32 v120, v120, v177
	v_sub_f32_e32 v119, v119, v177
	v_sub_f32_e32 v118, v118, v177
	v_sub_f32_e32 v117, v117, v177
	v_sub_f32_e32 v116, v116, v177
	v_sub_f32_e32 v115, v115, v177
	v_sub_f32_e32 v114, v114, v177
	s_and_saveexec_b64 s[20:21], s[40:41]
	ds_write_b32 v208, v221 offset:41088
	s_or_b64 exec, exec, s[20:21]
	v_mul_f32_e32 v209, v209, v221
	v_sub_f32_e32 v113, v113, v177
	v_sub_f32_e32 v112, v112, v177
	v_sub_f32_e32 v111, v111, v177
	v_sub_f32_e32 v110, v110, v177
	v_sub_f32_e32 v109, v109, v177
	v_sub_f32_e32 v108, v108, v177
	v_sub_f32_e32 v107, v107, v177
	v_sub_f32_e32 v106, v106, v177
	v_sub_f32_e32 v105, v105, v177
	v_sub_f32_e32 v104, v104, v177
	v_sub_f32_e32 v103, v103, v177
	v_sub_f32_e32 v102, v102, v177
	v_sub_f32_e32 v101, v101, v177
	v_sub_f32_e32 v100, v100, v177
	v_sub_f32_e32 v99, v99, v177
	v_sub_f32_e32 v98, v98, v177
	v_sub_f32_e32 v230, 0x40e00000, v217
	v_mov_b32_e32 v231, v230
	v_mov_b32_e32 v232, v230
	v_mov_b32_e32 v233, v230
	v_mov_b32_e32 v234, v230
	v_mov_b32_e32 v235, v230
	v_mov_b32_e32 v236, v230
	v_mov_b32_e32 v237, v230
	v_mov_b32_e32 v238, v230
	v_mov_b32_e32 v239, v230
	v_mov_b32_e32 v240, v230
	v_mov_b32_e32 v241, v230
	v_mov_b32_e32 v242, v230
	v_mov_b32_e32 v243, v230
	v_mov_b32_e32 v244, v230
	v_mov_b32_e32 v245, v230
	v_add_u32_e32 v0, v187, v207
	s_waitcnt lgkmcnt(0)
	ds_read_b128 v[66:69], v0 offset:41184
	ds_read_b128 v[70:73], v0 offset:41152
	ds_read_b128 v[74:77], v0 offset:41120
	ds_read_b128 v[78:81], v0 offset:41088
	s_waitcnt lgkmcnt(0)
	v_pk_mul_f32 v[62:63], v[62:63], v[66:67]
	v_pk_mul_f32 v[58:59], v[58:59], v[70:71]
	v_pk_mul_f32 v[54:55], v[54:55], v[74:75]
	v_pk_mul_f32 v[64:65], v[64:65], v[68:69]
	v_pk_mul_f32 v[60:61], v[60:61], v[72:73]
	v_pk_mul_f32 v[56:57], v[56:57], v[76:77]
	v_pk_mul_f32 v[52:53], v[52:53], v[80:81]
	v_pk_mul_f32 v[50:51], v[50:51], v[78:79]
	v_pk_mul_f32 v[46:47], v[46:47], v[66:67]
	v_pk_mul_f32 v[42:43], v[42:43], v[70:71]
	v_pk_mul_f32 v[38:39], v[38:39], v[74:75]
	v_pk_mul_f32 v[48:49], v[48:49], v[68:69]
	v_pk_mul_f32 v[44:45], v[44:45], v[72:73]
	v_pk_mul_f32 v[40:41], v[40:41], v[76:77]
	v_pk_mul_f32 v[36:37], v[36:37], v[80:81]
	v_pk_mul_f32 v[34:35], v[34:35], v[78:79]
	v_pk_mul_f32 v[30:31], v[30:31], v[66:67]
	v_pk_mul_f32 v[26:27], v[26:27], v[70:71]
	v_pk_mul_f32 v[22:23], v[22:23], v[74:75]
	v_pk_mul_f32 v[32:33], v[32:33], v[68:69]
	v_pk_mul_f32 v[28:29], v[28:29], v[72:73]
	v_pk_mul_f32 v[24:25], v[24:25], v[76:77]
	v_pk_mul_f32 v[20:21], v[20:21], v[80:81]
	v_pk_mul_f32 v[18:19], v[18:19], v[78:79]
	v_pk_mul_f32 v[14:15], v[14:15], v[66:67]
	v_pk_mul_f32 v[10:11], v[10:11], v[70:71]
	v_pk_mul_f32 v[6:7], v[6:7], v[74:75]
	v_pk_mul_f32 v[16:17], v[16:17], v[68:69]
	v_pk_mul_f32 v[12:13], v[12:13], v[72:73]
	v_pk_mul_f32 v[8:9], v[8:9], v[76:77]
	v_pk_mul_f32 v[4:5], v[4:5], v[80:81]
	v_pk_mul_f32 v[2:3], v[2:3], v[78:79]
	s_branch .Lmla_h0_cont
.Lmla_h1_newmax:
	v_add_f32_e32 v0, 0xc0a00000, v177
	v_max_f32_e32 v177, 0, v0
	v_exp_f32_e64 v218, -v177
	v_add_f32_e32 v217, v217, v177
	v_sub_f32_e32 v97, v97, v177
	v_sub_f32_e32 v96, v96, v177
	v_sub_f32_e32 v95, v95, v177
	v_sub_f32_e32 v94, v94, v177
	v_sub_f32_e32 v93, v93, v177
	v_sub_f32_e32 v92, v92, v177
	v_sub_f32_e32 v91, v91, v177
	v_sub_f32_e32 v90, v90, v177
	v_sub_f32_e32 v89, v89, v177
	v_sub_f32_e32 v88, v88, v177
	v_sub_f32_e32 v87, v87, v177
	v_sub_f32_e32 v86, v86, v177
	v_sub_f32_e32 v85, v85, v177
	v_sub_f32_e32 v84, v84, v177
	v_sub_f32_e32 v83, v83, v177
	v_sub_f32_e32 v82, v82, v177
	s_and_saveexec_b64 s[20:21], s[40:41]
	ds_write_b32 v208, v218 offset:41088
	s_or_b64 exec, exec, s[20:21]
	v_mul_f32_e32 v209, v209, v218
	v_sub_f32_e32 v81, v81, v177
	v_sub_f32_e32 v80, v80, v177
	v_sub_f32_e32 v79, v79, v177
	v_sub_f32_e32 v78, v78, v177
	v_sub_f32_e32 v77, v77, v177
	v_sub_f32_e32 v76, v76, v177
	v_sub_f32_e32 v75, v75, v177
	v_sub_f32_e32 v74, v74, v177
	v_sub_f32_e32 v73, v73, v177
	v_sub_f32_e32 v72, v72, v177
	v_sub_f32_e32 v71, v71, v177
	v_sub_f32_e32 v70, v70, v177
	v_sub_f32_e32 v69, v69, v177
	v_sub_f32_e32 v68, v68, v177
	v_sub_f32_e32 v67, v67, v177
	v_sub_f32_e32 v66, v66, v177
	v_sub_f32_e32 v230, 0x40e00000, v217
	v_mov_b32_e32 v231, v230
	v_mov_b32_e32 v232, v230
	v_mov_b32_e32 v233, v230
	v_mov_b32_e32 v234, v230
	v_mov_b32_e32 v235, v230
	v_mov_b32_e32 v236, v230
	v_mov_b32_e32 v237, v230
	v_mov_b32_e32 v238, v230
	v_mov_b32_e32 v239, v230
	v_mov_b32_e32 v240, v230
	v_mov_b32_e32 v241, v230
	v_mov_b32_e32 v242, v230
	v_mov_b32_e32 v243, v230
	v_mov_b32_e32 v244, v230
	v_mov_b32_e32 v245, v230
	v_add_u32_e32 v0, v187, v207
	s_waitcnt lgkmcnt(0)
	ds_read_b128 v[98:101], v0 offset:41184
	ds_read_b128 v[102:105], v0 offset:41152
	ds_read_b128 v[106:109], v0 offset:41120
	ds_read_b128 v[110:113], v0 offset:41088
	s_waitcnt lgkmcnt(0)
	v_pk_mul_f32 v[62:63], v[62:63], v[98:99]
	v_pk_mul_f32 v[58:59], v[58:59], v[102:103]
	v_pk_mul_f32 v[54:55], v[54:55], v[106:107]
	v_pk_mul_f32 v[64:65], v[64:65], v[100:101]
	v_pk_mul_f32 v[60:61], v[60:61], v[104:105]
	v_pk_mul_f32 v[56:57], v[56:57], v[108:109]
	v_pk_mul_f32 v[52:53], v[52:53], v[112:113]
	v_pk_mul_f32 v[50:51], v[50:51], v[110:111]
	v_pk_mul_f32 v[46:47], v[46:47], v[98:99]
	v_pk_mul_f32 v[42:43], v[42:43], v[102:103]
	v_pk_mul_f32 v[38:39], v[38:39], v[106:107]
	v_pk_mul_f32 v[48:49], v[48:49], v[100:101]
	v_pk_mul_f32 v[44:45], v[44:45], v[104:105]
	v_pk_mul_f32 v[40:41], v[40:41], v[108:109]
	v_pk_mul_f32 v[36:37], v[36:37], v[112:113]
	v_pk_mul_f32 v[34:35], v[34:35], v[110:111]
	v_pk_mul_f32 v[30:31], v[30:31], v[98:99]
	v_pk_mul_f32 v[26:27], v[26:27], v[102:103]
	v_pk_mul_f32 v[22:23], v[22:23], v[106:107]
	v_pk_mul_f32 v[32:33], v[32:33], v[100:101]
	v_pk_mul_f32 v[28:29], v[28:29], v[104:105]
	v_pk_mul_f32 v[24:25], v[24:25], v[108:109]
	v_pk_mul_f32 v[20:21], v[20:21], v[112:113]
	v_pk_mul_f32 v[18:19], v[18:19], v[110:111]
	v_pk_mul_f32 v[14:15], v[14:15], v[98:99]
	v_pk_mul_f32 v[10:11], v[10:11], v[102:103]
	v_pk_mul_f32 v[6:7], v[6:7], v[106:107]
	v_pk_mul_f32 v[16:17], v[16:17], v[100:101]
	v_pk_mul_f32 v[12:13], v[12:13], v[104:105]
	v_pk_mul_f32 v[8:9], v[8:9], v[108:109]
	v_pk_mul_f32 v[4:5], v[4:5], v[112:113]
	v_pk_mul_f32 v[2:3], v[2:3], v[110:111]
	s_branch .Lmla_h1_cont
